# GEMM tile transitions: the 128 accumulators zeroed with v_mov_b64 inline-0 pairs instead of 127 single v_mov_b32 copies; sites padded to keep every later byte offset
# speedup vs baseline: 1.0029x; 1.0029x over previous
; #define PG8_STAGE(bufoff, gbase, voff) do { _Pragma("unroll") for (int _i = 0; _i < 2; ++_i) \
;         __builtin_amdgcn_global_load_lds((const unsigned*)((const char*)(gbase) + (voff)[_i]), (PG8_LAS unsigned*)(lds + (bufoff) + ldsw + _i * 8192), 16, 0, 0); } while (0)
; #define PG8_LDA(dst, b, h) do { _Pragma("unroll") for (int m = 0; m < 4; ++m) _Pragma("unroll") for (int k = 0; k < 2; ++k) dst[m][k] = *(const PG8_LAS bf16x8*)(lds + PG8_SA(b, h) + aoff + m * 2048 + k * 1024); } while (0)
; #define PG8_LDB(dst, b, h) do { _Pragma("unroll") for (int n = 0; n < 2; ++n) _Pragma("unroll") for (int k = 0; k < 2; ++k) dst[n][k] = *(const PG8_LAS bf16x8*)(lds + PG8_SB(b, h) + boff + n * 2048 + k * 1024); } while (0)
; #define PG8_MMA(ai, bj, At, Bt) do { __builtin_amdgcn_s_setprio(1); _Pragma("unroll") for (int m = 0; m < 4; ++m) _Pragma("unroll") for (int n = 0; n < 2; ++n) _Pragma("unroll") for (int k = 0; k < 2; ++k) \
;         acc[ai][bj][m][n] = __builtin_amdgcn_mfma_f32_16x16x32_bf16(Bt[n][k], At[m][k], acc[ai][bj][m][n], 0, 0, 0); __builtin_amdgcn_s_setprio(0); } while (0)
; #define PG8_WAIT_V(n) asm volatile("s_waitcnt vmcnt(" #n ")" ::: "memory")
; #define PG8_WAIT_L(n) asm volatile("s_waitcnt lgkmcnt(" #n ")" ::: "memory")
; #define PG8_BAR __builtin_amdgcn_s_barrier()
; #define PG8_SCHED __builtin_amdgcn_sched_barrier(0)
; template <class Epi, class Sched, bool ALIGN_EPI = false, bool SP2 = false>
; __device__ __forceinline__ void gemm_phase(PG8_LAS unsigned char* lds, const Gemm g, const Sched& S, const Epi& E) {
;     ...
;             PG8_LDB(B0, 0, 0); PG8_LDB(B1, 0, 1); PG8_SCHED; PG8_LDA(At, 0, 0); PG8_STAGE(PG8_SA(1, 1), a1 + hstep, voffA);
;             PG8_WAIT_V(8); PG8_WAIT_L(0); PG8_BAR; PG8_MMA(0, 0, At, B0); PG8_MMA(0, 1, At, B1); PG8_BAR; PG8_SCHED;
;     ...
; #pragma unroll
;         for (int a = 0; a < 2; ++a)
; #pragma unroll
;             for (int b = 0; b < 2; ++b)
; #pragma unroll
;                 for (int m = 0; m < 4; ++m)
; #pragma unroll
;                     for (int n = 0; n < 2; ++n) acc[a][b][m][n] = (f32x4){0.f, 0.f, 0.f, 0.f};
;         cur = nxt; cA = nA; cB = nB; ++ui;
.LBB0_434:
	s_ashr_i32 s13, s12, 31
	s_lshl_b64 s[14:15], s[12:13], 19
	v_readlane_b32 s18, v240, 5
	v_readlane_b32 s19, v240, 6
	s_add_u32 s14, s18, s14
	s_addc_u32 s15, s19, s15
	s_and_b64 s[18:19], s[4:5], exec
	s_cselect_b32 s13, s15, s23
	s_cselect_b32 s47, s14, s22
	s_ashr_i32 s11, s10, 31
	s_lshl_b64 s[18:19], s[10:11], 19
	s_add_u32 s18, s28, s18
	s_addc_u32 s19, s29, s19
	s_and_b64 s[26:27], s[4:5], exec
	s_cselect_b32 s11, s19, s25
	s_cselect_b32 s48, s18, s24
	s_add_u32 s22, s22, 0x40080
	s_addc_u32 s23, s23, 0
	s_add_u32 s49, s24, 0x100
	v_mov_b32_e32 v0, 0
	s_addc_u32 s50, s25, 0
	s_mov_b32 s51, -2
	v_mov_b32_e32 v1, 0
	v_mov_b64_e32 v[2:3], 0
	v_mov_b64_e32 v[4:5], 0
	v_mov_b64_e32 v[6:7], 0
	v_mov_b64_e32 v[8:9], 0
	v_mov_b64_e32 v[10:11], 0
	v_mov_b64_e32 v[12:13], 0
	v_mov_b64_e32 v[14:15], 0
	v_mov_b64_e32 v[16:17], 0
	v_mov_b64_e32 v[18:19], 0
	v_mov_b64_e32 v[20:21], 0
	v_mov_b64_e32 v[22:23], 0
	v_mov_b64_e32 v[24:25], 0
	v_mov_b64_e32 v[26:27], 0
	v_mov_b64_e32 v[28:29], 0
	v_mov_b64_e32 v[30:31], 0
	v_mov_b64_e32 v[32:33], 0
	v_mov_b64_e32 v[34:35], 0
	v_mov_b64_e32 v[36:37], 0
	v_mov_b64_e32 v[38:39], 0
	v_mov_b64_e32 v[40:41], 0
	v_mov_b64_e32 v[42:43], 0
	v_mov_b64_e32 v[44:45], 0
	v_mov_b64_e32 v[46:47], 0
	v_mov_b64_e32 v[48:49], 0
	v_mov_b64_e32 v[50:51], 0
	v_mov_b64_e32 v[52:53], 0
	v_mov_b64_e32 v[54:55], 0
	v_mov_b64_e32 v[56:57], 0
	v_mov_b64_e32 v[58:59], 0
	v_mov_b64_e32 v[60:61], 0
	v_mov_b64_e32 v[62:63], 0
	v_mov_b64_e32 v[64:65], 0
	v_mov_b64_e32 v[66:67], 0
	v_mov_b64_e32 v[68:69], 0
	v_mov_b64_e32 v[70:71], 0
	v_mov_b64_e32 v[72:73], 0
	v_mov_b64_e32 v[74:75], 0
	v_mov_b64_e32 v[76:77], 0
	v_mov_b64_e32 v[78:79], 0
	v_mov_b64_e32 v[80:81], 0
	v_mov_b64_e32 v[82:83], 0
	v_mov_b64_e32 v[84:85], 0
	v_mov_b64_e32 v[86:87], 0
	v_mov_b64_e32 v[88:89], 0
	v_mov_b64_e32 v[90:91], 0
	v_mov_b64_e32 v[92:93], 0
	v_mov_b64_e32 v[94:95], 0
	v_mov_b64_e32 v[96:97], 0
	v_mov_b64_e32 v[98:99], 0
	v_mov_b64_e32 v[100:101], 0
	v_mov_b64_e32 v[102:103], 0
	v_mov_b64_e32 v[104:105], 0
	v_mov_b64_e32 v[106:107], 0
	v_mov_b64_e32 v[108:109], 0
	v_mov_b64_e32 v[110:111], 0
	v_mov_b64_e32 v[112:113], 0
	v_mov_b64_e32 v[114:115], 0
	v_mov_b64_e32 v[116:117], 0
	v_mov_b64_e32 v[118:119], 0
	v_mov_b64_e32 v[120:121], 0
	v_mov_b64_e32 v[122:123], 0
	v_mov_b64_e32 v[124:125], 0
	v_mov_b64_e32 v[126:127], 0
	s_branch .Lz64_0
	s_nop 0
	s_nop 0
	s_nop 0
	s_nop 0
	s_nop 0
	s_nop 0
	s_nop 0
	s_nop 0
	s_nop 0
	s_nop 0
	s_nop 0
	s_nop 0
	s_nop 0
	s_nop 0
	s_nop 0
	s_nop 0
	s_nop 0
	s_nop 0
	s_nop 0
	s_nop 0
	s_nop 0
	s_nop 0
	s_nop 0
	s_nop 0
	s_nop 0
	s_nop 0
	s_nop 0
	s_nop 0
	s_nop 0
	s_nop 0
	s_nop 0
	s_nop 0
	s_nop 0
	s_nop 0
	s_nop 0
	s_nop 0
	s_nop 0
	s_nop 0
	s_nop 0
	s_nop 0
	s_nop 0
	s_nop 0
	s_nop 0
	s_nop 0
	s_nop 0
	s_nop 0
	s_nop 0
	s_nop 0
	s_nop 0
	s_nop 0
	s_nop 0
	s_nop 0
	s_nop 0
	s_nop 0
	s_nop 0
	s_nop 0
	s_nop 0
	s_nop 0
	s_nop 0
	s_nop 0
	s_nop 0
	s_nop 0
.Lz64_0:
.LBB0_435:
	ds_read_b128 v[156:159], v150
	ds_read_b128 v[160:163], v150 offset:1024
	ds_read_b128 v[164:167], v150 offset:2048
	ds_read_b128 v[168:171], v150 offset:3072
	ds_read_b128 v[172:175], v151
	ds_read_b128 v[176:179], v151 offset:1024
	ds_read_b128 v[180:183], v151 offset:2048
	ds_read_b128 v[186:189], v151 offset:3072
	s_add_u32 s24, s22, 0xfffc0080
	s_addc_u32 s25, s23, -1
	s_cmp_eq_u32 s51, 12
	s_cselect_b32 s27, s13, s25
	s_cselect_b32 s26, s47, s24
	s_cselect_b32 s25, s11, s50
	s_cselect_b32 s24, s48, s49
	v_lshl_add_u64 v[146:147], s[22:23], 0, v[136:137]
	s_add_i32 m0, s21, 0xc000
	ds_read_b128 v[190:193], v152
	ds_read_b128 v[194:197], v152 offset:1024
	ds_read_b128 v[198:201], v152 offset:2048
	ds_read_b128 v[202:205], v152 offset:3072
	ds_read_b128 v[206:209], v152 offset:4096
	ds_read_b128 v[210:213], v152 offset:5120
	ds_read_b128 v[214:217], v152 offset:6144
	ds_read_b128 v[218:221], v152 offset:7168
	global_load_lds_dwordx4 v[146:147], off
	v_lshl_add_u64 v[146:147], s[22:23], 0, v[138:139]
	s_add_i32 m0, s21, 0xe000
	s_nop 0
	global_load_lds_dwordx4 v[146:147], off
	s_waitcnt vmcnt(8)
	s_waitcnt lgkmcnt(0)
	s_barrier
	s_setprio 1
	s_waitcnt lgkmcnt(0)
	v_mfma_f32_16x16x32_bf16 v[124:127], v[156:159], v[190:193], v[124:127]
	v_mfma_f32_16x16x32_bf16 v[120:123], v[164:167], v[190:193], v[120:123]
	v_mfma_f32_16x16x32_bf16 v[108:111], v[156:159], v[198:201], v[108:111]
	v_mfma_f32_16x16x32_bf16 v[104:107], v[164:167], v[198:201], v[104:107]
	v_mfma_f32_16x16x32_bf16 v[92:95], v[156:159], v[206:209], v[92:95]
	v_mfma_f32_16x16x32_bf16 v[88:91], v[164:167], v[206:209], v[88:91]
	v_mfma_f32_16x16x32_bf16 v[76:79], v[156:159], v[214:217], v[76:79]
	v_mfma_f32_16x16x32_bf16 v[72:75], v[164:167], v[214:217], v[72:75]
	v_mfma_f32_16x16x32_bf16 v[124:127], v[160:163], v[194:197], v[124:127]
	v_mfma_f32_16x16x32_bf16 v[120:123], v[168:171], v[194:197], v[120:123]
	v_mfma_f32_16x16x32_bf16 v[108:111], v[160:163], v[202:205], v[108:111]
	v_mfma_f32_16x16x32_bf16 v[104:107], v[168:171], v[202:205], v[104:107]
	v_mfma_f32_16x16x32_bf16 v[92:95], v[160:163], v[210:213], v[92:95]
	v_mfma_f32_16x16x32_bf16 v[88:91], v[168:171], v[210:213], v[88:91]
	v_mfma_f32_16x16x32_bf16 v[76:79], v[160:163], v[218:221], v[76:79]
	v_mfma_f32_16x16x32_bf16 v[72:75], v[168:171], v[218:221], v[72:75]
	s_setprio 0
	s_setprio 1
	v_mfma_f32_16x16x32_bf16 v[116:119], v[172:175], v[190:193], v[116:119]
	v_mfma_f32_16x16x32_bf16 v[112:115], v[180:183], v[190:193], v[112:115]
	v_mfma_f32_16x16x32_bf16 v[100:103], v[172:175], v[198:201], v[100:103]
	v_mfma_f32_16x16x32_bf16 v[96:99], v[180:183], v[198:201], v[96:99]
	v_mfma_f32_16x16x32_bf16 v[84:87], v[172:175], v[206:209], v[84:87]
	v_mfma_f32_16x16x32_bf16 v[80:83], v[180:183], v[206:209], v[80:83]
	v_mfma_f32_16x16x32_bf16 v[68:71], v[172:175], v[214:217], v[68:71]
	v_mfma_f32_16x16x32_bf16 v[64:67], v[180:183], v[214:217], v[64:67]
	v_mfma_f32_16x16x32_bf16 v[116:119], v[176:179], v[194:197], v[116:119]
	v_mfma_f32_16x16x32_bf16 v[112:115], v[186:189], v[194:197], v[112:115]
	v_mfma_f32_16x16x32_bf16 v[100:103], v[176:179], v[202:205], v[100:103]
	v_mfma_f32_16x16x32_bf16 v[96:99], v[186:189], v[202:205], v[96:99]
	v_mfma_f32_16x16x32_bf16 v[84:87], v[176:179], v[210:213], v[84:87]
	v_mfma_f32_16x16x32_bf16 v[80:83], v[186:189], v[210:213], v[80:83]
	v_mfma_f32_16x16x32_bf16 v[68:71], v[176:179], v[218:221], v[68:71]
	v_mfma_f32_16x16x32_bf16 v[64:67], v[186:189], v[218:221], v[64:67]
	s_setprio 0
	s_barrier
; #define PG8_STAGE(bufoff, gbase, voff) do { _Pragma("unroll") for (int _i = 0; _i < 2; ++_i) \
;         __builtin_amdgcn_global_load_lds((const unsigned*)((const char*)(gbase) + (voff)[_i]), (PG8_LAS unsigned*)(lds + (bufoff) + ldsw + _i * 8192), 16, 0, 0); } while (0)
; #define PG8_LDA(dst, b, h) do { _Pragma("unroll") for (int m = 0; m < 4; ++m) _Pragma("unroll") for (int k = 0; k < 2; ++k) dst[m][k] = *(const PG8_LAS bf16x8*)(lds + PG8_SA(b, h) + aoff + m * 2048 + k * 1024); } while (0)
; #define PG8_LDB(dst, b, h) do { _Pragma("unroll") for (int n = 0; n < 2; ++n) _Pragma("unroll") for (int k = 0; k < 2; ++k) dst[n][k] = *(const PG8_LAS bf16x8*)(lds + PG8_SB(b, h) + boff + n * 2048 + k * 1024); } while (0)
; #define PG8_MMA(ai, bj, At, Bt) do { __builtin_amdgcn_s_setprio(1); _Pragma("unroll") for (int m = 0; m < 4; ++m) _Pragma("unroll") for (int n = 0; n < 2; ++n) _Pragma("unroll") for (int k = 0; k < 2; ++k) \
;         acc[ai][bj][m][n] = __builtin_amdgcn_mfma_f32_16x16x32_bf16(Bt[n][k], At[m][k], acc[ai][bj][m][n], 0, 0, 0); __builtin_amdgcn_s_setprio(0); } while (0)
; #define PG8_WAIT_V(n) asm volatile("s_waitcnt vmcnt(" #n ")" ::: "memory")
; #define PG8_WAIT_L(n) asm volatile("s_waitcnt lgkmcnt(" #n ")" ::: "memory")
; #define PG8_BAR __builtin_amdgcn_s_barrier()
; #define PG8_SCHED __builtin_amdgcn_sched_barrier(0)
; template <class Epi, class Sched, bool ALIGN_EPI = false, bool SP2 = false>
; __device__ __forceinline__ void gemm_phase(PG8_LAS unsigned char* lds, const Gemm g, const Sched& S, const Epi& E) {
;     ...
;             PG8_LDA(At, 0, 1); PG8_STAGE(PG8_SB(0, 0), b2, voffB); PG8_STAGE(PG8_SB(0, 1), b2 + hstep, voffB); PG8_STAGE(PG8_SA(0, 0), a2, voffA);
;             PG8_WAIT_V(8); PG8_WAIT_L(0); PG8_BAR; PG8_MMA(1, 0, At, B0); PG8_MMA(1, 1, At, B1); PG8_BAR; PG8_SCHED;
;             PG8_LDB(B0, 1, 0); PG8_LDB(B1, 1, 1); PG8_SCHED; PG8_LDA(At, 1, 0); PG8_STAGE(PG8_SA(0, 1), a2 + hstep, voffA);
	s_add_i32 s52, s42, s30
	v_lshl_add_u64 v[146:147], s[24:25], 0, v[132:133]
	s_mov_b32 m0, s52
	ds_read_b128 v[190:193], v152 offset:16384
	ds_read_b128 v[194:197], v152 offset:17408
	ds_read_b128 v[198:201], v152 offset:18432
	ds_read_b128 v[202:205], v152 offset:19456
	ds_read_b128 v[206:209], v152 offset:20480
	ds_read_b128 v[210:213], v152 offset:21504
	ds_read_b128 v[214:217], v152 offset:22528
	ds_read_b128 v[218:221], v152 offset:23552
	global_load_lds_dwordx4 v[146:147], off
	s_add_i32 m0, s52, 0x2000
	s_add_u32 s52, s24, 0x40000
	v_lshl_add_u64 v[222:223], s[24:25], 0, v[128:129]
	s_addc_u32 s53, s25, 0
	s_add_i32 s54, s43, s30
	global_load_lds_dwordx4 v[222:223], off
	v_lshl_add_u64 v[224:225], s[52:53], 0, v[132:133]
	s_mov_b32 m0, s54
	v_lshl_add_u64 v[226:227], s[26:27], 0, v[130:131]
	global_load_lds_dwordx4 v[224:225], off
	v_lshl_add_u64 v[224:225], s[52:53], 0, v[128:129]
	s_add_i32 m0, s54, 0x2000
	s_nop 0
	global_load_lds_dwordx4 v[224:225], off
	v_lshl_add_u64 v[224:225], s[26:27], 0, v[134:135]
	s_mov_b32 m0, s21
	s_nop 0
	global_load_lds_dwordx4 v[224:225], off
	s_mov_b32 m0, s35
	s_nop 0
	global_load_lds_dwordx4 v[226:227], off
	s_waitcnt vmcnt(8)
	s_waitcnt lgkmcnt(0)
	s_barrier
	s_setprio 1
	s_waitcnt lgkmcnt(0)
	v_mfma_f32_16x16x32_bf16 v[60:63], v[156:159], v[190:193], v[60:63]
	v_mfma_f32_16x16x32_bf16 v[56:59], v[164:167], v[190:193], v[56:59]
	v_mfma_f32_16x16x32_bf16 v[44:47], v[156:159], v[198:201], v[44:47]
	v_mfma_f32_16x16x32_bf16 v[40:43], v[164:167], v[198:201], v[40:43]
	v_mfma_f32_16x16x32_bf16 v[28:31], v[156:159], v[206:209], v[28:31]
	v_mfma_f32_16x16x32_bf16 v[24:27], v[164:167], v[206:209], v[24:27]
	v_mfma_f32_16x16x32_bf16 v[12:15], v[156:159], v[214:217], v[12:15]
	v_mfma_f32_16x16x32_bf16 v[8:11], v[164:167], v[214:217], v[8:11]
	v_mfma_f32_16x16x32_bf16 v[60:63], v[160:163], v[194:197], v[60:63]
	v_mfma_f32_16x16x32_bf16 v[56:59], v[168:171], v[194:197], v[56:59]
	v_mfma_f32_16x16x32_bf16 v[44:47], v[160:163], v[202:205], v[44:47]
	v_mfma_f32_16x16x32_bf16 v[40:43], v[168:171], v[202:205], v[40:43]
	v_mfma_f32_16x16x32_bf16 v[28:31], v[160:163], v[210:213], v[28:31]
	v_mfma_f32_16x16x32_bf16 v[24:27], v[168:171], v[210:213], v[24:27]
	v_mfma_f32_16x16x32_bf16 v[12:15], v[160:163], v[218:221], v[12:15]
	v_mfma_f32_16x16x32_bf16 v[8:11], v[168:171], v[218:221], v[8:11]
	s_setprio 0
	s_setprio 1
	v_mfma_f32_16x16x32_bf16 v[52:55], v[172:175], v[190:193], v[52:55]
	v_mfma_f32_16x16x32_bf16 v[48:51], v[180:183], v[190:193], v[48:51]
	v_mfma_f32_16x16x32_bf16 v[36:39], v[172:175], v[198:201], v[36:39]
	v_mfma_f32_16x16x32_bf16 v[32:35], v[180:183], v[198:201], v[32:35]
	v_mfma_f32_16x16x32_bf16 v[20:23], v[172:175], v[206:209], v[20:23]
	v_mfma_f32_16x16x32_bf16 v[16:19], v[180:183], v[206:209], v[16:19]
	v_mfma_f32_16x16x32_bf16 v[4:7], v[172:175], v[214:217], v[4:7]
	v_mfma_f32_16x16x32_bf16 v[0:3], v[180:183], v[214:217], v[0:3]
	v_mfma_f32_16x16x32_bf16 v[52:55], v[176:179], v[194:197], v[52:55]
	v_mfma_f32_16x16x32_bf16 v[48:51], v[186:189], v[194:197], v[48:51]
	v_mfma_f32_16x16x32_bf16 v[36:39], v[176:179], v[202:205], v[36:39]
	v_mfma_f32_16x16x32_bf16 v[32:35], v[186:189], v[202:205], v[32:35]
	v_mfma_f32_16x16x32_bf16 v[20:23], v[176:179], v[210:213], v[20:23]
	v_mfma_f32_16x16x32_bf16 v[16:19], v[186:189], v[210:213], v[16:19]
	v_mfma_f32_16x16x32_bf16 v[4:7], v[176:179], v[218:221], v[4:7]
	v_mfma_f32_16x16x32_bf16 v[0:3], v[186:189], v[218:221], v[0:3]
	s_setprio 0
	s_barrier
	ds_read_b128 v[156:159], v153
	ds_read_b128 v[160:163], v153 offset:1024
	ds_read_b128 v[164:167], v153 offset:2048
	ds_read_b128 v[168:171], v153 offset:3072
	ds_read_b128 v[172:175], v154
	ds_read_b128 v[176:179], v154 offset:1024
	ds_read_b128 v[180:183], v154 offset:2048
	ds_read_b128 v[186:189], v154 offset:3072
	s_add_u32 s26, s26, 0x40000
	s_addc_u32 s27, s27, 0
	s_mov_b32 m0, s36
	v_lshl_add_u64 v[228:229], s[26:27], 0, v[134:135]
	ds_read_b128 v[190:193], v152 offset:32768
	ds_read_b128 v[194:197], v152 offset:33792
	ds_read_b128 v[198:201], v152 offset:34816
	ds_read_b128 v[202:205], v152 offset:35840
	ds_read_b128 v[206:209], v152 offset:36864
	ds_read_b128 v[210:213], v152 offset:37888
	ds_read_b128 v[214:217], v152 offset:38912
	ds_read_b128 v[218:221], v152 offset:39936
	global_load_lds_dwordx4 v[228:229], off
	v_lshl_add_u64 v[228:229], s[26:27], 0, v[130:131]
	s_mov_b32 m0, s37
	s_nop 0
	global_load_lds_dwordx4 v[228:229], off
	s_waitcnt vmcnt(8)
	s_waitcnt lgkmcnt(0)
	s_barrier
; #define PG8_STAGE(bufoff, gbase, voff) do { _Pragma("unroll") for (int _i = 0; _i < 2; ++_i) \
;         __builtin_amdgcn_global_load_lds((const unsigned*)((const char*)(gbase) + (voff)[_i]), (PG8_LAS unsigned*)(lds + (bufoff) + ldsw + _i * 8192), 16, 0, 0); } while (0)
; #define PG8_LDA(dst, b, h) do { _Pragma("unroll") for (int m = 0; m < 4; ++m) _Pragma("unroll") for (int k = 0; k < 2; ++k) dst[m][k] = *(const PG8_LAS bf16x8*)(lds + PG8_SA(b, h) + aoff + m * 2048 + k * 1024); } while (0)
; #define PG8_MMA(ai, bj, At, Bt) do { __builtin_amdgcn_s_setprio(1); _Pragma("unroll") for (int m = 0; m < 4; ++m) _Pragma("unroll") for (int n = 0; n < 2; ++n) _Pragma("unroll") for (int k = 0; k < 2; ++k) \
;         acc[ai][bj][m][n] = __builtin_amdgcn_mfma_f32_16x16x32_bf16(Bt[n][k], At[m][k], acc[ai][bj][m][n], 0, 0, 0); __builtin_amdgcn_s_setprio(0); } while (0)
; #define PG8_WAIT_V(n) asm volatile("s_waitcnt vmcnt(" #n ")" ::: "memory")
; #define PG8_WAIT_L(n) asm volatile("s_waitcnt lgkmcnt(" #n ")" ::: "memory")
; #define PG8_BAR __builtin_amdgcn_s_barrier()
; #define PG8_SCHED __builtin_amdgcn_sched_barrier(0)
; template <class Epi, class Sched, bool ALIGN_EPI = false, bool SP2 = false>
; __device__ __forceinline__ void gemm_phase(PG8_LAS unsigned char* lds, const Gemm g, const Sched& S, const Epi& E) {
;     ...
;             PG8_WAIT_V(8); PG8_WAIT_L(0); PG8_BAR; PG8_MMA(0, 0, At, B0); PG8_MMA(0, 1, At, B1); PG8_BAR; PG8_SCHED;
;             PG8_LDA(At, 1, 1); PG8_STAGE(PG8_SB(1, 0), b3, voffB); PG8_STAGE(PG8_SB(1, 1), b3 + hstep, voffB); PG8_STAGE(PG8_SA(1, 0), a3, voffA);
;             PG8_WAIT_V(8); PG8_WAIT_L(0); PG8_BAR; PG8_MMA(1, 0, At, B0); PG8_MMA(1, 1, At, B1); PG8_BAR; PG8_SCHED;
;     ...
;         if constexpr (ALIGN_EPI) { if (wr == 0) PG8_BAR; }
	s_setprio 1
	s_waitcnt lgkmcnt(0)
	v_mfma_f32_16x16x32_bf16 v[124:127], v[156:159], v[190:193], v[124:127]
	v_mfma_f32_16x16x32_bf16 v[120:123], v[164:167], v[190:193], v[120:123]
	v_mfma_f32_16x16x32_bf16 v[108:111], v[156:159], v[198:201], v[108:111]
	v_mfma_f32_16x16x32_bf16 v[104:107], v[164:167], v[198:201], v[104:107]
	v_mfma_f32_16x16x32_bf16 v[92:95], v[156:159], v[206:209], v[92:95]
	v_mfma_f32_16x16x32_bf16 v[88:91], v[164:167], v[206:209], v[88:91]
	v_mfma_f32_16x16x32_bf16 v[76:79], v[156:159], v[214:217], v[76:79]
	v_mfma_f32_16x16x32_bf16 v[72:75], v[164:167], v[214:217], v[72:75]
	v_mfma_f32_16x16x32_bf16 v[124:127], v[160:163], v[194:197], v[124:127]
	v_mfma_f32_16x16x32_bf16 v[120:123], v[168:171], v[194:197], v[120:123]
	v_mfma_f32_16x16x32_bf16 v[108:111], v[160:163], v[202:205], v[108:111]
	v_mfma_f32_16x16x32_bf16 v[104:107], v[168:171], v[202:205], v[104:107]
	v_mfma_f32_16x16x32_bf16 v[92:95], v[160:163], v[210:213], v[92:95]
	v_mfma_f32_16x16x32_bf16 v[88:91], v[168:171], v[210:213], v[88:91]
	v_mfma_f32_16x16x32_bf16 v[76:79], v[160:163], v[218:221], v[76:79]
	v_mfma_f32_16x16x32_bf16 v[72:75], v[168:171], v[218:221], v[72:75]
	s_setprio 0
	s_setprio 1
	v_mfma_f32_16x16x32_bf16 v[116:119], v[172:175], v[190:193], v[116:119]
	v_mfma_f32_16x16x32_bf16 v[112:115], v[180:183], v[190:193], v[112:115]
	v_mfma_f32_16x16x32_bf16 v[100:103], v[172:175], v[198:201], v[100:103]
	v_mfma_f32_16x16x32_bf16 v[96:99], v[180:183], v[198:201], v[96:99]
	v_mfma_f32_16x16x32_bf16 v[84:87], v[172:175], v[206:209], v[84:87]
	v_mfma_f32_16x16x32_bf16 v[80:83], v[180:183], v[206:209], v[80:83]
	v_mfma_f32_16x16x32_bf16 v[68:71], v[172:175], v[214:217], v[68:71]
	v_mfma_f32_16x16x32_bf16 v[64:67], v[180:183], v[214:217], v[64:67]
	v_mfma_f32_16x16x32_bf16 v[116:119], v[176:179], v[194:197], v[116:119]
	v_mfma_f32_16x16x32_bf16 v[112:115], v[186:189], v[194:197], v[112:115]
	v_mfma_f32_16x16x32_bf16 v[100:103], v[176:179], v[202:205], v[100:103]
	v_mfma_f32_16x16x32_bf16 v[96:99], v[186:189], v[202:205], v[96:99]
	v_mfma_f32_16x16x32_bf16 v[84:87], v[176:179], v[210:213], v[84:87]
	v_mfma_f32_16x16x32_bf16 v[80:83], v[186:189], v[210:213], v[80:83]
	v_mfma_f32_16x16x32_bf16 v[68:71], v[176:179], v[218:221], v[68:71]
	v_mfma_f32_16x16x32_bf16 v[64:67], v[186:189], v[218:221], v[64:67]
	s_setprio 0
	s_barrier
	s_add_i32 s26, s45, s30
	v_lshl_add_u64 v[146:147], v[146:147], 0, s[6:7]
	s_mov_b32 m0, s26
	ds_read_b128 v[190:193], v152 offset:49152
	ds_read_b128 v[194:197], v152 offset:50176
	ds_read_b128 v[198:201], v152 offset:51200
	ds_read_b128 v[202:205], v152 offset:52224
	ds_read_b128 v[206:209], v152 offset:53248
	ds_read_b128 v[210:213], v152 offset:54272
	ds_read_b128 v[214:217], v152 offset:55296
	ds_read_b128 v[218:221], v152 offset:56320
	global_load_lds_dwordx4 v[146:147], off
	s_add_i32 m0, s26, 0x2000
	s_add_u32 s24, s24, 0x40080
	v_lshl_add_u64 v[146:147], v[222:223], 0, s[6:7]
	s_addc_u32 s25, s25, 0
	s_add_i32 s26, s46, s30
	global_load_lds_dwordx4 v[146:147], off
	v_lshl_add_u64 v[146:147], s[24:25], 0, v[132:133]
	s_mov_b32 m0, s26
	s_nop 0
	global_load_lds_dwordx4 v[146:147], off
	v_lshl_add_u64 v[146:147], s[24:25], 0, v[128:129]
	s_add_i32 m0, s26, 0x2000
	s_nop 0
	global_load_lds_dwordx4 v[146:147], off
	v_lshl_add_u64 v[146:147], v[224:225], 0, s[6:7]
	s_mov_b32 m0, s39
	s_nop 0
	global_load_lds_dwordx4 v[146:147], off
	v_lshl_add_u64 v[146:147], v[226:227], 0, s[6:7]
	s_mov_b32 m0, s40
	s_nop 0
	global_load_lds_dwordx4 v[146:147], off
	s_waitcnt vmcnt(8)
	s_waitcnt lgkmcnt(0)
	s_barrier
	s_setprio 1
	s_waitcnt lgkmcnt(0)
	v_mfma_f32_16x16x32_bf16 v[60:63], v[156:159], v[190:193], v[60:63]
	v_mfma_f32_16x16x32_bf16 v[56:59], v[164:167], v[190:193], v[56:59]
	v_mfma_f32_16x16x32_bf16 v[44:47], v[156:159], v[198:201], v[44:47]
	v_mfma_f32_16x16x32_bf16 v[40:43], v[164:167], v[198:201], v[40:43]
	v_mfma_f32_16x16x32_bf16 v[28:31], v[156:159], v[206:209], v[28:31]
	v_mfma_f32_16x16x32_bf16 v[24:27], v[164:167], v[206:209], v[24:27]
	v_mfma_f32_16x16x32_bf16 v[12:15], v[156:159], v[214:217], v[12:15]
	v_mfma_f32_16x16x32_bf16 v[8:11], v[164:167], v[214:217], v[8:11]
	v_mfma_f32_16x16x32_bf16 v[60:63], v[160:163], v[194:197], v[60:63]
	v_mfma_f32_16x16x32_bf16 v[56:59], v[168:171], v[194:197], v[56:59]
	v_mfma_f32_16x16x32_bf16 v[44:47], v[160:163], v[202:205], v[44:47]
	v_mfma_f32_16x16x32_bf16 v[40:43], v[168:171], v[202:205], v[40:43]
	v_mfma_f32_16x16x32_bf16 v[28:31], v[160:163], v[210:213], v[28:31]
	v_mfma_f32_16x16x32_bf16 v[24:27], v[168:171], v[210:213], v[24:27]
	v_mfma_f32_16x16x32_bf16 v[12:15], v[160:163], v[218:221], v[12:15]
	v_mfma_f32_16x16x32_bf16 v[8:11], v[168:171], v[218:221], v[8:11]
	s_setprio 0
	s_setprio 1
	v_mfma_f32_16x16x32_bf16 v[52:55], v[172:175], v[190:193], v[52:55]
	v_mfma_f32_16x16x32_bf16 v[48:51], v[180:183], v[190:193], v[48:51]
	v_mfma_f32_16x16x32_bf16 v[36:39], v[172:175], v[198:201], v[36:39]
	v_mfma_f32_16x16x32_bf16 v[32:35], v[180:183], v[198:201], v[32:35]
	v_mfma_f32_16x16x32_bf16 v[20:23], v[172:175], v[206:209], v[20:23]
	v_mfma_f32_16x16x32_bf16 v[16:19], v[180:183], v[206:209], v[16:19]
	v_mfma_f32_16x16x32_bf16 v[4:7], v[172:175], v[214:217], v[4:7]
	v_mfma_f32_16x16x32_bf16 v[0:3], v[180:183], v[214:217], v[0:3]
	v_mfma_f32_16x16x32_bf16 v[52:55], v[176:179], v[194:197], v[52:55]
	v_mfma_f32_16x16x32_bf16 v[48:51], v[186:189], v[194:197], v[48:51]
	v_mfma_f32_16x16x32_bf16 v[36:39], v[176:179], v[202:205], v[36:39]
	v_mfma_f32_16x16x32_bf16 v[32:35], v[186:189], v[202:205], v[32:35]
	v_mfma_f32_16x16x32_bf16 v[20:23], v[176:179], v[210:213], v[20:23]
	v_mfma_f32_16x16x32_bf16 v[16:19], v[186:189], v[210:213], v[16:19]
	v_mfma_f32_16x16x32_bf16 v[4:7], v[176:179], v[218:221], v[4:7]
	v_mfma_f32_16x16x32_bf16 v[0:3], v[186:189], v[218:221], v[0:3]
	s_setprio 0
	s_barrier
	s_add_i32 s51, s51, 2
	s_add_u32 s22, s22, 0x100
	s_addc_u32 s23, s23, 0
	s_add_u32 s49, s49, 0x100
	s_addc_u32 s50, s50, 0
	s_cmp_gt_u32 s51, 13
	s_cbranch_scc0 .LBB0_435
	s_and_b64 vcc, exec, s[8:9]
	s_cbranch_vccz .LBB0_438
	s_barrier

; #define PG8_STAGE(bufoff, gbase, voff) do { _Pragma("unroll") for (int _i = 0; _i < 2; ++_i) \
;         __builtin_amdgcn_global_load_lds((const unsigned*)((const char*)(gbase) + (voff)[_i]), (PG8_LAS unsigned*)(lds + (bufoff) + ldsw + _i * 8192), 16, 0, 0); } while (0)
; #define PG8_LDA(dst, b, h) do { _Pragma("unroll") for (int m = 0; m < 4; ++m) _Pragma("unroll") for (int k = 0; k < 2; ++k) dst[m][k] = *(const PG8_LAS bf16x8*)(lds + PG8_SA(b, h) + aoff + m * 2048 + k * 1024); } while (0)
; #define PG8_LDB(dst, b, h) do { _Pragma("unroll") for (int n = 0; n < 2; ++n) _Pragma("unroll") for (int k = 0; k < 2; ++k) dst[n][k] = *(const PG8_LAS bf16x8*)(lds + PG8_SB(b, h) + boff + n * 2048 + k * 1024); } while (0)
; #define PG8_MMA(ai, bj, At, Bt) do { __builtin_amdgcn_s_setprio(1); _Pragma("unroll") for (int m = 0; m < 4; ++m) _Pragma("unroll") for (int n = 0; n < 2; ++n) _Pragma("unroll") for (int k = 0; k < 2; ++k) \
;         acc[ai][bj][m][n] = __builtin_amdgcn_mfma_f32_16x16x32_bf16(Bt[n][k], At[m][k], acc[ai][bj][m][n], 0, 0, 0); __builtin_amdgcn_s_setprio(0); } while (0)
; #define PG8_WAIT_V(n) asm volatile("s_waitcnt vmcnt(" #n ")" ::: "memory")
; #define PG8_WAIT_L(n) asm volatile("s_waitcnt lgkmcnt(" #n ")" ::: "memory")
; #define PG8_BAR __builtin_amdgcn_s_barrier()
; #define PG8_SCHED __builtin_amdgcn_sched_barrier(0)
; template <class Epi, class Sched, bool ALIGN_EPI = false, bool SP2 = false>
; __device__ __forceinline__ void gemm_phase(PG8_LAS unsigned char* lds, const Gemm g, const Sched& S, const Epi& E) {
;     ...
;             PG8_LDB(B0, 0, 0); PG8_LDB(B1, 0, 1); PG8_SCHED; PG8_LDA(At, 0, 0); PG8_STAGE(PG8_SA(1, 1), a1 + hstep, voffA);
;             PG8_WAIT_V(8); PG8_WAIT_L(0); PG8_BAR; PG8_MMA(0, 0, At, B0); PG8_MMA(0, 1, At, B1); PG8_BAR; PG8_SCHED;
;     ...
; #pragma unroll
;         for (int a = 0; a < 2; ++a)
; #pragma unroll
;             for (int b = 0; b < 2; ++b)
; #pragma unroll
;                 for (int m = 0; m < 4; ++m)
; #pragma unroll
;                     for (int n = 0; n < 2; ++n) acc[a][b][m][n] = (f32x4){0.f, 0.f, 0.f, 0.f};
;         cur = nxt; cA = nA; cB = nB; ++ui;
.LBB0_515:
	s_add_u32 s26, s26, 0xb0080
	s_addc_u32 s27, s27, 0
	s_add_u32 s55, s28, 0x100
	v_mov_b32_e32 v0, 0
	s_addc_u32 s56, s29, 0
	s_mov_b32 s57, -2
	v_mov_b32_e32 v1, 0
	v_mov_b64_e32 v[2:3], 0
	v_mov_b64_e32 v[4:5], 0
	v_mov_b64_e32 v[6:7], 0
	v_mov_b64_e32 v[8:9], 0
	v_mov_b64_e32 v[10:11], 0
	v_mov_b64_e32 v[12:13], 0
	v_mov_b64_e32 v[14:15], 0
	v_mov_b64_e32 v[16:17], 0
	v_mov_b64_e32 v[18:19], 0
	v_mov_b64_e32 v[20:21], 0
	v_mov_b64_e32 v[22:23], 0
	v_mov_b64_e32 v[24:25], 0
	v_mov_b64_e32 v[26:27], 0
	v_mov_b64_e32 v[28:29], 0
	v_mov_b64_e32 v[30:31], 0
	v_mov_b64_e32 v[32:33], 0
	v_mov_b64_e32 v[34:35], 0
	v_mov_b64_e32 v[36:37], 0
	v_mov_b64_e32 v[38:39], 0
	v_mov_b64_e32 v[40:41], 0
	v_mov_b64_e32 v[42:43], 0
	v_mov_b64_e32 v[44:45], 0
	v_mov_b64_e32 v[46:47], 0
	v_mov_b64_e32 v[48:49], 0
	v_mov_b64_e32 v[50:51], 0
	v_mov_b64_e32 v[52:53], 0
	v_mov_b64_e32 v[54:55], 0
	v_mov_b64_e32 v[56:57], 0
	v_mov_b64_e32 v[58:59], 0
	v_mov_b64_e32 v[60:61], 0
	v_mov_b64_e32 v[62:63], 0
	v_mov_b64_e32 v[64:65], 0
	v_mov_b64_e32 v[66:67], 0
	v_mov_b64_e32 v[68:69], 0
	v_mov_b64_e32 v[70:71], 0
	v_mov_b64_e32 v[72:73], 0
	v_mov_b64_e32 v[74:75], 0
	v_mov_b64_e32 v[76:77], 0
	v_mov_b64_e32 v[78:79], 0
	v_mov_b64_e32 v[80:81], 0
	v_mov_b64_e32 v[82:83], 0
	v_mov_b64_e32 v[84:85], 0
	v_mov_b64_e32 v[86:87], 0
	v_mov_b64_e32 v[88:89], 0
	v_mov_b64_e32 v[90:91], 0
	v_mov_b64_e32 v[92:93], 0
	v_mov_b64_e32 v[94:95], 0
	v_mov_b64_e32 v[96:97], 0
	v_mov_b64_e32 v[98:99], 0
	v_mov_b64_e32 v[100:101], 0
	v_mov_b64_e32 v[102:103], 0
	v_mov_b64_e32 v[104:105], 0
	v_mov_b64_e32 v[106:107], 0
	v_mov_b64_e32 v[108:109], 0
	v_mov_b64_e32 v[110:111], 0
	v_mov_b64_e32 v[112:113], 0
	v_mov_b64_e32 v[114:115], 0
	v_mov_b64_e32 v[116:117], 0
	v_mov_b64_e32 v[118:119], 0
	v_mov_b64_e32 v[120:121], 0
	v_mov_b64_e32 v[122:123], 0
	v_mov_b64_e32 v[124:125], 0
	v_mov_b64_e32 v[126:127], 0
	s_branch .Lz64_1
	s_nop 0
	s_nop 0
	s_nop 0
	s_nop 0
	s_nop 0
	s_nop 0
	s_nop 0
	s_nop 0
	s_nop 0
	s_nop 0
	s_nop 0
	s_nop 0
	s_nop 0
	s_nop 0
	s_nop 0
	s_nop 0
	s_nop 0
	s_nop 0
	s_nop 0
	s_nop 0
	s_nop 0
	s_nop 0
	s_nop 0
	s_nop 0
	s_nop 0
	s_nop 0
	s_nop 0
	s_nop 0
	s_nop 0
	s_nop 0
	s_nop 0
	s_nop 0
	s_nop 0
	s_nop 0
	s_nop 0
	s_nop 0
	s_nop 0
	s_nop 0
	s_nop 0
	s_nop 0
	s_nop 0
	s_nop 0
	s_nop 0
	s_nop 0
	s_nop 0
	s_nop 0
	s_nop 0
	s_nop 0
	s_nop 0
	s_nop 0
	s_nop 0
	s_nop 0
	s_nop 0
	s_nop 0
	s_nop 0
	s_nop 0
	s_nop 0
	s_nop 0
	s_nop 0
	s_nop 0
	s_nop 0
	s_nop 0
.Lz64_1:
.LBB0_516:
	ds_read_b128 v[146:149], v162
	ds_read_b128 v[150:153], v162 offset:1024
	ds_read_b128 v[154:157], v162 offset:2048
	ds_read_b128 v[168:171], v162 offset:3072
	ds_read_b128 v[172:175], v163
	ds_read_b128 v[176:179], v163 offset:1024
	ds_read_b128 v[180:183], v163 offset:2048
	ds_read_b128 v[186:189], v163 offset:3072
	s_add_u32 s28, s26, 0xfff50080
	s_addc_u32 s29, s27, -1
	s_cmp_eq_u32 s57, 40
	s_cselect_b32 s31, s7, s29
	s_cselect_b32 s30, s6, s28
	s_cselect_b32 s29, s25, s56
	s_cselect_b32 s28, s24, s55
	v_lshl_add_u64 v[158:159], s[26:27], 0, v[136:137]
	s_add_i32 m0, s37, 0xc000
	ds_read_b128 v[190:193], v164
	ds_read_b128 v[194:197], v164 offset:1024
	ds_read_b128 v[198:201], v164 offset:2048
	ds_read_b128 v[202:205], v164 offset:3072
	ds_read_b128 v[206:209], v164 offset:4096
	ds_read_b128 v[210:213], v164 offset:5120
	ds_read_b128 v[214:217], v164 offset:6144
	ds_read_b128 v[218:221], v164 offset:7168
	global_load_lds_dwordx4 v[158:159], off
	v_lshl_add_u64 v[158:159], s[26:27], 0, v[138:139]
	s_add_i32 m0, s37, 0xe000
	s_nop 0
	global_load_lds_dwordx4 v[158:159], off
	s_waitcnt vmcnt(8)
	s_waitcnt lgkmcnt(0)
	s_barrier
	s_setprio 1
	s_waitcnt lgkmcnt(0)
	v_mfma_f32_16x16x32_bf16 v[124:127], v[146:149], v[190:193], v[124:127]
	v_mfma_f32_16x16x32_bf16 v[120:123], v[154:157], v[190:193], v[120:123]
	v_mfma_f32_16x16x32_bf16 v[108:111], v[146:149], v[198:201], v[108:111]
	v_mfma_f32_16x16x32_bf16 v[104:107], v[154:157], v[198:201], v[104:107]
	v_mfma_f32_16x16x32_bf16 v[92:95], v[146:149], v[206:209], v[92:95]
	v_mfma_f32_16x16x32_bf16 v[88:91], v[154:157], v[206:209], v[88:91]
	v_mfma_f32_16x16x32_bf16 v[76:79], v[146:149], v[214:217], v[76:79]
	v_mfma_f32_16x16x32_bf16 v[72:75], v[154:157], v[214:217], v[72:75]
	v_mfma_f32_16x16x32_bf16 v[124:127], v[150:153], v[194:197], v[124:127]
	v_mfma_f32_16x16x32_bf16 v[120:123], v[168:171], v[194:197], v[120:123]
	v_mfma_f32_16x16x32_bf16 v[108:111], v[150:153], v[202:205], v[108:111]
	v_mfma_f32_16x16x32_bf16 v[104:107], v[168:171], v[202:205], v[104:107]
	v_mfma_f32_16x16x32_bf16 v[92:95], v[150:153], v[210:213], v[92:95]
	v_mfma_f32_16x16x32_bf16 v[88:91], v[168:171], v[210:213], v[88:91]
	v_mfma_f32_16x16x32_bf16 v[76:79], v[150:153], v[218:221], v[76:79]
	v_mfma_f32_16x16x32_bf16 v[72:75], v[168:171], v[218:221], v[72:75]
	s_setprio 0
	s_setprio 1
	v_mfma_f32_16x16x32_bf16 v[116:119], v[172:175], v[190:193], v[116:119]
	v_mfma_f32_16x16x32_bf16 v[112:115], v[180:183], v[190:193], v[112:115]
	v_mfma_f32_16x16x32_bf16 v[100:103], v[172:175], v[198:201], v[100:103]
	v_mfma_f32_16x16x32_bf16 v[96:99], v[180:183], v[198:201], v[96:99]
	v_mfma_f32_16x16x32_bf16 v[84:87], v[172:175], v[206:209], v[84:87]
	v_mfma_f32_16x16x32_bf16 v[80:83], v[180:183], v[206:209], v[80:83]
	v_mfma_f32_16x16x32_bf16 v[68:71], v[172:175], v[214:217], v[68:71]
	v_mfma_f32_16x16x32_bf16 v[64:67], v[180:183], v[214:217], v[64:67]
	v_mfma_f32_16x16x32_bf16 v[116:119], v[176:179], v[194:197], v[116:119]
	v_mfma_f32_16x16x32_bf16 v[112:115], v[186:189], v[194:197], v[112:115]
	v_mfma_f32_16x16x32_bf16 v[100:103], v[176:179], v[202:205], v[100:103]
	v_mfma_f32_16x16x32_bf16 v[96:99], v[186:189], v[202:205], v[96:99]
	v_mfma_f32_16x16x32_bf16 v[84:87], v[176:179], v[210:213], v[84:87]
	v_mfma_f32_16x16x32_bf16 v[80:83], v[186:189], v[210:213], v[80:83]
	v_mfma_f32_16x16x32_bf16 v[68:71], v[176:179], v[218:221], v[68:71]
	v_mfma_f32_16x16x32_bf16 v[64:67], v[186:189], v[218:221], v[64:67]
	s_setprio 0
	s_barrier
; #define PG8_STAGE(bufoff, gbase, voff) do { _Pragma("unroll") for (int _i = 0; _i < 2; ++_i) \
;         __builtin_amdgcn_global_load_lds((const unsigned*)((const char*)(gbase) + (voff)[_i]), (PG8_LAS unsigned*)(lds + (bufoff) + ldsw + _i * 8192), 16, 0, 0); } while (0)
; #define PG8_LDA(dst, b, h) do { _Pragma("unroll") for (int m = 0; m < 4; ++m) _Pragma("unroll") for (int k = 0; k < 2; ++k) dst[m][k] = *(const PG8_LAS bf16x8*)(lds + PG8_SA(b, h) + aoff + m * 2048 + k * 1024); } while (0)
; #define PG8_LDB(dst, b, h) do { _Pragma("unroll") for (int n = 0; n < 2; ++n) _Pragma("unroll") for (int k = 0; k < 2; ++k) dst[n][k] = *(const PG8_LAS bf16x8*)(lds + PG8_SB(b, h) + boff + n * 2048 + k * 1024); } while (0)
; #define PG8_MMA(ai, bj, At, Bt) do { __builtin_amdgcn_s_setprio(1); _Pragma("unroll") for (int m = 0; m < 4; ++m) _Pragma("unroll") for (int n = 0; n < 2; ++n) _Pragma("unroll") for (int k = 0; k < 2; ++k) \
;         acc[ai][bj][m][n] = __builtin_amdgcn_mfma_f32_16x16x32_bf16(Bt[n][k], At[m][k], acc[ai][bj][m][n], 0, 0, 0); __builtin_amdgcn_s_setprio(0); } while (0)
; #define PG8_WAIT_V(n) asm volatile("s_waitcnt vmcnt(" #n ")" ::: "memory")
; #define PG8_WAIT_L(n) asm volatile("s_waitcnt lgkmcnt(" #n ")" ::: "memory")
; #define PG8_BAR __builtin_amdgcn_s_barrier()
; #define PG8_SCHED __builtin_amdgcn_sched_barrier(0)
; template <class Epi, class Sched, bool ALIGN_EPI = false, bool SP2 = false>
; __device__ __forceinline__ void gemm_phase(PG8_LAS unsigned char* lds, const Gemm g, const Sched& S, const Epi& E) {
;     ...
;             PG8_LDA(At, 0, 1); PG8_STAGE(PG8_SB(0, 0), b2, voffB); PG8_STAGE(PG8_SB(0, 1), b2 + hstep, voffB); PG8_STAGE(PG8_SA(0, 0), a2, voffA);
;             PG8_WAIT_V(8); PG8_WAIT_L(0); PG8_BAR; PG8_MMA(1, 0, At, B0); PG8_MMA(1, 1, At, B1); PG8_BAR; PG8_SCHED;
;             PG8_LDB(B0, 1, 0); PG8_LDB(B1, 1, 1); PG8_SCHED; PG8_LDA(At, 1, 0); PG8_STAGE(PG8_SA(0, 1), a2 + hstep, voffA);
	s_add_i32 s58, s48, s36
	v_lshl_add_u64 v[158:159], s[28:29], 0, v[130:131]
	s_mov_b32 m0, s58
	ds_read_b128 v[190:193], v164 offset:16384
	ds_read_b128 v[194:197], v164 offset:17408
	ds_read_b128 v[198:201], v164 offset:18432
	ds_read_b128 v[202:205], v164 offset:19456
	ds_read_b128 v[206:209], v164 offset:20480
	ds_read_b128 v[210:213], v164 offset:21504
	ds_read_b128 v[214:217], v164 offset:22528
	ds_read_b128 v[218:221], v164 offset:23552
	global_load_lds_dwordx4 v[158:159], off
	s_add_i32 m0, s58, 0x2000
	s_add_u32 s58, s28, 0xb0000
	v_lshl_add_u64 v[222:223], s[28:29], 0, v[134:135]
	s_addc_u32 s59, s29, 0
	s_add_i32 s60, s49, s36
	global_load_lds_dwordx4 v[222:223], off
	v_lshl_add_u64 v[224:225], s[58:59], 0, v[130:131]
	s_mov_b32 m0, s60
	v_lshl_add_u64 v[226:227], s[30:31], 0, v[132:133]
	global_load_lds_dwordx4 v[224:225], off
	v_lshl_add_u64 v[224:225], s[58:59], 0, v[134:135]
	s_add_i32 m0, s60, 0x2000
	s_nop 0
	global_load_lds_dwordx4 v[224:225], off
	v_lshl_add_u64 v[224:225], s[30:31], 0, v[128:129]
	s_mov_b32 m0, s37
	s_nop 0
	global_load_lds_dwordx4 v[224:225], off
	s_mov_b32 m0, s38
	s_nop 0
	global_load_lds_dwordx4 v[226:227], off
	s_waitcnt vmcnt(8)
	s_waitcnt lgkmcnt(0)
	s_barrier
	s_setprio 1
	s_waitcnt lgkmcnt(0)
	v_mfma_f32_16x16x32_bf16 v[60:63], v[146:149], v[190:193], v[60:63]
	v_mfma_f32_16x16x32_bf16 v[56:59], v[154:157], v[190:193], v[56:59]
	v_mfma_f32_16x16x32_bf16 v[44:47], v[146:149], v[198:201], v[44:47]
	v_mfma_f32_16x16x32_bf16 v[40:43], v[154:157], v[198:201], v[40:43]
	v_mfma_f32_16x16x32_bf16 v[28:31], v[146:149], v[206:209], v[28:31]
	v_mfma_f32_16x16x32_bf16 v[24:27], v[154:157], v[206:209], v[24:27]
	v_mfma_f32_16x16x32_bf16 v[12:15], v[146:149], v[214:217], v[12:15]
	v_mfma_f32_16x16x32_bf16 v[8:11], v[154:157], v[214:217], v[8:11]
	v_mfma_f32_16x16x32_bf16 v[60:63], v[150:153], v[194:197], v[60:63]
	v_mfma_f32_16x16x32_bf16 v[56:59], v[168:171], v[194:197], v[56:59]
	v_mfma_f32_16x16x32_bf16 v[44:47], v[150:153], v[202:205], v[44:47]
	v_mfma_f32_16x16x32_bf16 v[40:43], v[168:171], v[202:205], v[40:43]
	v_mfma_f32_16x16x32_bf16 v[28:31], v[150:153], v[210:213], v[28:31]
	v_mfma_f32_16x16x32_bf16 v[24:27], v[168:171], v[210:213], v[24:27]
	v_mfma_f32_16x16x32_bf16 v[12:15], v[150:153], v[218:221], v[12:15]
	v_mfma_f32_16x16x32_bf16 v[8:11], v[168:171], v[218:221], v[8:11]
	s_setprio 0
	s_setprio 1
	v_mfma_f32_16x16x32_bf16 v[52:55], v[172:175], v[190:193], v[52:55]
	v_mfma_f32_16x16x32_bf16 v[48:51], v[180:183], v[190:193], v[48:51]
	v_mfma_f32_16x16x32_bf16 v[36:39], v[172:175], v[198:201], v[36:39]
	v_mfma_f32_16x16x32_bf16 v[32:35], v[180:183], v[198:201], v[32:35]
	v_mfma_f32_16x16x32_bf16 v[20:23], v[172:175], v[206:209], v[20:23]
	v_mfma_f32_16x16x32_bf16 v[16:19], v[180:183], v[206:209], v[16:19]
	v_mfma_f32_16x16x32_bf16 v[4:7], v[172:175], v[214:217], v[4:7]
	v_mfma_f32_16x16x32_bf16 v[0:3], v[180:183], v[214:217], v[0:3]
	v_mfma_f32_16x16x32_bf16 v[52:55], v[176:179], v[194:197], v[52:55]
	v_mfma_f32_16x16x32_bf16 v[48:51], v[186:189], v[194:197], v[48:51]
	v_mfma_f32_16x16x32_bf16 v[36:39], v[176:179], v[202:205], v[36:39]
	v_mfma_f32_16x16x32_bf16 v[32:35], v[186:189], v[202:205], v[32:35]
	v_mfma_f32_16x16x32_bf16 v[20:23], v[176:179], v[210:213], v[20:23]
	v_mfma_f32_16x16x32_bf16 v[16:19], v[186:189], v[210:213], v[16:19]
	v_mfma_f32_16x16x32_bf16 v[4:7], v[176:179], v[218:221], v[4:7]
	v_mfma_f32_16x16x32_bf16 v[0:3], v[186:189], v[218:221], v[0:3]
	s_setprio 0
	s_barrier
	ds_read_b128 v[146:149], v165
	ds_read_b128 v[150:153], v165 offset:1024
	ds_read_b128 v[154:157], v165 offset:2048
	ds_read_b128 v[168:171], v165 offset:3072
	ds_read_b128 v[172:175], v166
	ds_read_b128 v[176:179], v166 offset:1024
	ds_read_b128 v[180:183], v166 offset:2048
	ds_read_b128 v[186:189], v166 offset:3072
	s_add_u32 s30, s30, 0xb0000
	s_addc_u32 s31, s31, 0
	s_mov_b32 m0, s39
	v_lshl_add_u64 v[228:229], s[30:31], 0, v[128:129]
	ds_read_b128 v[190:193], v164 offset:32768
	ds_read_b128 v[194:197], v164 offset:33792
	ds_read_b128 v[198:201], v164 offset:34816
	ds_read_b128 v[202:205], v164 offset:35840
	ds_read_b128 v[206:209], v164 offset:36864
	ds_read_b128 v[210:213], v164 offset:37888
	ds_read_b128 v[214:217], v164 offset:38912
	ds_read_b128 v[218:221], v164 offset:39936
	global_load_lds_dwordx4 v[228:229], off
	v_lshl_add_u64 v[228:229], s[30:31], 0, v[132:133]
	s_mov_b32 m0, s40
	s_nop 0
	global_load_lds_dwordx4 v[228:229], off
	s_waitcnt vmcnt(8)
	s_waitcnt lgkmcnt(0)
	s_barrier
; #define PG8_STAGE(bufoff, gbase, voff) do { _Pragma("unroll") for (int _i = 0; _i < 2; ++_i) \
;         __builtin_amdgcn_global_load_lds((const unsigned*)((const char*)(gbase) + (voff)[_i]), (PG8_LAS unsigned*)(lds + (bufoff) + ldsw + _i * 8192), 16, 0, 0); } while (0)
; #define PG8_LDA(dst, b, h) do { _Pragma("unroll") for (int m = 0; m < 4; ++m) _Pragma("unroll") for (int k = 0; k < 2; ++k) dst[m][k] = *(const PG8_LAS bf16x8*)(lds + PG8_SA(b, h) + aoff + m * 2048 + k * 1024); } while (0)
; #define PG8_MMA(ai, bj, At, Bt) do { __builtin_amdgcn_s_setprio(1); _Pragma("unroll") for (int m = 0; m < 4; ++m) _Pragma("unroll") for (int n = 0; n < 2; ++n) _Pragma("unroll") for (int k = 0; k < 2; ++k) \
;         acc[ai][bj][m][n] = __builtin_amdgcn_mfma_f32_16x16x32_bf16(Bt[n][k], At[m][k], acc[ai][bj][m][n], 0, 0, 0); __builtin_amdgcn_s_setprio(0); } while (0)
; #define PG8_WAIT_V(n) asm volatile("s_waitcnt vmcnt(" #n ")" ::: "memory")
; #define PG8_WAIT_L(n) asm volatile("s_waitcnt lgkmcnt(" #n ")" ::: "memory")
; #define PG8_BAR __builtin_amdgcn_s_barrier()
; #define PG8_SCHED __builtin_amdgcn_sched_barrier(0)
; template <class Epi, class Sched, bool ALIGN_EPI = false, bool SP2 = false>
; __device__ __forceinline__ void gemm_phase(PG8_LAS unsigned char* lds, const Gemm g, const Sched& S, const Epi& E) {
;     ...
;             PG8_WAIT_V(8); PG8_WAIT_L(0); PG8_BAR; PG8_MMA(0, 0, At, B0); PG8_MMA(0, 1, At, B1); PG8_BAR; PG8_SCHED;
;             PG8_LDA(At, 1, 1); PG8_STAGE(PG8_SB(1, 0), b3, voffB); PG8_STAGE(PG8_SB(1, 1), b3 + hstep, voffB); PG8_STAGE(PG8_SA(1, 0), a3, voffA);
;             PG8_WAIT_V(8); PG8_WAIT_L(0); PG8_BAR; PG8_MMA(1, 0, At, B0); PG8_MMA(1, 1, At, B1); PG8_BAR; PG8_SCHED;
;     ...
;         if constexpr (ALIGN_EPI) { if (wr == 0) PG8_BAR; }
	s_setprio 1
	s_waitcnt lgkmcnt(0)
	v_mfma_f32_16x16x32_bf16 v[124:127], v[146:149], v[190:193], v[124:127]
	v_mfma_f32_16x16x32_bf16 v[120:123], v[154:157], v[190:193], v[120:123]
	v_mfma_f32_16x16x32_bf16 v[108:111], v[146:149], v[198:201], v[108:111]
	v_mfma_f32_16x16x32_bf16 v[104:107], v[154:157], v[198:201], v[104:107]
	v_mfma_f32_16x16x32_bf16 v[92:95], v[146:149], v[206:209], v[92:95]
	v_mfma_f32_16x16x32_bf16 v[88:91], v[154:157], v[206:209], v[88:91]
	v_mfma_f32_16x16x32_bf16 v[76:79], v[146:149], v[214:217], v[76:79]
	v_mfma_f32_16x16x32_bf16 v[72:75], v[154:157], v[214:217], v[72:75]
	v_mfma_f32_16x16x32_bf16 v[124:127], v[150:153], v[194:197], v[124:127]
	v_mfma_f32_16x16x32_bf16 v[120:123], v[168:171], v[194:197], v[120:123]
	v_mfma_f32_16x16x32_bf16 v[108:111], v[150:153], v[202:205], v[108:111]
	v_mfma_f32_16x16x32_bf16 v[104:107], v[168:171], v[202:205], v[104:107]
	v_mfma_f32_16x16x32_bf16 v[92:95], v[150:153], v[210:213], v[92:95]
	v_mfma_f32_16x16x32_bf16 v[88:91], v[168:171], v[210:213], v[88:91]
	v_mfma_f32_16x16x32_bf16 v[76:79], v[150:153], v[218:221], v[76:79]
	v_mfma_f32_16x16x32_bf16 v[72:75], v[168:171], v[218:221], v[72:75]
	s_setprio 0
	s_setprio 1
	v_mfma_f32_16x16x32_bf16 v[116:119], v[172:175], v[190:193], v[116:119]
	v_mfma_f32_16x16x32_bf16 v[112:115], v[180:183], v[190:193], v[112:115]
	v_mfma_f32_16x16x32_bf16 v[100:103], v[172:175], v[198:201], v[100:103]
	v_mfma_f32_16x16x32_bf16 v[96:99], v[180:183], v[198:201], v[96:99]
	v_mfma_f32_16x16x32_bf16 v[84:87], v[172:175], v[206:209], v[84:87]
	v_mfma_f32_16x16x32_bf16 v[80:83], v[180:183], v[206:209], v[80:83]
	v_mfma_f32_16x16x32_bf16 v[68:71], v[172:175], v[214:217], v[68:71]
	v_mfma_f32_16x16x32_bf16 v[64:67], v[180:183], v[214:217], v[64:67]
	v_mfma_f32_16x16x32_bf16 v[116:119], v[176:179], v[194:197], v[116:119]
	v_mfma_f32_16x16x32_bf16 v[112:115], v[186:189], v[194:197], v[112:115]
	v_mfma_f32_16x16x32_bf16 v[100:103], v[176:179], v[202:205], v[100:103]
	v_mfma_f32_16x16x32_bf16 v[96:99], v[186:189], v[202:205], v[96:99]
	v_mfma_f32_16x16x32_bf16 v[84:87], v[176:179], v[210:213], v[84:87]
	v_mfma_f32_16x16x32_bf16 v[80:83], v[186:189], v[210:213], v[80:83]
	v_mfma_f32_16x16x32_bf16 v[68:71], v[176:179], v[218:221], v[68:71]
	v_mfma_f32_16x16x32_bf16 v[64:67], v[186:189], v[218:221], v[64:67]
	s_setprio 0
	s_barrier
	s_add_i32 s30, s50, s36
	v_lshl_add_u64 v[158:159], v[158:159], 0, s[12:13]
	s_mov_b32 m0, s30
	ds_read_b128 v[190:193], v164 offset:49152
	ds_read_b128 v[194:197], v164 offset:50176
	ds_read_b128 v[198:201], v164 offset:51200
	ds_read_b128 v[202:205], v164 offset:52224
	ds_read_b128 v[206:209], v164 offset:53248
	ds_read_b128 v[210:213], v164 offset:54272
	ds_read_b128 v[214:217], v164 offset:55296
	ds_read_b128 v[218:221], v164 offset:56320
	global_load_lds_dwordx4 v[158:159], off
	s_add_i32 m0, s30, 0x2000
	s_add_u32 s28, s28, 0xb0080
	v_lshl_add_u64 v[158:159], v[222:223], 0, s[12:13]
	s_addc_u32 s29, s29, 0
	s_add_i32 s30, s51, s36
	global_load_lds_dwordx4 v[158:159], off
	v_lshl_add_u64 v[158:159], s[28:29], 0, v[130:131]
	s_mov_b32 m0, s30
	s_nop 0
	global_load_lds_dwordx4 v[158:159], off
	v_lshl_add_u64 v[158:159], s[28:29], 0, v[134:135]
	s_add_i32 m0, s30, 0x2000
	s_nop 0
	global_load_lds_dwordx4 v[158:159], off
	v_lshl_add_u64 v[158:159], v[224:225], 0, s[12:13]
	s_mov_b32 m0, s43
	s_nop 0
	global_load_lds_dwordx4 v[158:159], off
	v_lshl_add_u64 v[158:159], v[226:227], 0, s[12:13]
	s_mov_b32 m0, s44
	s_nop 0
	global_load_lds_dwordx4 v[158:159], off
	s_waitcnt vmcnt(8)
	s_waitcnt lgkmcnt(0)
	s_barrier
	s_setprio 1
	s_waitcnt lgkmcnt(0)
	v_mfma_f32_16x16x32_bf16 v[60:63], v[146:149], v[190:193], v[60:63]
	v_mfma_f32_16x16x32_bf16 v[56:59], v[154:157], v[190:193], v[56:59]
	v_mfma_f32_16x16x32_bf16 v[44:47], v[146:149], v[198:201], v[44:47]
	v_mfma_f32_16x16x32_bf16 v[40:43], v[154:157], v[198:201], v[40:43]
	v_mfma_f32_16x16x32_bf16 v[28:31], v[146:149], v[206:209], v[28:31]
	v_mfma_f32_16x16x32_bf16 v[24:27], v[154:157], v[206:209], v[24:27]
	v_mfma_f32_16x16x32_bf16 v[12:15], v[146:149], v[214:217], v[12:15]
	v_mfma_f32_16x16x32_bf16 v[8:11], v[154:157], v[214:217], v[8:11]
	v_mfma_f32_16x16x32_bf16 v[60:63], v[150:153], v[194:197], v[60:63]
	v_mfma_f32_16x16x32_bf16 v[56:59], v[168:171], v[194:197], v[56:59]
	v_mfma_f32_16x16x32_bf16 v[44:47], v[150:153], v[202:205], v[44:47]
	v_mfma_f32_16x16x32_bf16 v[40:43], v[168:171], v[202:205], v[40:43]
	v_mfma_f32_16x16x32_bf16 v[28:31], v[150:153], v[210:213], v[28:31]
	v_mfma_f32_16x16x32_bf16 v[24:27], v[168:171], v[210:213], v[24:27]
	v_mfma_f32_16x16x32_bf16 v[12:15], v[150:153], v[218:221], v[12:15]
	v_mfma_f32_16x16x32_bf16 v[8:11], v[168:171], v[218:221], v[8:11]
	s_setprio 0
	s_setprio 1
	v_mfma_f32_16x16x32_bf16 v[52:55], v[172:175], v[190:193], v[52:55]
	v_mfma_f32_16x16x32_bf16 v[48:51], v[180:183], v[190:193], v[48:51]
	v_mfma_f32_16x16x32_bf16 v[36:39], v[172:175], v[198:201], v[36:39]
	v_mfma_f32_16x16x32_bf16 v[32:35], v[180:183], v[198:201], v[32:35]
	v_mfma_f32_16x16x32_bf16 v[20:23], v[172:175], v[206:209], v[20:23]
	v_mfma_f32_16x16x32_bf16 v[16:19], v[180:183], v[206:209], v[16:19]
	v_mfma_f32_16x16x32_bf16 v[4:7], v[172:175], v[214:217], v[4:7]
	v_mfma_f32_16x16x32_bf16 v[0:3], v[180:183], v[214:217], v[0:3]
	v_mfma_f32_16x16x32_bf16 v[52:55], v[176:179], v[194:197], v[52:55]
	v_mfma_f32_16x16x32_bf16 v[48:51], v[186:189], v[194:197], v[48:51]
	v_mfma_f32_16x16x32_bf16 v[36:39], v[176:179], v[202:205], v[36:39]
	v_mfma_f32_16x16x32_bf16 v[32:35], v[186:189], v[202:205], v[32:35]
	v_mfma_f32_16x16x32_bf16 v[20:23], v[176:179], v[210:213], v[20:23]
	v_mfma_f32_16x16x32_bf16 v[16:19], v[186:189], v[210:213], v[16:19]
	v_mfma_f32_16x16x32_bf16 v[4:7], v[176:179], v[218:221], v[4:7]
	v_mfma_f32_16x16x32_bf16 v[0:3], v[186:189], v[218:221], v[0:3]
	s_setprio 0
	s_barrier
	s_add_i32 s57, s57, 2
	s_add_u32 s26, s26, 0x100
	s_addc_u32 s27, s27, 0
	s_add_u32 s55, s55, 0x100
	s_addc_u32 s56, s56, 0
	s_cmp_gt_u32 s57, 41
	s_cbranch_scc0 .LBB0_516
	s_and_b64 vcc, exec, s[14:15]
	s_cbranch_vccz .LBB0_519
	s_barrier

; #define PG8_STAGE(bufoff, gbase, voff) do { _Pragma("unroll") for (int _i = 0; _i < 2; ++_i) \
;         __builtin_amdgcn_global_load_lds((const unsigned*)((const char*)(gbase) + (voff)[_i]), (PG8_LAS unsigned*)(lds + (bufoff) + ldsw + _i * 8192), 16, 0, 0); } while (0)
; #define PG8_LDA(dst, b, h) do { _Pragma("unroll") for (int m = 0; m < 4; ++m) _Pragma("unroll") for (int k = 0; k < 2; ++k) dst[m][k] = *(const PG8_LAS bf16x8*)(lds + PG8_SA(b, h) + aoff + m * 2048 + k * 1024); } while (0)
; #define PG8_LDB(dst, b, h) do { _Pragma("unroll") for (int n = 0; n < 2; ++n) _Pragma("unroll") for (int k = 0; k < 2; ++k) dst[n][k] = *(const PG8_LAS bf16x8*)(lds + PG8_SB(b, h) + boff + n * 2048 + k * 1024); } while (0)
; #define PG8_MMA(ai, bj, At, Bt) do { __builtin_amdgcn_s_setprio(1); _Pragma("unroll") for (int m = 0; m < 4; ++m) _Pragma("unroll") for (int n = 0; n < 2; ++n) _Pragma("unroll") for (int k = 0; k < 2; ++k) \
;         acc[ai][bj][m][n] = __builtin_amdgcn_mfma_f32_16x16x32_bf16(Bt[n][k], At[m][k], acc[ai][bj][m][n], 0, 0, 0); __builtin_amdgcn_s_setprio(0); } while (0)
; #define PG8_WAIT_V(n) asm volatile("s_waitcnt vmcnt(" #n ")" ::: "memory")
; #define PG8_WAIT_L(n) asm volatile("s_waitcnt lgkmcnt(" #n ")" ::: "memory")
; #define PG8_BAR __builtin_amdgcn_s_barrier()
; #define PG8_SCHED __builtin_amdgcn_sched_barrier(0)
; template <class Epi, class Sched, bool ALIGN_EPI = false, bool SP2 = false>
; __device__ __forceinline__ void gemm_phase(PG8_LAS unsigned char* lds, const Gemm g, const Sched& S, const Epi& E) {
;     ...
;             PG8_LDB(B0, 0, 0); PG8_LDB(B1, 0, 1); PG8_SCHED; PG8_LDA(At, 0, 0); PG8_STAGE(PG8_SA(1, 1), a1 + hstep, voffA);
;             PG8_WAIT_V(8); PG8_WAIT_L(0); PG8_BAR; PG8_MMA(0, 0, At, B0); PG8_MMA(0, 1, At, B1); PG8_BAR; PG8_SCHED;
;     ...
; #pragma unroll
;         for (int a = 0; a < 2; ++a)
; #pragma unroll
;             for (int b = 0; b < 2; ++b)
; #pragma unroll
;                 for (int m = 0; m < 4; ++m)
; #pragma unroll
;                     for (int n = 0; n < 2; ++n) acc[a][b][m][n] = (f32x4){0.f, 0.f, 0.f, 0.f};
;         cur = nxt; cA = nA; cB = nB; ++ui;
.LBB0_646:
	s_ashr_i32 s19, s18, 31
	s_lshl_b64 s[20:21], s[18:19], 19
	v_readlane_b32 s22, v240, 5
	v_readlane_b32 s23, v240, 6
	s_add_u32 s20, s22, s20
	s_addc_u32 s21, s23, s21
	s_and_b64 s[22:23], s[6:7], exec
	s_cselect_b32 s19, s21, s29
	s_cselect_b32 s25, s20, s28
	s_ashr_i32 s15, s14, 31
	s_lshl_b64 s[22:23], s[14:15], 19
	s_add_u32 s22, s2, s22
	s_addc_u32 s23, s36, s23
	s_and_b64 s[34:35], s[6:7], exec
	s_cselect_b32 s15, s23, s31
	s_cselect_b32 s27, s22, s30
	s_add_u32 s28, s28, 0x40080
	s_addc_u32 s29, s29, 0
	s_add_u32 s53, s30, 0x100
	v_mov_b32_e32 v0, 0
	s_addc_u32 s54, s31, 0
	s_mov_b32 s55, -2
	v_mov_b32_e32 v1, 0
	v_mov_b64_e32 v[2:3], 0
	v_mov_b64_e32 v[4:5], 0
	v_mov_b64_e32 v[6:7], 0
	v_mov_b64_e32 v[8:9], 0
	v_mov_b64_e32 v[10:11], 0
	v_mov_b64_e32 v[12:13], 0
	v_mov_b64_e32 v[14:15], 0
	v_mov_b64_e32 v[16:17], 0
	v_mov_b64_e32 v[18:19], 0
	v_mov_b64_e32 v[20:21], 0
	v_mov_b64_e32 v[22:23], 0
	v_mov_b64_e32 v[24:25], 0
	v_mov_b64_e32 v[26:27], 0
	v_mov_b64_e32 v[28:29], 0
	v_mov_b64_e32 v[30:31], 0
	v_mov_b64_e32 v[32:33], 0
	v_mov_b64_e32 v[34:35], 0
	v_mov_b64_e32 v[36:37], 0
	v_mov_b64_e32 v[38:39], 0
	v_mov_b64_e32 v[40:41], 0
	v_mov_b64_e32 v[42:43], 0
	v_mov_b64_e32 v[44:45], 0
	v_mov_b64_e32 v[46:47], 0
	v_mov_b64_e32 v[48:49], 0
	v_mov_b64_e32 v[50:51], 0
	v_mov_b64_e32 v[52:53], 0
	v_mov_b64_e32 v[54:55], 0
	v_mov_b64_e32 v[56:57], 0
	v_mov_b64_e32 v[58:59], 0
	v_mov_b64_e32 v[60:61], 0
	v_mov_b64_e32 v[62:63], 0
	v_mov_b64_e32 v[64:65], 0
	v_mov_b64_e32 v[66:67], 0
	v_mov_b64_e32 v[68:69], 0
	v_mov_b64_e32 v[70:71], 0
	v_mov_b64_e32 v[72:73], 0
	v_mov_b64_e32 v[74:75], 0
	v_mov_b64_e32 v[76:77], 0
	v_mov_b64_e32 v[78:79], 0
	v_mov_b64_e32 v[80:81], 0
	v_mov_b64_e32 v[82:83], 0
	v_mov_b64_e32 v[84:85], 0
	v_mov_b64_e32 v[86:87], 0
	v_mov_b64_e32 v[88:89], 0
	v_mov_b64_e32 v[90:91], 0
	v_mov_b64_e32 v[92:93], 0
	v_mov_b64_e32 v[94:95], 0
	v_mov_b64_e32 v[96:97], 0
	v_mov_b64_e32 v[98:99], 0
	v_mov_b64_e32 v[100:101], 0
	v_mov_b64_e32 v[102:103], 0
	v_mov_b64_e32 v[104:105], 0
	v_mov_b64_e32 v[106:107], 0
	v_mov_b64_e32 v[108:109], 0
	v_mov_b64_e32 v[110:111], 0
	v_mov_b64_e32 v[112:113], 0
	v_mov_b64_e32 v[114:115], 0
	v_mov_b64_e32 v[116:117], 0
	v_mov_b64_e32 v[118:119], 0
	v_mov_b64_e32 v[120:121], 0
	v_mov_b64_e32 v[122:123], 0
	v_mov_b64_e32 v[124:125], 0
	v_mov_b64_e32 v[126:127], 0
	s_branch .Lz64_2
	s_nop 0
	s_nop 0
	s_nop 0
	s_nop 0
	s_nop 0
	s_nop 0
	s_nop 0
	s_nop 0
	s_nop 0
	s_nop 0
	s_nop 0
	s_nop 0
	s_nop 0
	s_nop 0
	s_nop 0
	s_nop 0
	s_nop 0
	s_nop 0
	s_nop 0
	s_nop 0
	s_nop 0
	s_nop 0
	s_nop 0
	s_nop 0
	s_nop 0
	s_nop 0
	s_nop 0
	s_nop 0
	s_nop 0
	s_nop 0
	s_nop 0
	s_nop 0
	s_nop 0
	s_nop 0
	s_nop 0
	s_nop 0
	s_nop 0
	s_nop 0
	s_nop 0
	s_nop 0
	s_nop 0
	s_nop 0
	s_nop 0
	s_nop 0
	s_nop 0
	s_nop 0
	s_nop 0
	s_nop 0
	s_nop 0
	s_nop 0
	s_nop 0
	s_nop 0
	s_nop 0
	s_nop 0
	s_nop 0
	s_nop 0
	s_nop 0
	s_nop 0
	s_nop 0
	s_nop 0
	s_nop 0
	s_nop 0
.Lz64_2:
.LBB0_647:
	ds_read_b128 v[148:151], v154
	ds_read_b128 v[160:163], v154 offset:1024
	ds_read_b128 v[164:167], v154 offset:2048
	ds_read_b128 v[168:171], v154 offset:3072
	ds_read_b128 v[172:175], v155
	ds_read_b128 v[176:179], v155 offset:1024
	ds_read_b128 v[180:183], v155 offset:2048
	ds_read_b128 v[186:189], v155 offset:3072
	s_add_u32 s30, s28, 0xfffc0080
	s_addc_u32 s31, s29, -1
	s_cmp_eq_u32 s55, 12
	s_cselect_b32 s35, s19, s31
	s_cselect_b32 s34, s25, s30
	s_cselect_b32 s31, s15, s54
	s_cselect_b32 s30, s27, s53
	v_lshl_add_u64 v[222:223], s[28:29], 0, v[138:139]
	s_add_i32 m0, s38, 0xc000
	ds_read_b128 v[190:193], v156
	ds_read_b128 v[194:197], v156 offset:1024
	ds_read_b128 v[198:201], v156 offset:2048
	ds_read_b128 v[202:205], v156 offset:3072
	ds_read_b128 v[206:209], v156 offset:4096
	ds_read_b128 v[210:213], v156 offset:5120
	ds_read_b128 v[214:217], v156 offset:6144
	ds_read_b128 v[218:221], v156 offset:7168
	global_load_lds_dwordx4 v[222:223], off
	v_lshl_add_u64 v[222:223], s[28:29], 0, v[140:141]
	s_add_i32 m0, s38, 0xe000
	s_nop 0
	global_load_lds_dwordx4 v[222:223], off
	s_waitcnt vmcnt(8)
	s_waitcnt lgkmcnt(0)
	s_barrier
	s_setprio 1
	s_waitcnt lgkmcnt(0)
	v_mfma_f32_16x16x32_bf16 v[124:127], v[148:151], v[190:193], v[124:127]
	v_mfma_f32_16x16x32_bf16 v[120:123], v[164:167], v[190:193], v[120:123]
	v_mfma_f32_16x16x32_bf16 v[116:119], v[148:151], v[198:201], v[116:119]
	v_mfma_f32_16x16x32_bf16 v[112:115], v[164:167], v[198:201], v[112:115]
	v_mfma_f32_16x16x32_bf16 v[100:103], v[148:151], v[206:209], v[100:103]
	v_mfma_f32_16x16x32_bf16 v[96:99], v[164:167], v[206:209], v[96:99]
	v_mfma_f32_16x16x32_bf16 v[84:87], v[148:151], v[214:217], v[84:87]
	v_mfma_f32_16x16x32_bf16 v[80:83], v[164:167], v[214:217], v[80:83]
	v_mfma_f32_16x16x32_bf16 v[124:127], v[160:163], v[194:197], v[124:127]
	v_mfma_f32_16x16x32_bf16 v[120:123], v[168:171], v[194:197], v[120:123]
	v_mfma_f32_16x16x32_bf16 v[116:119], v[160:163], v[202:205], v[116:119]
	v_mfma_f32_16x16x32_bf16 v[112:115], v[168:171], v[202:205], v[112:115]
	v_mfma_f32_16x16x32_bf16 v[100:103], v[160:163], v[210:213], v[100:103]
	v_mfma_f32_16x16x32_bf16 v[96:99], v[168:171], v[210:213], v[96:99]
	v_mfma_f32_16x16x32_bf16 v[84:87], v[160:163], v[218:221], v[84:87]
	v_mfma_f32_16x16x32_bf16 v[80:83], v[168:171], v[218:221], v[80:83]
	s_setprio 0
	s_setprio 1
	v_mfma_f32_16x16x32_bf16 v[108:111], v[172:175], v[190:193], v[108:111]
	v_mfma_f32_16x16x32_bf16 v[104:107], v[180:183], v[190:193], v[104:107]
	v_mfma_f32_16x16x32_bf16 v[92:95], v[172:175], v[198:201], v[92:95]
	v_mfma_f32_16x16x32_bf16 v[88:91], v[180:183], v[198:201], v[88:91]
	v_mfma_f32_16x16x32_bf16 v[76:79], v[172:175], v[206:209], v[76:79]
	v_mfma_f32_16x16x32_bf16 v[72:75], v[180:183], v[206:209], v[72:75]
	v_mfma_f32_16x16x32_bf16 v[68:71], v[172:175], v[214:217], v[68:71]
	v_mfma_f32_16x16x32_bf16 v[64:67], v[180:183], v[214:217], v[64:67]
	v_mfma_f32_16x16x32_bf16 v[108:111], v[176:179], v[194:197], v[108:111]
	v_mfma_f32_16x16x32_bf16 v[104:107], v[186:189], v[194:197], v[104:107]
	v_mfma_f32_16x16x32_bf16 v[92:95], v[176:179], v[202:205], v[92:95]
	v_mfma_f32_16x16x32_bf16 v[88:91], v[186:189], v[202:205], v[88:91]
	v_mfma_f32_16x16x32_bf16 v[76:79], v[176:179], v[210:213], v[76:79]
	v_mfma_f32_16x16x32_bf16 v[72:75], v[186:189], v[210:213], v[72:75]
	v_mfma_f32_16x16x32_bf16 v[68:71], v[176:179], v[218:221], v[68:71]
	v_mfma_f32_16x16x32_bf16 v[64:67], v[186:189], v[218:221], v[64:67]
	s_setprio 0
	s_barrier
; #define PG8_STAGE(bufoff, gbase, voff) do { _Pragma("unroll") for (int _i = 0; _i < 2; ++_i) \
;         __builtin_amdgcn_global_load_lds((const unsigned*)((const char*)(gbase) + (voff)[_i]), (PG8_LAS unsigned*)(lds + (bufoff) + ldsw + _i * 8192), 16, 0, 0); } while (0)
; #define PG8_LDA(dst, b, h) do { _Pragma("unroll") for (int m = 0; m < 4; ++m) _Pragma("unroll") for (int k = 0; k < 2; ++k) dst[m][k] = *(const PG8_LAS bf16x8*)(lds + PG8_SA(b, h) + aoff + m * 2048 + k * 1024); } while (0)
; #define PG8_LDB(dst, b, h) do { _Pragma("unroll") for (int n = 0; n < 2; ++n) _Pragma("unroll") for (int k = 0; k < 2; ++k) dst[n][k] = *(const PG8_LAS bf16x8*)(lds + PG8_SB(b, h) + boff + n * 2048 + k * 1024); } while (0)
; #define PG8_MMA(ai, bj, At, Bt) do { __builtin_amdgcn_s_setprio(1); _Pragma("unroll") for (int m = 0; m < 4; ++m) _Pragma("unroll") for (int n = 0; n < 2; ++n) _Pragma("unroll") for (int k = 0; k < 2; ++k) \
;         acc[ai][bj][m][n] = __builtin_amdgcn_mfma_f32_16x16x32_bf16(Bt[n][k], At[m][k], acc[ai][bj][m][n], 0, 0, 0); __builtin_amdgcn_s_setprio(0); } while (0)
; #define PG8_WAIT_V(n) asm volatile("s_waitcnt vmcnt(" #n ")" ::: "memory")
; #define PG8_WAIT_L(n) asm volatile("s_waitcnt lgkmcnt(" #n ")" ::: "memory")
; #define PG8_BAR __builtin_amdgcn_s_barrier()
; #define PG8_SCHED __builtin_amdgcn_sched_barrier(0)
; template <class Epi, class Sched, bool ALIGN_EPI = false, bool SP2 = false>
; __device__ __forceinline__ void gemm_phase(PG8_LAS unsigned char* lds, const Gemm g, const Sched& S, const Epi& E) {
;     ...
;             PG8_LDA(At, 0, 1); PG8_STAGE(PG8_SB(0, 0), b2, voffB); PG8_STAGE(PG8_SB(0, 1), b2 + hstep, voffB); PG8_STAGE(PG8_SA(0, 0), a2, voffA);
;             PG8_WAIT_V(8); PG8_WAIT_L(0); PG8_BAR; PG8_MMA(1, 0, At, B0); PG8_MMA(1, 1, At, B1); PG8_BAR; PG8_SCHED;
;             PG8_LDB(B0, 1, 0); PG8_LDB(B1, 1, 1); PG8_SCHED; PG8_LDA(At, 1, 0); PG8_STAGE(PG8_SA(0, 1), a2 + hstep, voffA);
	s_add_i32 s56, s48, s37
	v_lshl_add_u64 v[222:223], s[30:31], 0, v[130:131]
	s_mov_b32 m0, s56
	ds_read_b128 v[190:193], v156 offset:16384
	ds_read_b128 v[194:197], v156 offset:17408
	ds_read_b128 v[198:201], v156 offset:18432
	ds_read_b128 v[202:205], v156 offset:19456
	ds_read_b128 v[206:209], v156 offset:20480
	ds_read_b128 v[210:213], v156 offset:21504
	ds_read_b128 v[214:217], v156 offset:22528
	ds_read_b128 v[218:221], v156 offset:23552
	global_load_lds_dwordx4 v[222:223], off
	s_add_i32 m0, s56, 0x2000
	s_add_u32 s56, s30, 0x40000
	v_lshl_add_u64 v[224:225], s[30:31], 0, v[134:135]
	s_addc_u32 s57, s31, 0
	s_add_i32 s58, s49, s37
	global_load_lds_dwordx4 v[224:225], off
	v_lshl_add_u64 v[226:227], s[56:57], 0, v[130:131]
	s_mov_b32 m0, s58
	v_lshl_add_u64 v[228:229], s[34:35], 0, v[132:133]
	global_load_lds_dwordx4 v[226:227], off
	v_lshl_add_u64 v[226:227], s[56:57], 0, v[134:135]
	s_add_i32 m0, s58, 0x2000
	s_nop 0
	global_load_lds_dwordx4 v[226:227], off
	v_lshl_add_u64 v[226:227], s[34:35], 0, v[128:129]
	s_mov_b32 m0, s38
	s_nop 0
	global_load_lds_dwordx4 v[226:227], off
	s_mov_b32 m0, s39
	s_nop 0
	global_load_lds_dwordx4 v[228:229], off
	s_waitcnt vmcnt(8)
	s_waitcnt lgkmcnt(0)
	s_barrier
	s_setprio 1
	s_waitcnt lgkmcnt(0)
	v_mfma_f32_16x16x32_bf16 v[60:63], v[148:151], v[190:193], v[60:63]
	v_mfma_f32_16x16x32_bf16 v[56:59], v[164:167], v[190:193], v[56:59]
	v_mfma_f32_16x16x32_bf16 v[52:55], v[148:151], v[198:201], v[52:55]
	v_mfma_f32_16x16x32_bf16 v[48:51], v[164:167], v[198:201], v[48:51]
	v_mfma_f32_16x16x32_bf16 v[36:39], v[148:151], v[206:209], v[36:39]
	v_mfma_f32_16x16x32_bf16 v[32:35], v[164:167], v[206:209], v[32:35]
	v_mfma_f32_16x16x32_bf16 v[20:23], v[148:151], v[214:217], v[20:23]
	v_mfma_f32_16x16x32_bf16 v[16:19], v[164:167], v[214:217], v[16:19]
	v_mfma_f32_16x16x32_bf16 v[60:63], v[160:163], v[194:197], v[60:63]
	v_mfma_f32_16x16x32_bf16 v[56:59], v[168:171], v[194:197], v[56:59]
	v_mfma_f32_16x16x32_bf16 v[52:55], v[160:163], v[202:205], v[52:55]
	v_mfma_f32_16x16x32_bf16 v[48:51], v[168:171], v[202:205], v[48:51]
	v_mfma_f32_16x16x32_bf16 v[36:39], v[160:163], v[210:213], v[36:39]
	v_mfma_f32_16x16x32_bf16 v[32:35], v[168:171], v[210:213], v[32:35]
	v_mfma_f32_16x16x32_bf16 v[20:23], v[160:163], v[218:221], v[20:23]
	v_mfma_f32_16x16x32_bf16 v[16:19], v[168:171], v[218:221], v[16:19]
	s_setprio 0
	s_setprio 1
	v_mfma_f32_16x16x32_bf16 v[44:47], v[172:175], v[190:193], v[44:47]
	v_mfma_f32_16x16x32_bf16 v[40:43], v[180:183], v[190:193], v[40:43]
	v_mfma_f32_16x16x32_bf16 v[28:31], v[172:175], v[198:201], v[28:31]
	v_mfma_f32_16x16x32_bf16 v[24:27], v[180:183], v[198:201], v[24:27]
	v_mfma_f32_16x16x32_bf16 v[12:15], v[172:175], v[206:209], v[12:15]
	v_mfma_f32_16x16x32_bf16 v[8:11], v[180:183], v[206:209], v[8:11]
	v_mfma_f32_16x16x32_bf16 v[4:7], v[172:175], v[214:217], v[4:7]
	v_mfma_f32_16x16x32_bf16 v[0:3], v[180:183], v[214:217], v[0:3]
	v_mfma_f32_16x16x32_bf16 v[44:47], v[176:179], v[194:197], v[44:47]
	v_mfma_f32_16x16x32_bf16 v[40:43], v[186:189], v[194:197], v[40:43]
	v_mfma_f32_16x16x32_bf16 v[28:31], v[176:179], v[202:205], v[28:31]
	v_mfma_f32_16x16x32_bf16 v[24:27], v[186:189], v[202:205], v[24:27]
	v_mfma_f32_16x16x32_bf16 v[12:15], v[176:179], v[210:213], v[12:15]
	v_mfma_f32_16x16x32_bf16 v[8:11], v[186:189], v[210:213], v[8:11]
	v_mfma_f32_16x16x32_bf16 v[4:7], v[176:179], v[218:221], v[4:7]
	v_mfma_f32_16x16x32_bf16 v[0:3], v[186:189], v[218:221], v[0:3]
	s_setprio 0
	s_barrier
	ds_read_b128 v[148:151], v157
	ds_read_b128 v[160:163], v157 offset:1024
	ds_read_b128 v[164:167], v157 offset:2048
	ds_read_b128 v[168:171], v157 offset:3072
	ds_read_b128 v[172:175], v158
	ds_read_b128 v[176:179], v158 offset:1024
	ds_read_b128 v[180:183], v158 offset:2048
	ds_read_b128 v[186:189], v158 offset:3072
	s_add_u32 s34, s34, 0x40000
	s_addc_u32 s35, s35, 0
	s_mov_b32 m0, s33
	v_lshl_add_u64 v[230:231], s[34:35], 0, v[128:129]
	ds_read_b128 v[190:193], v156 offset:32768
	ds_read_b128 v[194:197], v156 offset:33792
	ds_read_b128 v[198:201], v156 offset:34816
	ds_read_b128 v[202:205], v156 offset:35840
	ds_read_b128 v[206:209], v156 offset:36864
	ds_read_b128 v[210:213], v156 offset:37888
	ds_read_b128 v[214:217], v156 offset:38912
	ds_read_b128 v[218:221], v156 offset:39936
	global_load_lds_dwordx4 v[230:231], off
	v_lshl_add_u64 v[230:231], s[34:35], 0, v[132:133]
	s_mov_b32 m0, s40
	s_nop 0
	global_load_lds_dwordx4 v[230:231], off
	s_waitcnt vmcnt(8)
	s_waitcnt lgkmcnt(0)
	s_barrier
; #define PG8_STAGE(bufoff, gbase, voff) do { _Pragma("unroll") for (int _i = 0; _i < 2; ++_i) \
;         __builtin_amdgcn_global_load_lds((const unsigned*)((const char*)(gbase) + (voff)[_i]), (PG8_LAS unsigned*)(lds + (bufoff) + ldsw + _i * 8192), 16, 0, 0); } while (0)
; #define PG8_LDA(dst, b, h) do { _Pragma("unroll") for (int m = 0; m < 4; ++m) _Pragma("unroll") for (int k = 0; k < 2; ++k) dst[m][k] = *(const PG8_LAS bf16x8*)(lds + PG8_SA(b, h) + aoff + m * 2048 + k * 1024); } while (0)
; #define PG8_MMA(ai, bj, At, Bt) do { __builtin_amdgcn_s_setprio(1); _Pragma("unroll") for (int m = 0; m < 4; ++m) _Pragma("unroll") for (int n = 0; n < 2; ++n) _Pragma("unroll") for (int k = 0; k < 2; ++k) \
;         acc[ai][bj][m][n] = __builtin_amdgcn_mfma_f32_16x16x32_bf16(Bt[n][k], At[m][k], acc[ai][bj][m][n], 0, 0, 0); __builtin_amdgcn_s_setprio(0); } while (0)
; #define PG8_WAIT_V(n) asm volatile("s_waitcnt vmcnt(" #n ")" ::: "memory")
; #define PG8_WAIT_L(n) asm volatile("s_waitcnt lgkmcnt(" #n ")" ::: "memory")
; #define PG8_BAR __builtin_amdgcn_s_barrier()
; #define PG8_SCHED __builtin_amdgcn_sched_barrier(0)
; template <class Epi, class Sched, bool ALIGN_EPI = false, bool SP2 = false>
; __device__ __forceinline__ void gemm_phase(PG8_LAS unsigned char* lds, const Gemm g, const Sched& S, const Epi& E) {
;     ...
;             PG8_WAIT_V(8); PG8_WAIT_L(0); PG8_BAR; PG8_MMA(0, 0, At, B0); PG8_MMA(0, 1, At, B1); PG8_BAR; PG8_SCHED;
;             PG8_LDA(At, 1, 1); PG8_STAGE(PG8_SB(1, 0), b3, voffB); PG8_STAGE(PG8_SB(1, 1), b3 + hstep, voffB); PG8_STAGE(PG8_SA(1, 0), a3, voffA);
;             PG8_WAIT_V(8); PG8_WAIT_L(0); PG8_BAR; PG8_MMA(1, 0, At, B0); PG8_MMA(1, 1, At, B1); PG8_BAR; PG8_SCHED;
;     ...
;         if constexpr (ALIGN_EPI) { if (wr == 0) PG8_BAR; }
	s_setprio 1
	s_waitcnt lgkmcnt(0)
	v_mfma_f32_16x16x32_bf16 v[124:127], v[148:151], v[190:193], v[124:127]
	v_mfma_f32_16x16x32_bf16 v[120:123], v[164:167], v[190:193], v[120:123]
	v_mfma_f32_16x16x32_bf16 v[116:119], v[148:151], v[198:201], v[116:119]
	v_mfma_f32_16x16x32_bf16 v[112:115], v[164:167], v[198:201], v[112:115]
	v_mfma_f32_16x16x32_bf16 v[100:103], v[148:151], v[206:209], v[100:103]
	v_mfma_f32_16x16x32_bf16 v[96:99], v[164:167], v[206:209], v[96:99]
	v_mfma_f32_16x16x32_bf16 v[84:87], v[148:151], v[214:217], v[84:87]
	v_mfma_f32_16x16x32_bf16 v[80:83], v[164:167], v[214:217], v[80:83]
	v_mfma_f32_16x16x32_bf16 v[124:127], v[160:163], v[194:197], v[124:127]
	v_mfma_f32_16x16x32_bf16 v[120:123], v[168:171], v[194:197], v[120:123]
	v_mfma_f32_16x16x32_bf16 v[116:119], v[160:163], v[202:205], v[116:119]
	v_mfma_f32_16x16x32_bf16 v[112:115], v[168:171], v[202:205], v[112:115]
	v_mfma_f32_16x16x32_bf16 v[100:103], v[160:163], v[210:213], v[100:103]
	v_mfma_f32_16x16x32_bf16 v[96:99], v[168:171], v[210:213], v[96:99]
	v_mfma_f32_16x16x32_bf16 v[84:87], v[160:163], v[218:221], v[84:87]
	v_mfma_f32_16x16x32_bf16 v[80:83], v[168:171], v[218:221], v[80:83]
	s_setprio 0
	s_setprio 1
	v_mfma_f32_16x16x32_bf16 v[108:111], v[172:175], v[190:193], v[108:111]
	v_mfma_f32_16x16x32_bf16 v[104:107], v[180:183], v[190:193], v[104:107]
	v_mfma_f32_16x16x32_bf16 v[92:95], v[172:175], v[198:201], v[92:95]
	v_mfma_f32_16x16x32_bf16 v[88:91], v[180:183], v[198:201], v[88:91]
	v_mfma_f32_16x16x32_bf16 v[76:79], v[172:175], v[206:209], v[76:79]
	v_mfma_f32_16x16x32_bf16 v[72:75], v[180:183], v[206:209], v[72:75]
	v_mfma_f32_16x16x32_bf16 v[68:71], v[172:175], v[214:217], v[68:71]
	v_mfma_f32_16x16x32_bf16 v[64:67], v[180:183], v[214:217], v[64:67]
	v_mfma_f32_16x16x32_bf16 v[108:111], v[176:179], v[194:197], v[108:111]
	v_mfma_f32_16x16x32_bf16 v[104:107], v[186:189], v[194:197], v[104:107]
	v_mfma_f32_16x16x32_bf16 v[92:95], v[176:179], v[202:205], v[92:95]
	v_mfma_f32_16x16x32_bf16 v[88:91], v[186:189], v[202:205], v[88:91]
	v_mfma_f32_16x16x32_bf16 v[76:79], v[176:179], v[210:213], v[76:79]
	v_mfma_f32_16x16x32_bf16 v[72:75], v[186:189], v[210:213], v[72:75]
	v_mfma_f32_16x16x32_bf16 v[68:71], v[176:179], v[218:221], v[68:71]
	v_mfma_f32_16x16x32_bf16 v[64:67], v[186:189], v[218:221], v[64:67]
	s_setprio 0
	s_barrier
	s_add_i32 s34, s51, s37
	v_lshl_add_u64 v[222:223], v[222:223], 0, s[8:9]
	s_mov_b32 m0, s34
	ds_read_b128 v[190:193], v156 offset:49152
	ds_read_b128 v[194:197], v156 offset:50176
	ds_read_b128 v[198:201], v156 offset:51200
	ds_read_b128 v[202:205], v156 offset:52224
	ds_read_b128 v[206:209], v156 offset:53248
	ds_read_b128 v[210:213], v156 offset:54272
	ds_read_b128 v[214:217], v156 offset:55296
	ds_read_b128 v[218:221], v156 offset:56320
	global_load_lds_dwordx4 v[222:223], off
	s_add_i32 m0, s34, 0x2000
	s_add_u32 s30, s30, 0x40080
	v_lshl_add_u64 v[222:223], v[224:225], 0, s[8:9]
	s_addc_u32 s31, s31, 0
	s_add_i32 s34, s52, s37
	global_load_lds_dwordx4 v[222:223], off
	v_lshl_add_u64 v[222:223], s[30:31], 0, v[130:131]
	s_mov_b32 m0, s34
	s_nop 0
	global_load_lds_dwordx4 v[222:223], off
	v_lshl_add_u64 v[222:223], s[30:31], 0, v[134:135]
	s_add_i32 m0, s34, 0x2000
	s_nop 0
	global_load_lds_dwordx4 v[222:223], off
	v_lshl_add_u64 v[222:223], v[226:227], 0, s[8:9]
	s_mov_b32 m0, s41
	s_nop 0
	global_load_lds_dwordx4 v[222:223], off
	v_lshl_add_u64 v[222:223], v[228:229], 0, s[8:9]
	s_mov_b32 m0, s42
	s_nop 0
	global_load_lds_dwordx4 v[222:223], off
	s_waitcnt vmcnt(8)
	s_waitcnt lgkmcnt(0)
	s_barrier
	s_setprio 1
	s_waitcnt lgkmcnt(0)
	v_mfma_f32_16x16x32_bf16 v[60:63], v[148:151], v[190:193], v[60:63]
	v_mfma_f32_16x16x32_bf16 v[56:59], v[164:167], v[190:193], v[56:59]
	v_mfma_f32_16x16x32_bf16 v[52:55], v[148:151], v[198:201], v[52:55]
	v_mfma_f32_16x16x32_bf16 v[48:51], v[164:167], v[198:201], v[48:51]
	v_mfma_f32_16x16x32_bf16 v[36:39], v[148:151], v[206:209], v[36:39]
	v_mfma_f32_16x16x32_bf16 v[32:35], v[164:167], v[206:209], v[32:35]
	v_mfma_f32_16x16x32_bf16 v[20:23], v[148:151], v[214:217], v[20:23]
	v_mfma_f32_16x16x32_bf16 v[16:19], v[164:167], v[214:217], v[16:19]
	v_mfma_f32_16x16x32_bf16 v[60:63], v[160:163], v[194:197], v[60:63]
	v_mfma_f32_16x16x32_bf16 v[56:59], v[168:171], v[194:197], v[56:59]
	v_mfma_f32_16x16x32_bf16 v[52:55], v[160:163], v[202:205], v[52:55]
	v_mfma_f32_16x16x32_bf16 v[48:51], v[168:171], v[202:205], v[48:51]
	v_mfma_f32_16x16x32_bf16 v[36:39], v[160:163], v[210:213], v[36:39]
	v_mfma_f32_16x16x32_bf16 v[32:35], v[168:171], v[210:213], v[32:35]
	v_mfma_f32_16x16x32_bf16 v[20:23], v[160:163], v[218:221], v[20:23]
	v_mfma_f32_16x16x32_bf16 v[16:19], v[168:171], v[218:221], v[16:19]
	s_setprio 0
	s_setprio 1
	v_mfma_f32_16x16x32_bf16 v[44:47], v[172:175], v[190:193], v[44:47]
	v_mfma_f32_16x16x32_bf16 v[40:43], v[180:183], v[190:193], v[40:43]
	v_mfma_f32_16x16x32_bf16 v[28:31], v[172:175], v[198:201], v[28:31]
	v_mfma_f32_16x16x32_bf16 v[24:27], v[180:183], v[198:201], v[24:27]
	v_mfma_f32_16x16x32_bf16 v[12:15], v[172:175], v[206:209], v[12:15]
	v_mfma_f32_16x16x32_bf16 v[8:11], v[180:183], v[206:209], v[8:11]
	v_mfma_f32_16x16x32_bf16 v[4:7], v[172:175], v[214:217], v[4:7]
	v_mfma_f32_16x16x32_bf16 v[0:3], v[180:183], v[214:217], v[0:3]
	v_mfma_f32_16x16x32_bf16 v[44:47], v[176:179], v[194:197], v[44:47]
	v_mfma_f32_16x16x32_bf16 v[40:43], v[186:189], v[194:197], v[40:43]
	v_mfma_f32_16x16x32_bf16 v[28:31], v[176:179], v[202:205], v[28:31]
	v_mfma_f32_16x16x32_bf16 v[24:27], v[186:189], v[202:205], v[24:27]
	v_mfma_f32_16x16x32_bf16 v[12:15], v[176:179], v[210:213], v[12:15]
	v_mfma_f32_16x16x32_bf16 v[8:11], v[186:189], v[210:213], v[8:11]
	v_mfma_f32_16x16x32_bf16 v[4:7], v[176:179], v[218:221], v[4:7]
	v_mfma_f32_16x16x32_bf16 v[0:3], v[186:189], v[218:221], v[0:3]
	s_setprio 0
	s_barrier
	s_add_i32 s55, s55, 2
	s_add_u32 s28, s28, 0x100
	s_addc_u32 s29, s29, 0
	s_add_u32 s53, s53, 0x100
	s_addc_u32 s54, s54, 0
	s_cmp_gt_u32 s55, 13
	s_cbranch_scc0 .LBB0_647
	s_and_b64 vcc, exec, s[10:11]
	s_cbranch_vccz .LBB0_650
	s_barrier

; #define PG8_STAGE(bufoff, gbase, voff) do { _Pragma("unroll") for (int _i = 0; _i < 2; ++_i) \
;         __builtin_amdgcn_global_load_lds((const unsigned*)((const char*)(gbase) + (voff)[_i]), (PG8_LAS unsigned*)(lds + (bufoff) + ldsw + _i * 8192), 16, 0, 0); } while (0)
; #define PG8_LDA(dst, b, h) do { _Pragma("unroll") for (int m = 0; m < 4; ++m) _Pragma("unroll") for (int k = 0; k < 2; ++k) dst[m][k] = *(const PG8_LAS bf16x8*)(lds + PG8_SA(b, h) + aoff + m * 2048 + k * 1024); } while (0)
; #define PG8_LDB(dst, b, h) do { _Pragma("unroll") for (int n = 0; n < 2; ++n) _Pragma("unroll") for (int k = 0; k < 2; ++k) dst[n][k] = *(const PG8_LAS bf16x8*)(lds + PG8_SB(b, h) + boff + n * 2048 + k * 1024); } while (0)
; #define PG8_MMA(ai, bj, At, Bt) do { __builtin_amdgcn_s_setprio(1); _Pragma("unroll") for (int m = 0; m < 4; ++m) _Pragma("unroll") for (int n = 0; n < 2; ++n) _Pragma("unroll") for (int k = 0; k < 2; ++k) \
;         acc[ai][bj][m][n] = __builtin_amdgcn_mfma_f32_16x16x32_bf16(Bt[n][k], At[m][k], acc[ai][bj][m][n], 0, 0, 0); __builtin_amdgcn_s_setprio(0); } while (0)
; #define PG8_WAIT_V(n) asm volatile("s_waitcnt vmcnt(" #n ")" ::: "memory")
; #define PG8_WAIT_L(n) asm volatile("s_waitcnt lgkmcnt(" #n ")" ::: "memory")
; #define PG8_BAR __builtin_amdgcn_s_barrier()
; #define PG8_SCHED __builtin_amdgcn_sched_barrier(0)
; template <class Epi, class Sched, bool ALIGN_EPI = false, bool SP2 = false>
; __device__ __forceinline__ void gemm_phase(PG8_LAS unsigned char* lds, const Gemm g, const Sched& S, const Epi& E) {
;     ...
;             PG8_LDB(B0, 0, 0); PG8_LDB(B1, 0, 1); PG8_SCHED; PG8_LDA(At, 0, 0); PG8_STAGE(PG8_SA(1, 1), a1 + hstep, voffA);
;             PG8_WAIT_V(8); PG8_WAIT_L(0); PG8_BAR; PG8_MMA(0, 0, At, B0); PG8_MMA(0, 1, At, B1); PG8_BAR; PG8_SCHED;
;     ...
; #pragma unroll
;         for (int a = 0; a < 2; ++a)
; #pragma unroll
;             for (int b = 0; b < 2; ++b)
; #pragma unroll
;                 for (int m = 0; m < 4; ++m)
; #pragma unroll
;                     for (int n = 0; n < 2; ++n) acc[a][b][m][n] = (f32x4){0.f, 0.f, 0.f, 0.f};
;         cur = nxt; cA = nA; cB = nB; ++ui;
.LBB0_1959:
	s_ashr_i32 s19, s18, 31
	s_lshl_b64 s[20:21], s[18:19], 18
	s_add_u32 s20, s6, s20
	s_addc_u32 s21, s7, s21
	s_and_b64 s[22:23], s[4:5], exec
	s_cselect_b32 s19, s21, s25
	s_cselect_b32 s33, s20, s24
	s_ashr_i32 s17, s16, 31
	s_lshl_b64 s[22:23], s[16:17], 18
	s_add_u32 s22, s31, s22
	s_addc_u32 s23, s34, s23
	s_and_b64 s[28:29], s[4:5], exec
	s_cselect_b32 s17, s23, s27
	s_cselect_b32 s50, s22, s26
	s_add_u32 s24, s24, 0x20080
	s_addc_u32 s25, s25, 0
	s_add_u32 s51, s26, 0x100
	v_mov_b32_e32 v0, 0
	s_addc_u32 s52, s27, 0
	s_mov_b32 s53, -2
	v_mov_b32_e32 v1, v0
	v_mov_b32_e32 v2, v0
	v_mov_b32_e32 v3, v0
	v_mov_b32_e32 v4, v0
	v_mov_b32_e32 v5, v0
	v_mov_b32_e32 v6, v0
	v_mov_b32_e32 v7, v0
	v_mov_b32_e32 v16, v0
	v_mov_b32_e32 v17, v0
	v_mov_b32_e32 v18, v0
	v_mov_b32_e32 v19, v0
	v_mov_b32_e32 v20, v0
	v_mov_b32_e32 v21, v0
	v_mov_b32_e32 v22, v0
	v_mov_b32_e32 v23, v0
	s_waitcnt vmcnt(0)
	v_mov_b64_e32 v[8:9], 0
	v_mov_b64_e32 v[10:11], 0
	v_mov_b64_e32 v[12:13], 0
	v_mov_b64_e32 v[14:15], 0
	v_mov_b64_e32 v[24:25], 0
	v_mov_b64_e32 v[26:27], 0
	v_mov_b64_e32 v[28:29], 0
	v_mov_b64_e32 v[30:31], 0
	v_mov_b64_e32 v[32:33], 0
	v_mov_b64_e32 v[34:35], 0
	v_mov_b64_e32 v[36:37], 0
	v_mov_b64_e32 v[38:39], 0
	v_mov_b64_e32 v[40:41], 0
	v_mov_b64_e32 v[42:43], 0
	v_mov_b64_e32 v[44:45], 0
	v_mov_b64_e32 v[46:47], 0
	v_mov_b64_e32 v[48:49], 0
	v_mov_b64_e32 v[50:51], 0
	v_mov_b64_e32 v[52:53], 0
	v_mov_b64_e32 v[54:55], 0
	v_mov_b64_e32 v[56:57], 0
	v_mov_b64_e32 v[58:59], 0
	v_mov_b64_e32 v[60:61], 0
	v_mov_b64_e32 v[62:63], 0
	v_mov_b64_e32 v[64:65], 0
	v_mov_b64_e32 v[66:67], 0
	v_mov_b64_e32 v[68:69], 0
	v_mov_b64_e32 v[70:71], 0
	v_mov_b64_e32 v[72:73], 0
	v_mov_b64_e32 v[74:75], 0
	v_mov_b64_e32 v[76:77], 0
	v_mov_b64_e32 v[78:79], 0
	v_mov_b64_e32 v[80:81], 0
	v_mov_b64_e32 v[82:83], 0
	v_mov_b64_e32 v[84:85], 0
	v_mov_b64_e32 v[86:87], 0
	v_mov_b64_e32 v[88:89], 0
	v_mov_b64_e32 v[90:91], 0
	v_mov_b64_e32 v[92:93], 0
	v_mov_b64_e32 v[94:95], 0
	v_mov_b64_e32 v[96:97], 0
	v_mov_b64_e32 v[98:99], 0
	v_mov_b64_e32 v[100:101], 0
	v_mov_b64_e32 v[102:103], 0
	v_mov_b64_e32 v[104:105], 0
	v_mov_b64_e32 v[106:107], 0
	v_mov_b64_e32 v[108:109], 0
	v_mov_b64_e32 v[110:111], 0
	v_mov_b64_e32 v[112:113], 0
	v_mov_b64_e32 v[114:115], 0
	v_mov_b64_e32 v[116:117], 0
	v_mov_b64_e32 v[118:119], 0
	v_mov_b64_e32 v[120:121], 0
	v_mov_b64_e32 v[122:123], 0
	v_mov_b64_e32 v[124:125], 0
	v_mov_b64_e32 v[126:127], 0
	s_branch .Lz64_3
	s_nop 0
	s_nop 0
	s_nop 0
	s_nop 0
	s_nop 0
	s_nop 0
	s_nop 0
	s_nop 0
	s_nop 0
	s_nop 0
	s_nop 0
	s_nop 0
	s_nop 0
	s_nop 0
	s_nop 0
	s_nop 0
	s_nop 0
	s_nop 0
	s_nop 0
	s_nop 0
	s_nop 0
	s_nop 0
	s_nop 0
	s_nop 0
	s_nop 0
	s_nop 0
	s_nop 0
	s_nop 0
	s_nop 0
	s_nop 0
	s_nop 0
	s_nop 0
	s_nop 0
	s_nop 0
	s_nop 0
	s_nop 0
	s_nop 0
	s_nop 0
	s_nop 0
	s_nop 0
	s_nop 0
	s_nop 0
	s_nop 0
	s_nop 0
	s_nop 0
	s_nop 0
	s_nop 0
	s_nop 0
	s_nop 0
	s_nop 0
	s_nop 0
	s_nop 0
	s_nop 0
	s_nop 0
	s_nop 0
.Lz64_3:
.LBB0_1960:
	ds_read_b128 v[146:149], v162
	ds_read_b128 v[166:169], v162 offset:1024
	ds_read_b128 v[170:173], v162 offset:2048
	ds_read_b128 v[174:177], v162 offset:3072
	ds_read_b128 v[178:181], v163
	ds_read_b128 v[182:185], v163 offset:1024
	ds_read_b128 v[186:189], v163 offset:2048
	ds_read_b128 v[190:193], v163 offset:3072
	s_add_u32 s26, s24, 0xfffe0080
	s_addc_u32 s27, s25, -1
	s_cmp_eq_u32 s53, 4
	s_cselect_b32 s29, s19, s27
	s_cselect_b32 s28, s33, s26
	s_cselect_b32 s27, s17, s52
	s_cselect_b32 s26, s50, s51
	v_lshl_add_u64 v[150:151], s[24:25], 0, v[136:137]
	s_add_i32 m0, s36, 0xc000
	ds_read_b128 v[194:197], v164
	ds_read_b128 v[198:201], v164 offset:1024
	ds_read_b128 v[202:205], v164 offset:2048
	ds_read_b128 v[206:209], v164 offset:3072
	ds_read_b128 v[210:213], v164 offset:4096
	ds_read_b128 v[214:217], v164 offset:5120
	ds_read_b128 v[218:221], v164 offset:6144
	ds_read_b128 v[222:225], v164 offset:7168
	global_load_lds_dwordx4 v[150:151], off
	v_lshl_add_u64 v[150:151], s[24:25], 0, v[138:139]
	s_add_i32 m0, s36, 0xe000
	s_nop 0
	global_load_lds_dwordx4 v[150:151], off
	s_waitcnt vmcnt(8)
	s_waitcnt lgkmcnt(0)
	s_barrier
	s_setprio 1
	s_waitcnt lgkmcnt(0)
	v_mfma_f32_16x16x32_bf16 v[124:127], v[146:149], v[194:197], v[124:127]
	v_mfma_f32_16x16x32_bf16 v[120:123], v[170:173], v[194:197], v[120:123]
	v_mfma_f32_16x16x32_bf16 v[108:111], v[146:149], v[202:205], v[108:111]
	v_mfma_f32_16x16x32_bf16 v[104:107], v[170:173], v[202:205], v[104:107]
	v_mfma_f32_16x16x32_bf16 v[92:95], v[146:149], v[210:213], v[92:95]
	v_mfma_f32_16x16x32_bf16 v[88:91], v[170:173], v[210:213], v[88:91]
	v_mfma_f32_16x16x32_bf16 v[76:79], v[146:149], v[218:221], v[76:79]
	v_mfma_f32_16x16x32_bf16 v[72:75], v[170:173], v[218:221], v[72:75]
	v_mfma_f32_16x16x32_bf16 v[124:127], v[166:169], v[198:201], v[124:127]
	v_mfma_f32_16x16x32_bf16 v[120:123], v[174:177], v[198:201], v[120:123]
	v_mfma_f32_16x16x32_bf16 v[108:111], v[166:169], v[206:209], v[108:111]
	v_mfma_f32_16x16x32_bf16 v[104:107], v[174:177], v[206:209], v[104:107]
	v_mfma_f32_16x16x32_bf16 v[92:95], v[166:169], v[214:217], v[92:95]
	v_mfma_f32_16x16x32_bf16 v[88:91], v[174:177], v[214:217], v[88:91]
	v_mfma_f32_16x16x32_bf16 v[76:79], v[166:169], v[222:225], v[76:79]
	v_mfma_f32_16x16x32_bf16 v[72:75], v[174:177], v[222:225], v[72:75]
	s_setprio 0
	s_setprio 1
	v_mfma_f32_16x16x32_bf16 v[116:119], v[178:181], v[194:197], v[116:119]
	v_mfma_f32_16x16x32_bf16 v[112:115], v[186:189], v[194:197], v[112:115]
	v_mfma_f32_16x16x32_bf16 v[100:103], v[178:181], v[202:205], v[100:103]
	v_mfma_f32_16x16x32_bf16 v[96:99], v[186:189], v[202:205], v[96:99]
	v_mfma_f32_16x16x32_bf16 v[84:87], v[178:181], v[210:213], v[84:87]
	v_mfma_f32_16x16x32_bf16 v[80:83], v[186:189], v[210:213], v[80:83]
	v_mfma_f32_16x16x32_bf16 v[68:71], v[178:181], v[218:221], v[68:71]
	v_mfma_f32_16x16x32_bf16 v[64:67], v[186:189], v[218:221], v[64:67]
	v_mfma_f32_16x16x32_bf16 v[116:119], v[182:185], v[198:201], v[116:119]
	v_mfma_f32_16x16x32_bf16 v[112:115], v[190:193], v[198:201], v[112:115]
	v_mfma_f32_16x16x32_bf16 v[100:103], v[182:185], v[206:209], v[100:103]
	v_mfma_f32_16x16x32_bf16 v[96:99], v[190:193], v[206:209], v[96:99]
	v_mfma_f32_16x16x32_bf16 v[84:87], v[182:185], v[214:217], v[84:87]
	v_mfma_f32_16x16x32_bf16 v[80:83], v[190:193], v[214:217], v[80:83]
	v_mfma_f32_16x16x32_bf16 v[68:71], v[182:185], v[222:225], v[68:71]
	v_mfma_f32_16x16x32_bf16 v[64:67], v[190:193], v[222:225], v[64:67]
	s_setprio 0
	s_barrier
; #define PG8_STAGE(bufoff, gbase, voff) do { _Pragma("unroll") for (int _i = 0; _i < 2; ++_i) \
;         __builtin_amdgcn_global_load_lds((const unsigned*)((const char*)(gbase) + (voff)[_i]), (PG8_LAS unsigned*)(lds + (bufoff) + ldsw + _i * 8192), 16, 0, 0); } while (0)
; #define PG8_LDA(dst, b, h) do { _Pragma("unroll") for (int m = 0; m < 4; ++m) _Pragma("unroll") for (int k = 0; k < 2; ++k) dst[m][k] = *(const PG8_LAS bf16x8*)(lds + PG8_SA(b, h) + aoff + m * 2048 + k * 1024); } while (0)
; #define PG8_LDB(dst, b, h) do { _Pragma("unroll") for (int n = 0; n < 2; ++n) _Pragma("unroll") for (int k = 0; k < 2; ++k) dst[n][k] = *(const PG8_LAS bf16x8*)(lds + PG8_SB(b, h) + boff + n * 2048 + k * 1024); } while (0)
; #define PG8_MMA(ai, bj, At, Bt) do { __builtin_amdgcn_s_setprio(1); _Pragma("unroll") for (int m = 0; m < 4; ++m) _Pragma("unroll") for (int n = 0; n < 2; ++n) _Pragma("unroll") for (int k = 0; k < 2; ++k) \
;         acc[ai][bj][m][n] = __builtin_amdgcn_mfma_f32_16x16x32_bf16(Bt[n][k], At[m][k], acc[ai][bj][m][n], 0, 0, 0); __builtin_amdgcn_s_setprio(0); } while (0)
; #define PG8_WAIT_V(n) asm volatile("s_waitcnt vmcnt(" #n ")" ::: "memory")
; #define PG8_WAIT_L(n) asm volatile("s_waitcnt lgkmcnt(" #n ")" ::: "memory")
; #define PG8_BAR __builtin_amdgcn_s_barrier()
; #define PG8_SCHED __builtin_amdgcn_sched_barrier(0)
; template <class Epi, class Sched, bool ALIGN_EPI = false, bool SP2 = false>
; __device__ __forceinline__ void gemm_phase(PG8_LAS unsigned char* lds, const Gemm g, const Sched& S, const Epi& E) {
;     ...
;             PG8_LDA(At, 0, 1); PG8_STAGE(PG8_SB(0, 0), b2, voffB); PG8_STAGE(PG8_SB(0, 1), b2 + hstep, voffB); PG8_STAGE(PG8_SA(0, 0), a2, voffA);
;             PG8_WAIT_V(8); PG8_WAIT_L(0); PG8_BAR; PG8_MMA(1, 0, At, B0); PG8_MMA(1, 1, At, B1); PG8_BAR; PG8_SCHED;
;             PG8_LDB(B0, 1, 0); PG8_LDB(B1, 1, 1); PG8_SCHED; PG8_LDA(At, 1, 0); PG8_STAGE(PG8_SA(0, 1), a2 + hstep, voffA);
	s_add_i32 s54, s46, s35
	v_lshl_add_u64 v[150:151], s[26:27], 0, v[130:131]
	s_mov_b32 m0, s54
	ds_read_b128 v[194:197], v164 offset:16384
	ds_read_b128 v[198:201], v164 offset:17408
	ds_read_b128 v[202:205], v164 offset:18432
	ds_read_b128 v[206:209], v164 offset:19456
	ds_read_b128 v[210:213], v164 offset:20480
	ds_read_b128 v[214:217], v164 offset:21504
	ds_read_b128 v[218:221], v164 offset:22528
	ds_read_b128 v[222:225], v164 offset:23552
	global_load_lds_dwordx4 v[150:151], off
	s_add_i32 m0, s54, 0x2000
	s_add_u32 s54, s26, 0x20000
	v_lshl_add_u64 v[226:227], s[26:27], 0, v[134:135]
	s_addc_u32 s55, s27, 0
	s_add_i32 s56, s47, s35
	global_load_lds_dwordx4 v[226:227], off
	v_lshl_add_u64 v[228:229], s[54:55], 0, v[130:131]
	s_mov_b32 m0, s56
	v_lshl_add_u64 v[230:231], s[28:29], 0, v[132:133]
	global_load_lds_dwordx4 v[228:229], off
	v_lshl_add_u64 v[228:229], s[54:55], 0, v[134:135]
	s_add_i32 m0, s56, 0x2000
	s_nop 0
	global_load_lds_dwordx4 v[228:229], off
	v_lshl_add_u64 v[228:229], s[28:29], 0, v[128:129]
	s_mov_b32 m0, s36
	s_nop 0
	global_load_lds_dwordx4 v[228:229], off
	s_mov_b32 m0, s37
	s_nop 0
	global_load_lds_dwordx4 v[230:231], off
	s_waitcnt vmcnt(8)
	s_waitcnt lgkmcnt(0)
	s_barrier
	s_setprio 1
	s_waitcnt lgkmcnt(0)
	v_mfma_f32_16x16x32_bf16 v[60:63], v[146:149], v[194:197], v[60:63]
	v_mfma_f32_16x16x32_bf16 v[56:59], v[170:173], v[194:197], v[56:59]
	v_mfma_f32_16x16x32_bf16 v[44:47], v[146:149], v[202:205], v[44:47]
	v_mfma_f32_16x16x32_bf16 v[40:43], v[170:173], v[202:205], v[40:43]
	v_mfma_f32_16x16x32_bf16 v[28:31], v[146:149], v[210:213], v[28:31]
	v_mfma_f32_16x16x32_bf16 v[24:27], v[170:173], v[210:213], v[24:27]
	v_mfma_f32_16x16x32_bf16 v[12:15], v[146:149], v[218:221], v[12:15]
	v_mfma_f32_16x16x32_bf16 v[8:11], v[170:173], v[218:221], v[8:11]
	v_mfma_f32_16x16x32_bf16 v[60:63], v[166:169], v[198:201], v[60:63]
	v_mfma_f32_16x16x32_bf16 v[56:59], v[174:177], v[198:201], v[56:59]
	v_mfma_f32_16x16x32_bf16 v[44:47], v[166:169], v[206:209], v[44:47]
	v_mfma_f32_16x16x32_bf16 v[40:43], v[174:177], v[206:209], v[40:43]
	v_mfma_f32_16x16x32_bf16 v[28:31], v[166:169], v[214:217], v[28:31]
	v_mfma_f32_16x16x32_bf16 v[24:27], v[174:177], v[214:217], v[24:27]
	v_mfma_f32_16x16x32_bf16 v[12:15], v[166:169], v[222:225], v[12:15]
	v_mfma_f32_16x16x32_bf16 v[8:11], v[174:177], v[222:225], v[8:11]
	s_setprio 0
	s_setprio 1
	v_mfma_f32_16x16x32_bf16 v[52:55], v[178:181], v[194:197], v[52:55]
	v_mfma_f32_16x16x32_bf16 v[48:51], v[186:189], v[194:197], v[48:51]
	v_mfma_f32_16x16x32_bf16 v[36:39], v[178:181], v[202:205], v[36:39]
	v_mfma_f32_16x16x32_bf16 v[32:35], v[186:189], v[202:205], v[32:35]
	v_mfma_f32_16x16x32_bf16 v[20:23], v[178:181], v[210:213], v[20:23]
	v_mfma_f32_16x16x32_bf16 v[16:19], v[186:189], v[210:213], v[16:19]
	v_mfma_f32_16x16x32_bf16 v[4:7], v[178:181], v[218:221], v[4:7]
	v_mfma_f32_16x16x32_bf16 v[0:3], v[186:189], v[218:221], v[0:3]
	v_mfma_f32_16x16x32_bf16 v[52:55], v[182:185], v[198:201], v[52:55]
	v_mfma_f32_16x16x32_bf16 v[48:51], v[190:193], v[198:201], v[48:51]
	v_mfma_f32_16x16x32_bf16 v[36:39], v[182:185], v[206:209], v[36:39]
	v_mfma_f32_16x16x32_bf16 v[32:35], v[190:193], v[206:209], v[32:35]
	v_mfma_f32_16x16x32_bf16 v[20:23], v[182:185], v[214:217], v[20:23]
	v_mfma_f32_16x16x32_bf16 v[16:19], v[190:193], v[214:217], v[16:19]
	v_mfma_f32_16x16x32_bf16 v[4:7], v[182:185], v[222:225], v[4:7]
	v_mfma_f32_16x16x32_bf16 v[0:3], v[190:193], v[222:225], v[0:3]
	s_setprio 0
	s_barrier
	s_add_i32 s54, s42, 0x100
	v_add_u32_e32 v190, s54, v160
	ds_read_b128 v[146:149], v165
	ds_read_b128 v[166:169], v165 offset:1024
	ds_read_b128 v[170:173], v165 offset:2048
	ds_read_b128 v[174:177], v165 offset:3072
	ds_read_b128 v[178:181], v190
	ds_read_b128 v[182:185], v190 offset:1024
	ds_read_b128 v[186:189], v190 offset:2048
	ds_read_b128 v[190:193], v190 offset:3072
	s_add_u32 s28, s28, 0x20000
	s_addc_u32 s29, s29, 0
	s_mov_b32 m0, s38
	v_lshl_add_u64 v[232:233], s[28:29], 0, v[128:129]
	ds_read_b128 v[194:197], v164 offset:32768
	ds_read_b128 v[198:201], v164 offset:33792
	ds_read_b128 v[202:205], v164 offset:34816
	ds_read_b128 v[206:209], v164 offset:35840
	ds_read_b128 v[210:213], v164 offset:36864
	ds_read_b128 v[214:217], v164 offset:37888
	ds_read_b128 v[218:221], v164 offset:38912
	ds_read_b128 v[222:225], v164 offset:39936
	global_load_lds_dwordx4 v[232:233], off
	v_lshl_add_u64 v[232:233], s[28:29], 0, v[132:133]
	s_mov_b32 m0, s39
	s_nop 0
	global_load_lds_dwordx4 v[232:233], off
	s_waitcnt vmcnt(8)
	s_waitcnt lgkmcnt(0)
	s_barrier
; #define PG8_STAGE(bufoff, gbase, voff) do { _Pragma("unroll") for (int _i = 0; _i < 2; ++_i) \
;         __builtin_amdgcn_global_load_lds((const unsigned*)((const char*)(gbase) + (voff)[_i]), (PG8_LAS unsigned*)(lds + (bufoff) + ldsw + _i * 8192), 16, 0, 0); } while (0)
; #define PG8_LDA(dst, b, h) do { _Pragma("unroll") for (int m = 0; m < 4; ++m) _Pragma("unroll") for (int k = 0; k < 2; ++k) dst[m][k] = *(const PG8_LAS bf16x8*)(lds + PG8_SA(b, h) + aoff + m * 2048 + k * 1024); } while (0)
; #define PG8_MMA(ai, bj, At, Bt) do { __builtin_amdgcn_s_setprio(1); _Pragma("unroll") for (int m = 0; m < 4; ++m) _Pragma("unroll") for (int n = 0; n < 2; ++n) _Pragma("unroll") for (int k = 0; k < 2; ++k) \
;         acc[ai][bj][m][n] = __builtin_amdgcn_mfma_f32_16x16x32_bf16(Bt[n][k], At[m][k], acc[ai][bj][m][n], 0, 0, 0); __builtin_amdgcn_s_setprio(0); } while (0)
; #define PG8_WAIT_V(n) asm volatile("s_waitcnt vmcnt(" #n ")" ::: "memory")
; #define PG8_WAIT_L(n) asm volatile("s_waitcnt lgkmcnt(" #n ")" ::: "memory")
; #define PG8_BAR __builtin_amdgcn_s_barrier()
; #define PG8_SCHED __builtin_amdgcn_sched_barrier(0)
; template <class Epi, class Sched, bool ALIGN_EPI = false, bool SP2 = false>
; __device__ __forceinline__ void gemm_phase(PG8_LAS unsigned char* lds, const Gemm g, const Sched& S, const Epi& E) {
;     ...
;             PG8_WAIT_V(8); PG8_WAIT_L(0); PG8_BAR; PG8_MMA(0, 0, At, B0); PG8_MMA(0, 1, At, B1); PG8_BAR; PG8_SCHED;
;             PG8_LDA(At, 1, 1); PG8_STAGE(PG8_SB(1, 0), b3, voffB); PG8_STAGE(PG8_SB(1, 1), b3 + hstep, voffB); PG8_STAGE(PG8_SA(1, 0), a3, voffA);
;             PG8_WAIT_V(8); PG8_WAIT_L(0); PG8_BAR; PG8_MMA(1, 0, At, B0); PG8_MMA(1, 1, At, B1); PG8_BAR; PG8_SCHED;
;     ...
;         if constexpr (ALIGN_EPI) { if (wr == 0) PG8_BAR; }
	s_setprio 1
	s_waitcnt lgkmcnt(0)
	v_mfma_f32_16x16x32_bf16 v[124:127], v[146:149], v[194:197], v[124:127]
	v_mfma_f32_16x16x32_bf16 v[120:123], v[170:173], v[194:197], v[120:123]
	v_mfma_f32_16x16x32_bf16 v[108:111], v[146:149], v[202:205], v[108:111]
	v_mfma_f32_16x16x32_bf16 v[104:107], v[170:173], v[202:205], v[104:107]
	v_mfma_f32_16x16x32_bf16 v[92:95], v[146:149], v[210:213], v[92:95]
	v_mfma_f32_16x16x32_bf16 v[88:91], v[170:173], v[210:213], v[88:91]
	v_mfma_f32_16x16x32_bf16 v[76:79], v[146:149], v[218:221], v[76:79]
	v_mfma_f32_16x16x32_bf16 v[72:75], v[170:173], v[218:221], v[72:75]
	v_mfma_f32_16x16x32_bf16 v[124:127], v[166:169], v[198:201], v[124:127]
	v_mfma_f32_16x16x32_bf16 v[120:123], v[174:177], v[198:201], v[120:123]
	v_mfma_f32_16x16x32_bf16 v[108:111], v[166:169], v[206:209], v[108:111]
	v_mfma_f32_16x16x32_bf16 v[104:107], v[174:177], v[206:209], v[104:107]
	v_mfma_f32_16x16x32_bf16 v[92:95], v[166:169], v[214:217], v[92:95]
	v_mfma_f32_16x16x32_bf16 v[88:91], v[174:177], v[214:217], v[88:91]
	v_mfma_f32_16x16x32_bf16 v[76:79], v[166:169], v[222:225], v[76:79]
	v_mfma_f32_16x16x32_bf16 v[72:75], v[174:177], v[222:225], v[72:75]
	s_setprio 0
	s_setprio 1
	v_mfma_f32_16x16x32_bf16 v[116:119], v[178:181], v[194:197], v[116:119]
	v_mfma_f32_16x16x32_bf16 v[112:115], v[186:189], v[194:197], v[112:115]
	v_mfma_f32_16x16x32_bf16 v[100:103], v[178:181], v[202:205], v[100:103]
	v_mfma_f32_16x16x32_bf16 v[96:99], v[186:189], v[202:205], v[96:99]
	v_mfma_f32_16x16x32_bf16 v[84:87], v[178:181], v[210:213], v[84:87]
	v_mfma_f32_16x16x32_bf16 v[80:83], v[186:189], v[210:213], v[80:83]
	v_mfma_f32_16x16x32_bf16 v[68:71], v[178:181], v[218:221], v[68:71]
	v_mfma_f32_16x16x32_bf16 v[64:67], v[186:189], v[218:221], v[64:67]
	v_mfma_f32_16x16x32_bf16 v[116:119], v[182:185], v[198:201], v[116:119]
	v_mfma_f32_16x16x32_bf16 v[112:115], v[190:193], v[198:201], v[112:115]
	v_mfma_f32_16x16x32_bf16 v[100:103], v[182:185], v[206:209], v[100:103]
	v_mfma_f32_16x16x32_bf16 v[96:99], v[190:193], v[206:209], v[96:99]
	v_mfma_f32_16x16x32_bf16 v[84:87], v[182:185], v[214:217], v[84:87]
	v_mfma_f32_16x16x32_bf16 v[80:83], v[190:193], v[214:217], v[80:83]
	v_mfma_f32_16x16x32_bf16 v[68:71], v[182:185], v[222:225], v[68:71]
	v_mfma_f32_16x16x32_bf16 v[64:67], v[190:193], v[222:225], v[64:67]
	s_setprio 0
	s_barrier
	s_add_i32 s28, s49, s35
	v_lshl_add_u64 v[150:151], v[150:151], 0, s[12:13]
	s_mov_b32 m0, s28
	ds_read_b128 v[194:197], v164 offset:49152
	ds_read_b128 v[198:201], v164 offset:50176
	ds_read_b128 v[202:205], v164 offset:51200
	ds_read_b128 v[206:209], v164 offset:52224
	ds_read_b128 v[210:213], v164 offset:53248
	ds_read_b128 v[214:217], v164 offset:54272
	ds_read_b128 v[218:221], v164 offset:55296
	ds_read_b128 v[222:225], v164 offset:56320
	global_load_lds_dwordx4 v[150:151], off
	s_add_i32 m0, s28, 0x2000
	s_add_u32 s26, s26, 0x20080
	v_lshl_add_u64 v[150:151], v[226:227], 0, s[12:13]
	s_addc_u32 s27, s27, 0
	s_add_i32 s28, s54, s35
	global_load_lds_dwordx4 v[150:151], off
	v_lshl_add_u64 v[150:151], s[26:27], 0, v[130:131]
	s_mov_b32 m0, s28
	s_nop 0
	global_load_lds_dwordx4 v[150:151], off
	v_lshl_add_u64 v[150:151], s[26:27], 0, v[134:135]
	s_add_i32 m0, s28, 0x2000
	s_nop 0
	global_load_lds_dwordx4 v[150:151], off
	v_lshl_add_u64 v[150:151], v[228:229], 0, s[12:13]
	s_mov_b32 m0, s40
	s_nop 0
	global_load_lds_dwordx4 v[150:151], off
	v_lshl_add_u64 v[150:151], v[230:231], 0, s[12:13]
	s_mov_b32 m0, s41
	s_nop 0
	global_load_lds_dwordx4 v[150:151], off
	s_waitcnt vmcnt(8)
	s_waitcnt lgkmcnt(0)
	s_barrier
	s_setprio 1
	s_waitcnt lgkmcnt(0)
	v_mfma_f32_16x16x32_bf16 v[60:63], v[146:149], v[194:197], v[60:63]
	v_mfma_f32_16x16x32_bf16 v[56:59], v[170:173], v[194:197], v[56:59]
	v_mfma_f32_16x16x32_bf16 v[44:47], v[146:149], v[202:205], v[44:47]
	v_mfma_f32_16x16x32_bf16 v[40:43], v[170:173], v[202:205], v[40:43]
	v_mfma_f32_16x16x32_bf16 v[28:31], v[146:149], v[210:213], v[28:31]
	v_mfma_f32_16x16x32_bf16 v[24:27], v[170:173], v[210:213], v[24:27]
	v_mfma_f32_16x16x32_bf16 v[12:15], v[146:149], v[218:221], v[12:15]
	v_mfma_f32_16x16x32_bf16 v[8:11], v[170:173], v[218:221], v[8:11]
	v_mfma_f32_16x16x32_bf16 v[60:63], v[166:169], v[198:201], v[60:63]
	v_mfma_f32_16x16x32_bf16 v[56:59], v[174:177], v[198:201], v[56:59]
	v_mfma_f32_16x16x32_bf16 v[44:47], v[166:169], v[206:209], v[44:47]
	v_mfma_f32_16x16x32_bf16 v[40:43], v[174:177], v[206:209], v[40:43]
	v_mfma_f32_16x16x32_bf16 v[28:31], v[166:169], v[214:217], v[28:31]
	v_mfma_f32_16x16x32_bf16 v[24:27], v[174:177], v[214:217], v[24:27]
	v_mfma_f32_16x16x32_bf16 v[12:15], v[166:169], v[222:225], v[12:15]
	v_mfma_f32_16x16x32_bf16 v[8:11], v[174:177], v[222:225], v[8:11]
	s_setprio 0
	s_setprio 1
	v_mfma_f32_16x16x32_bf16 v[52:55], v[178:181], v[194:197], v[52:55]
	v_mfma_f32_16x16x32_bf16 v[48:51], v[186:189], v[194:197], v[48:51]
	v_mfma_f32_16x16x32_bf16 v[36:39], v[178:181], v[202:205], v[36:39]
	v_mfma_f32_16x16x32_bf16 v[32:35], v[186:189], v[202:205], v[32:35]
	v_mfma_f32_16x16x32_bf16 v[20:23], v[178:181], v[210:213], v[20:23]
	v_mfma_f32_16x16x32_bf16 v[16:19], v[186:189], v[210:213], v[16:19]
	v_mfma_f32_16x16x32_bf16 v[4:7], v[178:181], v[218:221], v[4:7]
	v_mfma_f32_16x16x32_bf16 v[0:3], v[186:189], v[218:221], v[0:3]
	v_mfma_f32_16x16x32_bf16 v[52:55], v[182:185], v[198:201], v[52:55]
	v_mfma_f32_16x16x32_bf16 v[48:51], v[190:193], v[198:201], v[48:51]
	v_mfma_f32_16x16x32_bf16 v[36:39], v[182:185], v[206:209], v[36:39]
	v_mfma_f32_16x16x32_bf16 v[32:35], v[190:193], v[206:209], v[32:35]
	v_mfma_f32_16x16x32_bf16 v[20:23], v[182:185], v[214:217], v[20:23]
	v_mfma_f32_16x16x32_bf16 v[16:19], v[190:193], v[214:217], v[16:19]
	v_mfma_f32_16x16x32_bf16 v[4:7], v[182:185], v[222:225], v[4:7]
	v_mfma_f32_16x16x32_bf16 v[0:3], v[190:193], v[222:225], v[0:3]
	s_setprio 0
	s_barrier
	s_add_i32 s53, s53, 2
	s_add_u32 s24, s24, 0x100
	s_addc_u32 s25, s25, 0
	s_add_u32 s51, s51, 0x100
	s_addc_u32 s52, s52, 0
	s_cmp_gt_u32 s53, 5
	s_cbranch_scc0 .LBB0_1960
	s_and_b64 vcc, exec, s[14:15]
	s_cbranch_vccz .LBB0_1963
	s_barrier

; #define PG8_STAGE(bufoff, gbase, voff) do { _Pragma("unroll") for (int _i = 0; _i < 2; ++_i) \
;         __builtin_amdgcn_global_load_lds((const unsigned*)((const char*)(gbase) + (voff)[_i]), (PG8_LAS unsigned*)(lds + (bufoff) + ldsw + _i * 8192), 16, 0, 0); } while (0)
; #define PG8_LDA(dst, b, h) do { _Pragma("unroll") for (int m = 0; m < 4; ++m) _Pragma("unroll") for (int k = 0; k < 2; ++k) dst[m][k] = *(const PG8_LAS bf16x8*)(lds + PG8_SA(b, h) + aoff + m * 2048 + k * 1024); } while (0)
; #define PG8_LDB(dst, b, h) do { _Pragma("unroll") for (int n = 0; n < 2; ++n) _Pragma("unroll") for (int k = 0; k < 2; ++k) dst[n][k] = *(const PG8_LAS bf16x8*)(lds + PG8_SB(b, h) + boff + n * 2048 + k * 1024); } while (0)
; #define PG8_MMA(ai, bj, At, Bt) do { __builtin_amdgcn_s_setprio(1); _Pragma("unroll") for (int m = 0; m < 4; ++m) _Pragma("unroll") for (int n = 0; n < 2; ++n) _Pragma("unroll") for (int k = 0; k < 2; ++k) \
;         acc[ai][bj][m][n] = __builtin_amdgcn_mfma_f32_16x16x32_bf16(Bt[n][k], At[m][k], acc[ai][bj][m][n], 0, 0, 0); __builtin_amdgcn_s_setprio(0); } while (0)
; #define PG8_WAIT_V(n) asm volatile("s_waitcnt vmcnt(" #n ")" ::: "memory")
; #define PG8_WAIT_L(n) asm volatile("s_waitcnt lgkmcnt(" #n ")" ::: "memory")
; #define PG8_BAR __builtin_amdgcn_s_barrier()
; #define PG8_SCHED __builtin_amdgcn_sched_barrier(0)
; template <class Epi, class Sched, bool ALIGN_EPI = false, bool SP2 = false>
; __device__ __forceinline__ void gemm_phase(PG8_LAS unsigned char* lds, const Gemm g, const Sched& S, const Epi& E) {
;     ...
;             PG8_LDB(B0, 0, 0); PG8_LDB(B1, 0, 1); PG8_SCHED; PG8_LDA(At, 0, 0); PG8_STAGE(PG8_SA(1, 1), a1 + hstep, voffA);
;             PG8_WAIT_V(8); PG8_WAIT_L(0); PG8_BAR; PG8_MMA(0, 0, At, B0); PG8_MMA(0, 1, At, B1); PG8_BAR; PG8_SCHED;
;     ...
; #pragma unroll
;         for (int a = 0; a < 2; ++a)
; #pragma unroll
;             for (int b = 0; b < 2; ++b)
; #pragma unroll
;                 for (int m = 0; m < 4; ++m)
; #pragma unroll
;                     for (int n = 0; n < 2; ++n) acc[a][b][m][n] = (f32x4){0.f, 0.f, 0.f, 0.f};
;         cur = nxt; cA = nA; cB = nB; ++ui;
.LBB0_1983:
	s_ashr_i32 s17, s16, 31
	s_lshl_b64 s[18:19], s[16:17], 18
	s_add_u32 s18, s29, s18
	s_addc_u32 s19, s30, s19
	s_and_b64 s[20:21], s[4:5], exec
	s_cselect_b32 s17, s19, s23
	s_cselect_b32 s33, s18, s22
	s_ashr_i32 s15, s14, 31
	s_lshl_b64 s[20:21], s[14:15], 18
	s_add_u32 s20, s31, s20
	s_addc_u32 s21, s34, s21
	s_and_b64 s[26:27], s[4:5], exec
	s_cselect_b32 s15, s21, s25
	s_cselect_b32 s50, s20, s24
	s_add_u32 s22, s22, 0x20080
	s_addc_u32 s23, s23, 0
	s_add_u32 s51, s24, 0x100
	v_mov_b32_e32 v0, 0
	s_addc_u32 s52, s25, 0
	s_mov_b32 s53, -2
	v_mov_b32_e32 v1, v0
	v_mov_b32_e32 v2, v0
	v_mov_b32_e32 v3, v0
	v_mov_b32_e32 v4, v0
	v_mov_b32_e32 v5, v0
	v_mov_b32_e32 v6, v0
	v_mov_b32_e32 v7, v0
	v_mov_b32_e32 v16, v0
	v_mov_b32_e32 v17, v0
	v_mov_b32_e32 v18, v0
	v_mov_b32_e32 v19, v0
	v_mov_b32_e32 v20, v0
	v_mov_b32_e32 v21, v0
	v_mov_b32_e32 v22, v0
	v_mov_b32_e32 v23, v0
	s_waitcnt vmcnt(0)
	v_mov_b64_e32 v[8:9], 0
	v_mov_b64_e32 v[10:11], 0
	v_mov_b64_e32 v[12:13], 0
	v_mov_b64_e32 v[14:15], 0
	v_mov_b64_e32 v[24:25], 0
	v_mov_b64_e32 v[26:27], 0
	v_mov_b64_e32 v[28:29], 0
	v_mov_b64_e32 v[30:31], 0
	v_mov_b64_e32 v[32:33], 0
	v_mov_b64_e32 v[34:35], 0
	v_mov_b64_e32 v[36:37], 0
	v_mov_b64_e32 v[38:39], 0
	v_mov_b64_e32 v[40:41], 0
	v_mov_b64_e32 v[42:43], 0
	v_mov_b64_e32 v[44:45], 0
	v_mov_b64_e32 v[46:47], 0
	v_mov_b64_e32 v[48:49], 0
	v_mov_b64_e32 v[50:51], 0
	v_mov_b64_e32 v[52:53], 0
	v_mov_b64_e32 v[54:55], 0
	v_mov_b64_e32 v[56:57], 0
	v_mov_b64_e32 v[58:59], 0
	v_mov_b64_e32 v[60:61], 0
	v_mov_b64_e32 v[62:63], 0
	v_mov_b64_e32 v[64:65], 0
	v_mov_b64_e32 v[66:67], 0
	v_mov_b64_e32 v[68:69], 0
	v_mov_b64_e32 v[70:71], 0
	v_mov_b64_e32 v[72:73], 0
	v_mov_b64_e32 v[74:75], 0
	v_mov_b64_e32 v[76:77], 0
	v_mov_b64_e32 v[78:79], 0
	v_mov_b64_e32 v[80:81], 0
	v_mov_b64_e32 v[82:83], 0
	v_mov_b64_e32 v[84:85], 0
	v_mov_b64_e32 v[86:87], 0
	v_mov_b64_e32 v[88:89], 0
	v_mov_b64_e32 v[90:91], 0
	v_mov_b64_e32 v[92:93], 0
	v_mov_b64_e32 v[94:95], 0
	v_mov_b64_e32 v[96:97], 0
	v_mov_b64_e32 v[98:99], 0
	v_mov_b64_e32 v[100:101], 0
	v_mov_b64_e32 v[102:103], 0
	v_mov_b64_e32 v[104:105], 0
	v_mov_b64_e32 v[106:107], 0
	v_mov_b64_e32 v[108:109], 0
	v_mov_b64_e32 v[110:111], 0
	v_mov_b64_e32 v[112:113], 0
	v_mov_b64_e32 v[114:115], 0
	v_mov_b64_e32 v[116:117], 0
	v_mov_b64_e32 v[118:119], 0
	v_mov_b64_e32 v[120:121], 0
	v_mov_b64_e32 v[122:123], 0
	v_mov_b64_e32 v[124:125], 0
	v_mov_b64_e32 v[126:127], 0
	s_branch .Lz64_4
	s_nop 0
	s_nop 0
	s_nop 0
	s_nop 0
	s_nop 0
	s_nop 0
	s_nop 0
	s_nop 0
	s_nop 0
	s_nop 0
	s_nop 0
	s_nop 0
	s_nop 0
	s_nop 0
	s_nop 0
	s_nop 0
	s_nop 0
	s_nop 0
	s_nop 0
	s_nop 0
	s_nop 0
	s_nop 0
	s_nop 0
	s_nop 0
	s_nop 0
	s_nop 0
	s_nop 0
	s_nop 0
	s_nop 0
	s_nop 0
	s_nop 0
	s_nop 0
	s_nop 0
	s_nop 0
	s_nop 0
	s_nop 0
	s_nop 0
	s_nop 0
	s_nop 0
	s_nop 0
	s_nop 0
	s_nop 0
	s_nop 0
	s_nop 0
	s_nop 0
	s_nop 0
	s_nop 0
	s_nop 0
	s_nop 0
	s_nop 0
	s_nop 0
	s_nop 0
	s_nop 0
	s_nop 0
	s_nop 0
.Lz64_4:
.LBB0_1984:
	ds_read_b128 v[146:149], v145
	ds_read_b128 v[150:153], v145 offset:1024
	ds_read_b128 v[160:163], v145 offset:2048
	ds_read_b128 v[164:167], v145 offset:3072
	ds_read_b128 v[168:171], v155
	ds_read_b128 v[172:175], v155 offset:1024
	ds_read_b128 v[176:179], v155 offset:2048
	ds_read_b128 v[180:183], v155 offset:3072
	s_add_u32 s24, s22, 0xfffe0080
	s_addc_u32 s25, s23, -1
	s_cmp_eq_u32 s53, 4
	s_cselect_b32 s27, s17, s25
	s_cselect_b32 s26, s33, s24
	s_cselect_b32 s25, s15, s52
	s_cselect_b32 s24, s50, s51
	v_lshl_add_u64 v[216:217], s[22:23], 0, v[136:137]
	s_add_i32 m0, s36, 0xc000
	ds_read_b128 v[184:187], v158
	ds_read_b128 v[188:191], v158 offset:1024
	ds_read_b128 v[192:195], v158 offset:2048
	ds_read_b128 v[196:199], v158 offset:3072
	ds_read_b128 v[200:203], v158 offset:4096
	ds_read_b128 v[204:207], v158 offset:5120
	ds_read_b128 v[208:211], v158 offset:6144
	ds_read_b128 v[212:215], v158 offset:7168
	global_load_lds_dwordx4 v[216:217], off
	v_lshl_add_u64 v[216:217], s[22:23], 0, v[138:139]
	s_add_i32 m0, s36, 0xe000
	s_nop 0
	global_load_lds_dwordx4 v[216:217], off
	s_waitcnt vmcnt(8)
	s_waitcnt lgkmcnt(0)
	s_barrier
	s_setprio 1
	s_waitcnt lgkmcnt(0)
	v_mfma_f32_16x16x32_bf16 v[124:127], v[146:149], v[184:187], v[124:127]
	v_mfma_f32_16x16x32_bf16 v[120:123], v[160:163], v[184:187], v[120:123]
	v_mfma_f32_16x16x32_bf16 v[108:111], v[146:149], v[192:195], v[108:111]
	v_mfma_f32_16x16x32_bf16 v[104:107], v[160:163], v[192:195], v[104:107]
	v_mfma_f32_16x16x32_bf16 v[92:95], v[146:149], v[200:203], v[92:95]
	v_mfma_f32_16x16x32_bf16 v[88:91], v[160:163], v[200:203], v[88:91]
	v_mfma_f32_16x16x32_bf16 v[76:79], v[146:149], v[208:211], v[76:79]
	v_mfma_f32_16x16x32_bf16 v[72:75], v[160:163], v[208:211], v[72:75]
	v_mfma_f32_16x16x32_bf16 v[124:127], v[150:153], v[188:191], v[124:127]
	v_mfma_f32_16x16x32_bf16 v[120:123], v[164:167], v[188:191], v[120:123]
	v_mfma_f32_16x16x32_bf16 v[108:111], v[150:153], v[196:199], v[108:111]
	v_mfma_f32_16x16x32_bf16 v[104:107], v[164:167], v[196:199], v[104:107]
	v_mfma_f32_16x16x32_bf16 v[92:95], v[150:153], v[204:207], v[92:95]
	v_mfma_f32_16x16x32_bf16 v[88:91], v[164:167], v[204:207], v[88:91]
	v_mfma_f32_16x16x32_bf16 v[76:79], v[150:153], v[212:215], v[76:79]
	v_mfma_f32_16x16x32_bf16 v[72:75], v[164:167], v[212:215], v[72:75]
	s_setprio 0
	s_setprio 1
	v_mfma_f32_16x16x32_bf16 v[116:119], v[168:171], v[184:187], v[116:119]
	v_mfma_f32_16x16x32_bf16 v[112:115], v[176:179], v[184:187], v[112:115]
	v_mfma_f32_16x16x32_bf16 v[100:103], v[168:171], v[192:195], v[100:103]
	v_mfma_f32_16x16x32_bf16 v[96:99], v[176:179], v[192:195], v[96:99]
	v_mfma_f32_16x16x32_bf16 v[84:87], v[168:171], v[200:203], v[84:87]
	v_mfma_f32_16x16x32_bf16 v[80:83], v[176:179], v[200:203], v[80:83]
	v_mfma_f32_16x16x32_bf16 v[68:71], v[168:171], v[208:211], v[68:71]
	v_mfma_f32_16x16x32_bf16 v[64:67], v[176:179], v[208:211], v[64:67]
	v_mfma_f32_16x16x32_bf16 v[116:119], v[172:175], v[188:191], v[116:119]
	v_mfma_f32_16x16x32_bf16 v[112:115], v[180:183], v[188:191], v[112:115]
	v_mfma_f32_16x16x32_bf16 v[100:103], v[172:175], v[196:199], v[100:103]
	v_mfma_f32_16x16x32_bf16 v[96:99], v[180:183], v[196:199], v[96:99]
	v_mfma_f32_16x16x32_bf16 v[84:87], v[172:175], v[204:207], v[84:87]
	v_mfma_f32_16x16x32_bf16 v[80:83], v[180:183], v[204:207], v[80:83]
	v_mfma_f32_16x16x32_bf16 v[68:71], v[172:175], v[212:215], v[68:71]
	v_mfma_f32_16x16x32_bf16 v[64:67], v[180:183], v[212:215], v[64:67]
	s_setprio 0
	s_barrier
; #define PG8_STAGE(bufoff, gbase, voff) do { _Pragma("unroll") for (int _i = 0; _i < 2; ++_i) \
;         __builtin_amdgcn_global_load_lds((const unsigned*)((const char*)(gbase) + (voff)[_i]), (PG8_LAS unsigned*)(lds + (bufoff) + ldsw + _i * 8192), 16, 0, 0); } while (0)
; #define PG8_LDA(dst, b, h) do { _Pragma("unroll") for (int m = 0; m < 4; ++m) _Pragma("unroll") for (int k = 0; k < 2; ++k) dst[m][k] = *(const PG8_LAS bf16x8*)(lds + PG8_SA(b, h) + aoff + m * 2048 + k * 1024); } while (0)
; #define PG8_LDB(dst, b, h) do { _Pragma("unroll") for (int n = 0; n < 2; ++n) _Pragma("unroll") for (int k = 0; k < 2; ++k) dst[n][k] = *(const PG8_LAS bf16x8*)(lds + PG8_SB(b, h) + boff + n * 2048 + k * 1024); } while (0)
; #define PG8_MMA(ai, bj, At, Bt) do { __builtin_amdgcn_s_setprio(1); _Pragma("unroll") for (int m = 0; m < 4; ++m) _Pragma("unroll") for (int n = 0; n < 2; ++n) _Pragma("unroll") for (int k = 0; k < 2; ++k) \
;         acc[ai][bj][m][n] = __builtin_amdgcn_mfma_f32_16x16x32_bf16(Bt[n][k], At[m][k], acc[ai][bj][m][n], 0, 0, 0); __builtin_amdgcn_s_setprio(0); } while (0)
; #define PG8_WAIT_V(n) asm volatile("s_waitcnt vmcnt(" #n ")" ::: "memory")
; #define PG8_WAIT_L(n) asm volatile("s_waitcnt lgkmcnt(" #n ")" ::: "memory")
; #define PG8_BAR __builtin_amdgcn_s_barrier()
; #define PG8_SCHED __builtin_amdgcn_sched_barrier(0)
; template <class Epi, class Sched, bool ALIGN_EPI = false, bool SP2 = false>
; __device__ __forceinline__ void gemm_phase(PG8_LAS unsigned char* lds, const Gemm g, const Sched& S, const Epi& E) {
;     ...
;             PG8_LDA(At, 0, 1); PG8_STAGE(PG8_SB(0, 0), b2, voffB); PG8_STAGE(PG8_SB(0, 1), b2 + hstep, voffB); PG8_STAGE(PG8_SA(0, 0), a2, voffA);
;             PG8_WAIT_V(8); PG8_WAIT_L(0); PG8_BAR; PG8_MMA(1, 0, At, B0); PG8_MMA(1, 1, At, B1); PG8_BAR; PG8_SCHED;
;             PG8_LDB(B0, 1, 0); PG8_LDB(B1, 1, 1); PG8_SCHED; PG8_LDA(At, 1, 0); PG8_STAGE(PG8_SA(0, 1), a2 + hstep, voffA);
	s_add_i32 s54, s46, s35
	v_lshl_add_u64 v[216:217], s[24:25], 0, v[130:131]
	s_mov_b32 m0, s54
	ds_read_b128 v[184:187], v158 offset:16384
	ds_read_b128 v[188:191], v158 offset:17408
	ds_read_b128 v[192:195], v158 offset:18432
	ds_read_b128 v[196:199], v158 offset:19456
	ds_read_b128 v[200:203], v158 offset:20480
	ds_read_b128 v[204:207], v158 offset:21504
	ds_read_b128 v[208:211], v158 offset:22528
	ds_read_b128 v[212:215], v158 offset:23552
	global_load_lds_dwordx4 v[216:217], off
	s_add_i32 m0, s54, 0x2000
	s_add_u32 s54, s24, 0x20000
	v_lshl_add_u64 v[218:219], s[24:25], 0, v[134:135]
	s_addc_u32 s55, s25, 0
	s_add_i32 s56, s47, s35
	global_load_lds_dwordx4 v[218:219], off
	v_lshl_add_u64 v[220:221], s[54:55], 0, v[130:131]
	s_mov_b32 m0, s56
	v_lshl_add_u64 v[222:223], s[26:27], 0, v[132:133]
	global_load_lds_dwordx4 v[220:221], off
	v_lshl_add_u64 v[220:221], s[54:55], 0, v[134:135]
	s_add_i32 m0, s56, 0x2000
	s_nop 0
	global_load_lds_dwordx4 v[220:221], off
	v_lshl_add_u64 v[220:221], s[26:27], 0, v[128:129]
	s_mov_b32 m0, s36
	s_nop 0
	global_load_lds_dwordx4 v[220:221], off
	s_mov_b32 m0, s37
	s_nop 0
	global_load_lds_dwordx4 v[222:223], off
	s_waitcnt vmcnt(8)
	s_waitcnt lgkmcnt(0)
	s_barrier
	s_setprio 1
	s_waitcnt lgkmcnt(0)
	v_mfma_f32_16x16x32_bf16 v[60:63], v[146:149], v[184:187], v[60:63]
	v_mfma_f32_16x16x32_bf16 v[56:59], v[160:163], v[184:187], v[56:59]
	v_mfma_f32_16x16x32_bf16 v[44:47], v[146:149], v[192:195], v[44:47]
	v_mfma_f32_16x16x32_bf16 v[40:43], v[160:163], v[192:195], v[40:43]
	v_mfma_f32_16x16x32_bf16 v[28:31], v[146:149], v[200:203], v[28:31]
	v_mfma_f32_16x16x32_bf16 v[24:27], v[160:163], v[200:203], v[24:27]
	v_mfma_f32_16x16x32_bf16 v[12:15], v[146:149], v[208:211], v[12:15]
	v_mfma_f32_16x16x32_bf16 v[8:11], v[160:163], v[208:211], v[8:11]
	v_mfma_f32_16x16x32_bf16 v[60:63], v[150:153], v[188:191], v[60:63]
	v_mfma_f32_16x16x32_bf16 v[56:59], v[164:167], v[188:191], v[56:59]
	v_mfma_f32_16x16x32_bf16 v[44:47], v[150:153], v[196:199], v[44:47]
	v_mfma_f32_16x16x32_bf16 v[40:43], v[164:167], v[196:199], v[40:43]
	v_mfma_f32_16x16x32_bf16 v[28:31], v[150:153], v[204:207], v[28:31]
	v_mfma_f32_16x16x32_bf16 v[24:27], v[164:167], v[204:207], v[24:27]
	v_mfma_f32_16x16x32_bf16 v[12:15], v[150:153], v[212:215], v[12:15]
	v_mfma_f32_16x16x32_bf16 v[8:11], v[164:167], v[212:215], v[8:11]
	s_setprio 0
	s_setprio 1
	v_mfma_f32_16x16x32_bf16 v[52:55], v[168:171], v[184:187], v[52:55]
	v_mfma_f32_16x16x32_bf16 v[48:51], v[176:179], v[184:187], v[48:51]
	v_mfma_f32_16x16x32_bf16 v[36:39], v[168:171], v[192:195], v[36:39]
	v_mfma_f32_16x16x32_bf16 v[32:35], v[176:179], v[192:195], v[32:35]
	v_mfma_f32_16x16x32_bf16 v[20:23], v[168:171], v[200:203], v[20:23]
	v_mfma_f32_16x16x32_bf16 v[16:19], v[176:179], v[200:203], v[16:19]
	v_mfma_f32_16x16x32_bf16 v[4:7], v[168:171], v[208:211], v[4:7]
	v_mfma_f32_16x16x32_bf16 v[0:3], v[176:179], v[208:211], v[0:3]
	v_mfma_f32_16x16x32_bf16 v[52:55], v[172:175], v[188:191], v[52:55]
	v_mfma_f32_16x16x32_bf16 v[48:51], v[180:183], v[188:191], v[48:51]
	v_mfma_f32_16x16x32_bf16 v[36:39], v[172:175], v[196:199], v[36:39]
	v_mfma_f32_16x16x32_bf16 v[32:35], v[180:183], v[196:199], v[32:35]
	v_mfma_f32_16x16x32_bf16 v[20:23], v[172:175], v[204:207], v[20:23]
	v_mfma_f32_16x16x32_bf16 v[16:19], v[180:183], v[204:207], v[16:19]
	v_mfma_f32_16x16x32_bf16 v[4:7], v[172:175], v[212:215], v[4:7]
	v_mfma_f32_16x16x32_bf16 v[0:3], v[180:183], v[212:215], v[0:3]
	s_setprio 0
	s_barrier
	s_add_i32 s54, s42, 0x100
	v_add_u32_e32 v180, s54, v157
	ds_read_b128 v[146:149], v159
	ds_read_b128 v[150:153], v159 offset:1024
	ds_read_b128 v[160:163], v159 offset:2048
	ds_read_b128 v[164:167], v159 offset:3072
	ds_read_b128 v[168:171], v180
	ds_read_b128 v[172:175], v180 offset:1024
	ds_read_b128 v[176:179], v180 offset:2048
	ds_read_b128 v[180:183], v180 offset:3072
	s_add_u32 s26, s26, 0x20000
	s_addc_u32 s27, s27, 0
	s_mov_b32 m0, s38
	v_lshl_add_u64 v[224:225], s[26:27], 0, v[128:129]
	ds_read_b128 v[184:187], v158 offset:32768
	ds_read_b128 v[188:191], v158 offset:33792
	ds_read_b128 v[192:195], v158 offset:34816
	ds_read_b128 v[196:199], v158 offset:35840
	ds_read_b128 v[200:203], v158 offset:36864
	ds_read_b128 v[204:207], v158 offset:37888
	ds_read_b128 v[208:211], v158 offset:38912
	ds_read_b128 v[212:215], v158 offset:39936
	global_load_lds_dwordx4 v[224:225], off
	v_lshl_add_u64 v[224:225], s[26:27], 0, v[132:133]
	s_mov_b32 m0, s39
	s_nop 0
	global_load_lds_dwordx4 v[224:225], off
	s_waitcnt vmcnt(8)
	s_waitcnt lgkmcnt(0)
	s_barrier
; #define PG8_STAGE(bufoff, gbase, voff) do { _Pragma("unroll") for (int _i = 0; _i < 2; ++_i) \
;         __builtin_amdgcn_global_load_lds((const unsigned*)((const char*)(gbase) + (voff)[_i]), (PG8_LAS unsigned*)(lds + (bufoff) + ldsw + _i * 8192), 16, 0, 0); } while (0)
; #define PG8_LDA(dst, b, h) do { _Pragma("unroll") for (int m = 0; m < 4; ++m) _Pragma("unroll") for (int k = 0; k < 2; ++k) dst[m][k] = *(const PG8_LAS bf16x8*)(lds + PG8_SA(b, h) + aoff + m * 2048 + k * 1024); } while (0)
; #define PG8_MMA(ai, bj, At, Bt) do { __builtin_amdgcn_s_setprio(1); _Pragma("unroll") for (int m = 0; m < 4; ++m) _Pragma("unroll") for (int n = 0; n < 2; ++n) _Pragma("unroll") for (int k = 0; k < 2; ++k) \
;         acc[ai][bj][m][n] = __builtin_amdgcn_mfma_f32_16x16x32_bf16(Bt[n][k], At[m][k], acc[ai][bj][m][n], 0, 0, 0); __builtin_amdgcn_s_setprio(0); } while (0)
; #define PG8_WAIT_V(n) asm volatile("s_waitcnt vmcnt(" #n ")" ::: "memory")
; #define PG8_WAIT_L(n) asm volatile("s_waitcnt lgkmcnt(" #n ")" ::: "memory")
; #define PG8_BAR __builtin_amdgcn_s_barrier()
; #define PG8_SCHED __builtin_amdgcn_sched_barrier(0)
; template <class Epi, class Sched, bool ALIGN_EPI = false, bool SP2 = false>
; __device__ __forceinline__ void gemm_phase(PG8_LAS unsigned char* lds, const Gemm g, const Sched& S, const Epi& E) {
;     ...
;             PG8_WAIT_V(8); PG8_WAIT_L(0); PG8_BAR; PG8_MMA(0, 0, At, B0); PG8_MMA(0, 1, At, B1); PG8_BAR; PG8_SCHED;
;             PG8_LDA(At, 1, 1); PG8_STAGE(PG8_SB(1, 0), b3, voffB); PG8_STAGE(PG8_SB(1, 1), b3 + hstep, voffB); PG8_STAGE(PG8_SA(1, 0), a3, voffA);
;             PG8_WAIT_V(8); PG8_WAIT_L(0); PG8_BAR; PG8_MMA(1, 0, At, B0); PG8_MMA(1, 1, At, B1); PG8_BAR; PG8_SCHED;
;     ...
;         if constexpr (ALIGN_EPI) { if (wr == 0) PG8_BAR; }
	s_setprio 1
	s_waitcnt lgkmcnt(0)
	v_mfma_f32_16x16x32_bf16 v[124:127], v[146:149], v[184:187], v[124:127]
	v_mfma_f32_16x16x32_bf16 v[120:123], v[160:163], v[184:187], v[120:123]
	v_mfma_f32_16x16x32_bf16 v[108:111], v[146:149], v[192:195], v[108:111]
	v_mfma_f32_16x16x32_bf16 v[104:107], v[160:163], v[192:195], v[104:107]
	v_mfma_f32_16x16x32_bf16 v[92:95], v[146:149], v[200:203], v[92:95]
	v_mfma_f32_16x16x32_bf16 v[88:91], v[160:163], v[200:203], v[88:91]
	v_mfma_f32_16x16x32_bf16 v[76:79], v[146:149], v[208:211], v[76:79]
	v_mfma_f32_16x16x32_bf16 v[72:75], v[160:163], v[208:211], v[72:75]
	v_mfma_f32_16x16x32_bf16 v[124:127], v[150:153], v[188:191], v[124:127]
	v_mfma_f32_16x16x32_bf16 v[120:123], v[164:167], v[188:191], v[120:123]
	v_mfma_f32_16x16x32_bf16 v[108:111], v[150:153], v[196:199], v[108:111]
	v_mfma_f32_16x16x32_bf16 v[104:107], v[164:167], v[196:199], v[104:107]
	v_mfma_f32_16x16x32_bf16 v[92:95], v[150:153], v[204:207], v[92:95]
	v_mfma_f32_16x16x32_bf16 v[88:91], v[164:167], v[204:207], v[88:91]
	v_mfma_f32_16x16x32_bf16 v[76:79], v[150:153], v[212:215], v[76:79]
	v_mfma_f32_16x16x32_bf16 v[72:75], v[164:167], v[212:215], v[72:75]
	s_setprio 0
	s_setprio 1
	v_mfma_f32_16x16x32_bf16 v[116:119], v[168:171], v[184:187], v[116:119]
	v_mfma_f32_16x16x32_bf16 v[112:115], v[176:179], v[184:187], v[112:115]
	v_mfma_f32_16x16x32_bf16 v[100:103], v[168:171], v[192:195], v[100:103]
	v_mfma_f32_16x16x32_bf16 v[96:99], v[176:179], v[192:195], v[96:99]
	v_mfma_f32_16x16x32_bf16 v[84:87], v[168:171], v[200:203], v[84:87]
	v_mfma_f32_16x16x32_bf16 v[80:83], v[176:179], v[200:203], v[80:83]
	v_mfma_f32_16x16x32_bf16 v[68:71], v[168:171], v[208:211], v[68:71]
	v_mfma_f32_16x16x32_bf16 v[64:67], v[176:179], v[208:211], v[64:67]
	v_mfma_f32_16x16x32_bf16 v[116:119], v[172:175], v[188:191], v[116:119]
	v_mfma_f32_16x16x32_bf16 v[112:115], v[180:183], v[188:191], v[112:115]
	v_mfma_f32_16x16x32_bf16 v[100:103], v[172:175], v[196:199], v[100:103]
	v_mfma_f32_16x16x32_bf16 v[96:99], v[180:183], v[196:199], v[96:99]
	v_mfma_f32_16x16x32_bf16 v[84:87], v[172:175], v[204:207], v[84:87]
	v_mfma_f32_16x16x32_bf16 v[80:83], v[180:183], v[204:207], v[80:83]
	v_mfma_f32_16x16x32_bf16 v[68:71], v[172:175], v[212:215], v[68:71]
	v_mfma_f32_16x16x32_bf16 v[64:67], v[180:183], v[212:215], v[64:67]
	s_setprio 0
	s_barrier
	s_add_i32 s26, s49, s35
	v_lshl_add_u64 v[216:217], v[216:217], 0, s[10:11]
	s_mov_b32 m0, s26
	ds_read_b128 v[184:187], v158 offset:49152
	ds_read_b128 v[188:191], v158 offset:50176
	ds_read_b128 v[192:195], v158 offset:51200
	ds_read_b128 v[196:199], v158 offset:52224
	ds_read_b128 v[200:203], v158 offset:53248
	ds_read_b128 v[204:207], v158 offset:54272
	ds_read_b128 v[208:211], v158 offset:55296
	ds_read_b128 v[212:215], v158 offset:56320
	global_load_lds_dwordx4 v[216:217], off
	s_add_i32 m0, s26, 0x2000
	s_add_u32 s24, s24, 0x20080
	v_lshl_add_u64 v[216:217], v[218:219], 0, s[10:11]
	s_addc_u32 s25, s25, 0
	s_add_i32 s26, s54, s35
	global_load_lds_dwordx4 v[216:217], off
	v_lshl_add_u64 v[216:217], s[24:25], 0, v[130:131]
	s_mov_b32 m0, s26
	s_nop 0
	global_load_lds_dwordx4 v[216:217], off
	v_lshl_add_u64 v[216:217], s[24:25], 0, v[134:135]
	s_add_i32 m0, s26, 0x2000
	s_nop 0
	global_load_lds_dwordx4 v[216:217], off
	v_lshl_add_u64 v[216:217], v[220:221], 0, s[10:11]
	s_mov_b32 m0, s40
	s_nop 0
	global_load_lds_dwordx4 v[216:217], off
	v_lshl_add_u64 v[216:217], v[222:223], 0, s[10:11]
	s_mov_b32 m0, s41
	s_nop 0
	global_load_lds_dwordx4 v[216:217], off
	s_waitcnt vmcnt(8)
	s_waitcnt lgkmcnt(0)
	s_barrier
	s_setprio 1
	s_waitcnt lgkmcnt(0)
	v_mfma_f32_16x16x32_bf16 v[60:63], v[146:149], v[184:187], v[60:63]
	v_mfma_f32_16x16x32_bf16 v[56:59], v[160:163], v[184:187], v[56:59]
	v_mfma_f32_16x16x32_bf16 v[44:47], v[146:149], v[192:195], v[44:47]
	v_mfma_f32_16x16x32_bf16 v[40:43], v[160:163], v[192:195], v[40:43]
	v_mfma_f32_16x16x32_bf16 v[28:31], v[146:149], v[200:203], v[28:31]
	v_mfma_f32_16x16x32_bf16 v[24:27], v[160:163], v[200:203], v[24:27]
	v_mfma_f32_16x16x32_bf16 v[12:15], v[146:149], v[208:211], v[12:15]
	v_mfma_f32_16x16x32_bf16 v[8:11], v[160:163], v[208:211], v[8:11]
	v_mfma_f32_16x16x32_bf16 v[60:63], v[150:153], v[188:191], v[60:63]
	v_mfma_f32_16x16x32_bf16 v[56:59], v[164:167], v[188:191], v[56:59]
	v_mfma_f32_16x16x32_bf16 v[44:47], v[150:153], v[196:199], v[44:47]
	v_mfma_f32_16x16x32_bf16 v[40:43], v[164:167], v[196:199], v[40:43]
	v_mfma_f32_16x16x32_bf16 v[28:31], v[150:153], v[204:207], v[28:31]
	v_mfma_f32_16x16x32_bf16 v[24:27], v[164:167], v[204:207], v[24:27]
	v_mfma_f32_16x16x32_bf16 v[12:15], v[150:153], v[212:215], v[12:15]
	v_mfma_f32_16x16x32_bf16 v[8:11], v[164:167], v[212:215], v[8:11]
	s_setprio 0
	s_setprio 1
	v_mfma_f32_16x16x32_bf16 v[52:55], v[168:171], v[184:187], v[52:55]
	v_mfma_f32_16x16x32_bf16 v[48:51], v[176:179], v[184:187], v[48:51]
	v_mfma_f32_16x16x32_bf16 v[36:39], v[168:171], v[192:195], v[36:39]
	v_mfma_f32_16x16x32_bf16 v[32:35], v[176:179], v[192:195], v[32:35]
	v_mfma_f32_16x16x32_bf16 v[20:23], v[168:171], v[200:203], v[20:23]
	v_mfma_f32_16x16x32_bf16 v[16:19], v[176:179], v[200:203], v[16:19]
	v_mfma_f32_16x16x32_bf16 v[4:7], v[168:171], v[208:211], v[4:7]
	v_mfma_f32_16x16x32_bf16 v[0:3], v[176:179], v[208:211], v[0:3]
	v_mfma_f32_16x16x32_bf16 v[52:55], v[172:175], v[188:191], v[52:55]
	v_mfma_f32_16x16x32_bf16 v[48:51], v[180:183], v[188:191], v[48:51]
	v_mfma_f32_16x16x32_bf16 v[36:39], v[172:175], v[196:199], v[36:39]
	v_mfma_f32_16x16x32_bf16 v[32:35], v[180:183], v[196:199], v[32:35]
	v_mfma_f32_16x16x32_bf16 v[20:23], v[172:175], v[204:207], v[20:23]
	v_mfma_f32_16x16x32_bf16 v[16:19], v[180:183], v[204:207], v[16:19]
	v_mfma_f32_16x16x32_bf16 v[4:7], v[172:175], v[212:215], v[4:7]
	v_mfma_f32_16x16x32_bf16 v[0:3], v[180:183], v[212:215], v[0:3]
	s_setprio 0
	s_barrier
	s_add_i32 s53, s53, 2
	s_add_u32 s22, s22, 0x100
	s_addc_u32 s23, s23, 0
	s_add_u32 s51, s51, 0x100
	s_addc_u32 s52, s52, 0
	s_cmp_gt_u32 s53, 5
	s_cbranch_scc0 .LBB0_1984
	s_and_b64 vcc, exec, s[12:13]
	s_cbranch_vccz .LBB0_1987
	s_barrier

; template <class Epi, class Sched, bool ALIGN_EPI = false, bool SP2 = false>
; __device__ __forceinline__ void gemm_phase(PG8_LAS unsigned char* lds, const Gemm g, const Sched& S, const Epi& E) {
;     ...
;         const bool has_next = S.next(ui + 1, nxt);
;         const char* nA = has_next ? (const char*)g.A + (size_t)nxt.pm * tstep : cA; const char* nB = has_next ? (const char*)g.Bt + (size_t)nxt.pn * tstep : cB;
;         for (int t = 0; t < nt; t += 2) {
;             const bool last = (t == nt - 2);
;             const char* a1 = cA + (size_t)(t + 1) * kstep;
;             const char* a2 = last ? nA : cA + (size_t)(t + 2) * kstep; const char* b2 = last ? nB : cB + (size_t)(t + 2) * kstep;
;             const char* a3 = a2 + kstep; const char* b3 = b2 + kstep;
;     ...
; #pragma unroll
;         for (int a = 0; a < 2; ++a)
; #pragma unroll
;             for (int b = 0; b < 2; ++b)
; #pragma unroll
;                 for (int m = 0; m < 4; ++m)
; #pragma unroll
;                     for (int n = 0; n < 2; ++n) acc[a][b][m][n] = (f32x4){0.f, 0.f, 0.f, 0.f};
;         cur = nxt; cA = nA; cB = nB; ++ui;
.LBB0_2060:
	s_ashr_i32 s21, s20, 31
	s_lshl_b64 s[22:23], s[20:21], 19
	v_readlane_b32 s24, v240, 5
	v_readlane_b32 s25, v240, 6
	s_add_u32 s22, s24, s22
	s_addc_u32 s23, s25, s23
	s_and_b64 s[24:25], s[4:5], exec
	s_cselect_b32 s21, s23, s29
	s_cselect_b32 s54, s22, s28
	s_ashr_i32 s19, s18, 31
	s_lshl_b64 s[24:25], s[18:19], 19
	s_add_u32 s24, s37, s24
	s_addc_u32 s25, s38, s25
	s_and_b64 s[34:35], s[4:5], exec
	s_cselect_b32 s19, s25, s31
	s_cselect_b32 s55, s24, s30
	s_add_u32 s28, s28, 0x40080
	s_addc_u32 s29, s29, 0
	s_add_u32 s56, s30, 0x100
	v_mov_b32_e32 v0, 0
	s_addc_u32 s57, s31, 0
	s_mov_b32 s58, -2
	v_mov_b32_e32 v1, 0
	v_mov_b64_e32 v[2:3], 0
	v_mov_b64_e32 v[4:5], 0
	v_mov_b64_e32 v[6:7], 0
	v_mov_b64_e32 v[8:9], 0
	v_mov_b64_e32 v[10:11], 0
	v_mov_b64_e32 v[12:13], 0
	v_mov_b64_e32 v[14:15], 0
	v_mov_b64_e32 v[16:17], 0
	v_mov_b64_e32 v[18:19], 0
	v_mov_b64_e32 v[20:21], 0
	v_mov_b64_e32 v[22:23], 0
	v_mov_b64_e32 v[24:25], 0
	v_mov_b64_e32 v[26:27], 0
	v_mov_b64_e32 v[28:29], 0
	v_mov_b64_e32 v[30:31], 0
	v_mov_b64_e32 v[32:33], 0
	v_mov_b64_e32 v[34:35], 0
	v_mov_b64_e32 v[36:37], 0
	v_mov_b64_e32 v[38:39], 0
	v_mov_b64_e32 v[40:41], 0
	v_mov_b64_e32 v[42:43], 0
	v_mov_b64_e32 v[44:45], 0
	v_mov_b64_e32 v[46:47], 0
	v_mov_b64_e32 v[48:49], 0
	v_mov_b64_e32 v[50:51], 0
	v_mov_b64_e32 v[52:53], 0
	v_mov_b64_e32 v[54:55], 0
	v_mov_b64_e32 v[56:57], 0
	v_mov_b64_e32 v[58:59], 0
	v_mov_b64_e32 v[60:61], 0
	v_mov_b64_e32 v[62:63], 0
	v_mov_b64_e32 v[64:65], 0
	v_mov_b64_e32 v[66:67], 0
	v_mov_b64_e32 v[68:69], 0
	v_mov_b64_e32 v[70:71], 0
	v_mov_b64_e32 v[72:73], 0
	v_mov_b32_e32 v74, 0
	v_mov_b64_e32 v[80:81], 0
	v_mov_b64_e32 v[82:83], 0
	v_mov_b64_e32 v[84:85], 0
	v_mov_b64_e32 v[86:87], 0
	v_mov_b64_e32 v[96:97], 0
	v_mov_b64_e32 v[98:99], 0
	v_mov_b64_e32 v[100:101], 0
	v_mov_b64_e32 v[102:103], 0
	v_mov_b64_e32 v[128:129], 0
	v_mov_b64_e32 v[130:131], 0
	v_mov_b64_e32 v[132:133], 0
	v_mov_b64_e32 v[134:135], 0
	s_branch .Lz64_5
	s_nop 0
	s_nop 0
	s_nop 0
	s_nop 0
	s_nop 0
	s_nop 0
	s_nop 0
	s_nop 0
	s_nop 0
	s_nop 0
	s_nop 0
	s_nop 0
	s_nop 0
	s_nop 0
	s_nop 0
	s_nop 0
	s_nop 0
	s_nop 0
	s_nop 0
	s_nop 0
	s_nop 0
	s_nop 0
	s_nop 0
	s_nop 0
	s_nop 0
	s_nop 0
	s_nop 0
	s_nop 0
	s_nop 0
	s_nop 0
	s_nop 0
	s_nop 0
	s_nop 0
	s_nop 0
	s_nop 0
	s_nop 0
	s_nop 0
	s_nop 0
	s_nop 0
	s_nop 0
	s_nop 0
	s_nop 0
	s_nop 0
	s_nop 0
	s_nop 0
	s_nop 0
	s_nop 0
.Lz64_5:
	s_waitcnt vmcnt(0)
	v_mov_b32_e32 v75, v0
	v_mov_b32_e32 v76, v0
	v_mov_b32_e32 v77, v0
	v_mov_b32_e32 v78, v0
	v_mov_b32_e32 v79, v0
	v_mov_b32_e32 v88, v0
	v_mov_b32_e32 v89, v0
	v_mov_b32_e32 v90, v0
	v_mov_b32_e32 v91, v0
	v_mov_b32_e32 v92, v0
	v_mov_b32_e32 v93, v0
	v_mov_b32_e32 v94, v0
	v_mov_b32_e32 v95, v0
	v_mov_b32_e32 v108, v0
	v_mov_b32_e32 v109, v0
	v_mov_b32_e32 v110, v0
	v_mov_b32_e32 v111, v0
	v_mov_b32_e32 v116, v0
	v_mov_b32_e32 v117, v0
	v_mov_b32_e32 v118, v0
	v_mov_b32_e32 v119, v0
	v_mov_b32_e32 v136, v0
	v_mov_b32_e32 v137, v0
	v_mov_b32_e32 v138, v0
	v_mov_b32_e32 v139, v0
	v_mov_b32_e32 v140, v0
	v_mov_b32_e32 v141, v0
	v_mov_b32_e32 v142, v0
	v_mov_b32_e32 v143, v0

; #define PG8_STAGE(bufoff, gbase, voff) do { _Pragma("unroll") for (int _i = 0; _i < 2; ++_i) \
;         __builtin_amdgcn_global_load_lds((const unsigned*)((const char*)(gbase) + (voff)[_i]), (PG8_LAS unsigned*)(lds + (bufoff) + ldsw + _i * 8192), 16, 0, 0); } while (0)
; #define PG8_LDA(dst, b, h) do { _Pragma("unroll") for (int m = 0; m < 4; ++m) _Pragma("unroll") for (int k = 0; k < 2; ++k) dst[m][k] = *(const PG8_LAS bf16x8*)(lds + PG8_SA(b, h) + aoff + m * 2048 + k * 1024); } while (0)
; #define PG8_LDB(dst, b, h) do { _Pragma("unroll") for (int n = 0; n < 2; ++n) _Pragma("unroll") for (int k = 0; k < 2; ++k) dst[n][k] = *(const PG8_LAS bf16x8*)(lds + PG8_SB(b, h) + boff + n * 2048 + k * 1024); } while (0)
; #define PG8_MMA(ai, bj, At, Bt) do { __builtin_amdgcn_s_setprio(1); _Pragma("unroll") for (int m = 0; m < 4; ++m) _Pragma("unroll") for (int n = 0; n < 2; ++n) _Pragma("unroll") for (int k = 0; k < 2; ++k) \
;         acc[ai][bj][m][n] = __builtin_amdgcn_mfma_f32_16x16x32_bf16(Bt[n][k], At[m][k], acc[ai][bj][m][n], 0, 0, 0); __builtin_amdgcn_s_setprio(0); } while (0)
; #define PG8_WAIT_V(n) asm volatile("s_waitcnt vmcnt(" #n ")" ::: "memory")
; template <class Epi, class Sched, bool ALIGN_EPI = false, bool SP2 = false>
; __device__ __forceinline__ void gemm_phase(PG8_LAS unsigned char* lds, const Gemm g, const Sched& S, const Epi& E) {
;     ...
;         for (int t = 0; t < nt; t += 2) {
;             const bool last = (t == nt - 2);
;             const char* a1 = cA + (size_t)(t + 1) * kstep;
;             const char* a2 = last ? nA : cA + (size_t)(t + 2) * kstep; const char* b2 = last ? nB : cB + (size_t)(t + 2) * kstep;
;             const char* a3 = a2 + kstep; const char* b3 = b2 + kstep;
;             if (last && has_next) S.a_ready(nxt);
;             if constexpr (SP2) {
;             PG8_LDB(B0, 0, 0); PG8_LDB(B1, 0, 1); PG8_SCHED; PG8_LDA(At, 0, 0); PG8_STAGE(PG8_SA(1, 1), a1 + hstep, voffA);
;             PG8_WAIT_V(8); PG8_WAIT_L(0); PG8_BAR; PG8_MMA(0, 0, At, B0); PG8_MMA(0, 1, At, B1); PG8_BAR; PG8_SCHED;
;     ...
; #pragma unroll
;         for (int a = 0; a < 2; ++a)
; #pragma unroll
;             for (int b = 0; b < 2; ++b)
; #pragma unroll
;                 for (int m = 0; m < 4; ++m)
; #pragma unroll
;                     for (int n = 0; n < 2; ++n) acc[a][b][m][n] = (f32x4){0.f, 0.f, 0.f, 0.f};
;         cur = nxt; cA = nA; cB = nB; ++ui;
.LBB0_2189:
	s_ashr_i32 s13, s12, 31
	s_lshl_b64 s[14:15], s[12:13], 19
	v_readlane_b32 s16, v240, 5
	v_readlane_b32 s17, v240, 6
	s_add_u32 s14, s16, s14
	s_addc_u32 s15, s17, s15
	s_and_b64 s[16:17], s[4:5], exec
	s_cselect_b32 s13, s15, s21
	s_cselect_b32 s46, s14, s20
	s_ashr_i32 s11, s10, 31
	s_lshl_b64 s[16:17], s[10:11], 19
	s_add_u32 s16, s26, s16
	s_addc_u32 s17, s27, s17
	s_and_b64 s[24:25], s[4:5], exec
	s_cselect_b32 s11, s17, s23
	s_cselect_b32 s47, s16, s22
	s_add_u32 s20, s20, 0x40080
	s_addc_u32 s21, s21, 0
	s_add_u32 s48, s22, 0x100
	v_mov_b32_e32 v0, 0
	s_addc_u32 s49, s23, 0
	s_mov_b32 s50, -2
	v_mov_b32_e32 v1, 0
	v_mov_b64_e32 v[2:3], 0
	v_mov_b64_e32 v[4:5], 0
	v_mov_b64_e32 v[6:7], 0
	v_mov_b64_e32 v[8:9], 0
	v_mov_b64_e32 v[10:11], 0
	v_mov_b64_e32 v[12:13], 0
	v_mov_b64_e32 v[14:15], 0
	v_mov_b64_e32 v[16:17], 0
	v_mov_b64_e32 v[18:19], 0
	v_mov_b64_e32 v[20:21], 0
	v_mov_b64_e32 v[22:23], 0
	v_mov_b64_e32 v[24:25], 0
	v_mov_b64_e32 v[26:27], 0
	v_mov_b64_e32 v[28:29], 0
	v_mov_b64_e32 v[30:31], 0
	v_mov_b64_e32 v[32:33], 0
	v_mov_b64_e32 v[34:35], 0
	v_mov_b64_e32 v[36:37], 0
	v_mov_b64_e32 v[38:39], 0
	v_mov_b64_e32 v[40:41], 0
	v_mov_b64_e32 v[42:43], 0
	v_mov_b64_e32 v[44:45], 0
	v_mov_b64_e32 v[46:47], 0
	v_mov_b64_e32 v[48:49], 0
	v_mov_b64_e32 v[50:51], 0
	v_mov_b64_e32 v[52:53], 0
	v_mov_b64_e32 v[54:55], 0
	v_mov_b64_e32 v[56:57], 0
	v_mov_b64_e32 v[58:59], 0
	v_mov_b64_e32 v[60:61], 0
	v_mov_b64_e32 v[62:63], 0
	v_mov_b64_e32 v[64:65], 0
	v_mov_b64_e32 v[66:67], 0
	v_mov_b64_e32 v[68:69], 0
	v_mov_b64_e32 v[70:71], 0
	v_mov_b64_e32 v[72:73], 0
	v_mov_b64_e32 v[74:75], 0
	v_mov_b64_e32 v[76:77], 0
	v_mov_b64_e32 v[78:79], 0
	v_mov_b64_e32 v[80:81], 0
	v_mov_b64_e32 v[82:83], 0
	v_mov_b64_e32 v[84:85], 0
	v_mov_b64_e32 v[86:87], 0
	v_mov_b64_e32 v[88:89], 0
	v_mov_b64_e32 v[90:91], 0
	v_mov_b64_e32 v[92:93], 0
	v_mov_b64_e32 v[94:95], 0
	v_mov_b64_e32 v[96:97], 0
	v_mov_b64_e32 v[98:99], 0
	v_mov_b64_e32 v[100:101], 0
	v_mov_b64_e32 v[102:103], 0
	v_mov_b64_e32 v[104:105], 0
	v_mov_b64_e32 v[106:107], 0
	v_mov_b64_e32 v[108:109], 0
	v_mov_b64_e32 v[110:111], 0
	v_mov_b64_e32 v[112:113], 0
	v_mov_b64_e32 v[114:115], 0
	v_mov_b64_e32 v[116:117], 0
	v_mov_b64_e32 v[118:119], 0
	v_mov_b64_e32 v[120:121], 0
	v_mov_b64_e32 v[122:123], 0
	v_mov_b64_e32 v[124:125], 0
	v_mov_b64_e32 v[126:127], 0
	s_branch .Lz64_6
	s_nop 0
	s_nop 0
	s_nop 0
	s_nop 0
	s_nop 0
	s_nop 0
	s_nop 0
	s_nop 0
	s_nop 0
	s_nop 0
	s_nop 0
	s_nop 0
	s_nop 0
	s_nop 0
	s_nop 0
	s_nop 0
	s_nop 0
	s_nop 0
	s_nop 0
	s_nop 0
	s_nop 0
	s_nop 0
	s_nop 0
	s_nop 0
	s_nop 0
	s_nop 0
	s_nop 0
	s_nop 0
	s_nop 0
	s_nop 0
	s_nop 0
	s_nop 0
	s_nop 0
	s_nop 0
	s_nop 0
	s_nop 0
	s_nop 0
	s_nop 0
	s_nop 0
	s_nop 0
	s_nop 0
	s_nop 0
	s_nop 0
	s_nop 0
	s_nop 0
	s_nop 0
	s_nop 0
	s_nop 0
	s_nop 0
	s_nop 0
	s_nop 0
	s_nop 0
	s_nop 0
	s_nop 0
	s_nop 0
	s_nop 0
	s_nop 0
	s_nop 0
	s_nop 0
	s_nop 0
	s_nop 0
	s_nop 0
.Lz64_6:
.LBB0_2190:
	ds_read_b128 v[154:157], v149
	ds_read_b128 v[158:161], v149 offset:1024
	ds_read_b128 v[162:165], v149 offset:2048
	ds_read_b128 v[166:169], v149 offset:3072
	ds_read_b128 v[170:173], v150
	ds_read_b128 v[174:177], v150 offset:1024
	ds_read_b128 v[178:181], v150 offset:2048
	ds_read_b128 v[182:185], v150 offset:3072
	s_add_u32 s22, s20, 0xfffc0080
	s_addc_u32 s23, s21, -1
	s_cmp_eq_u32 s50, 12
	s_cselect_b32 s25, s13, s23
	s_cselect_b32 s24, s46, s22
	s_cselect_b32 s23, s11, s49
	s_cselect_b32 s22, s47, s48
	v_lshl_add_u64 v[146:147], s[20:21], 0, v[136:137]
	s_add_i32 m0, s19, 0xc000
	ds_read_b128 v[186:189], v151
	ds_read_b128 v[190:193], v151 offset:1024
	ds_read_b128 v[194:197], v151 offset:2048
	ds_read_b128 v[198:201], v151 offset:3072
	ds_read_b128 v[202:205], v151 offset:4096
	ds_read_b128 v[206:209], v151 offset:5120
	ds_read_b128 v[210:213], v151 offset:6144
	ds_read_b128 v[214:217], v151 offset:7168
	global_load_lds_dwordx4 v[146:147], off
	v_lshl_add_u64 v[146:147], s[20:21], 0, v[138:139]
	s_add_i32 m0, s19, 0xe000
	s_nop 0
	global_load_lds_dwordx4 v[146:147], off
	s_waitcnt vmcnt(8)
	s_waitcnt lgkmcnt(0)
	s_barrier
	s_setprio 1
	s_waitcnt lgkmcnt(0)
	v_mfma_f32_16x16x32_bf16 v[124:127], v[154:157], v[186:189], v[124:127]
	v_mfma_f32_16x16x32_bf16 v[120:123], v[162:165], v[186:189], v[120:123]
	v_mfma_f32_16x16x32_bf16 v[108:111], v[154:157], v[194:197], v[108:111]
	v_mfma_f32_16x16x32_bf16 v[104:107], v[162:165], v[194:197], v[104:107]
	v_mfma_f32_16x16x32_bf16 v[92:95], v[154:157], v[202:205], v[92:95]
	v_mfma_f32_16x16x32_bf16 v[88:91], v[162:165], v[202:205], v[88:91]
	v_mfma_f32_16x16x32_bf16 v[76:79], v[154:157], v[210:213], v[76:79]
	v_mfma_f32_16x16x32_bf16 v[72:75], v[162:165], v[210:213], v[72:75]
	v_mfma_f32_16x16x32_bf16 v[124:127], v[158:161], v[190:193], v[124:127]
	v_mfma_f32_16x16x32_bf16 v[120:123], v[166:169], v[190:193], v[120:123]
	v_mfma_f32_16x16x32_bf16 v[108:111], v[158:161], v[198:201], v[108:111]
	v_mfma_f32_16x16x32_bf16 v[104:107], v[166:169], v[198:201], v[104:107]
	v_mfma_f32_16x16x32_bf16 v[92:95], v[158:161], v[206:209], v[92:95]
	v_mfma_f32_16x16x32_bf16 v[88:91], v[166:169], v[206:209], v[88:91]
	v_mfma_f32_16x16x32_bf16 v[76:79], v[158:161], v[214:217], v[76:79]
	v_mfma_f32_16x16x32_bf16 v[72:75], v[166:169], v[214:217], v[72:75]
	s_setprio 0
	s_setprio 1
	v_mfma_f32_16x16x32_bf16 v[116:119], v[170:173], v[186:189], v[116:119]
	v_mfma_f32_16x16x32_bf16 v[112:115], v[178:181], v[186:189], v[112:115]
	v_mfma_f32_16x16x32_bf16 v[100:103], v[170:173], v[194:197], v[100:103]
	v_mfma_f32_16x16x32_bf16 v[96:99], v[178:181], v[194:197], v[96:99]
	v_mfma_f32_16x16x32_bf16 v[84:87], v[170:173], v[202:205], v[84:87]
	v_mfma_f32_16x16x32_bf16 v[80:83], v[178:181], v[202:205], v[80:83]
	v_mfma_f32_16x16x32_bf16 v[68:71], v[170:173], v[210:213], v[68:71]
	v_mfma_f32_16x16x32_bf16 v[64:67], v[178:181], v[210:213], v[64:67]
	v_mfma_f32_16x16x32_bf16 v[116:119], v[174:177], v[190:193], v[116:119]
	v_mfma_f32_16x16x32_bf16 v[112:115], v[182:185], v[190:193], v[112:115]
	v_mfma_f32_16x16x32_bf16 v[100:103], v[174:177], v[198:201], v[100:103]
	v_mfma_f32_16x16x32_bf16 v[96:99], v[182:185], v[198:201], v[96:99]
	v_mfma_f32_16x16x32_bf16 v[84:87], v[174:177], v[206:209], v[84:87]
	v_mfma_f32_16x16x32_bf16 v[80:83], v[182:185], v[206:209], v[80:83]
	v_mfma_f32_16x16x32_bf16 v[68:71], v[174:177], v[214:217], v[68:71]
	v_mfma_f32_16x16x32_bf16 v[64:67], v[182:185], v[214:217], v[64:67]
	s_setprio 0
	s_barrier
; #define PG8_STAGE(bufoff, gbase, voff) do { _Pragma("unroll") for (int _i = 0; _i < 2; ++_i) \
;         __builtin_amdgcn_global_load_lds((const unsigned*)((const char*)(gbase) + (voff)[_i]), (PG8_LAS unsigned*)(lds + (bufoff) + ldsw + _i * 8192), 16, 0, 0); } while (0)
; #define PG8_LDA(dst, b, h) do { _Pragma("unroll") for (int m = 0; m < 4; ++m) _Pragma("unroll") for (int k = 0; k < 2; ++k) dst[m][k] = *(const PG8_LAS bf16x8*)(lds + PG8_SA(b, h) + aoff + m * 2048 + k * 1024); } while (0)
; #define PG8_LDB(dst, b, h) do { _Pragma("unroll") for (int n = 0; n < 2; ++n) _Pragma("unroll") for (int k = 0; k < 2; ++k) dst[n][k] = *(const PG8_LAS bf16x8*)(lds + PG8_SB(b, h) + boff + n * 2048 + k * 1024); } while (0)
; #define PG8_MMA(ai, bj, At, Bt) do { __builtin_amdgcn_s_setprio(1); _Pragma("unroll") for (int m = 0; m < 4; ++m) _Pragma("unroll") for (int n = 0; n < 2; ++n) _Pragma("unroll") for (int k = 0; k < 2; ++k) \
;         acc[ai][bj][m][n] = __builtin_amdgcn_mfma_f32_16x16x32_bf16(Bt[n][k], At[m][k], acc[ai][bj][m][n], 0, 0, 0); __builtin_amdgcn_s_setprio(0); } while (0)
; #define PG8_WAIT_V(n) asm volatile("s_waitcnt vmcnt(" #n ")" ::: "memory")
; #define PG8_WAIT_L(n) asm volatile("s_waitcnt lgkmcnt(" #n ")" ::: "memory")
; #define PG8_BAR __builtin_amdgcn_s_barrier()
; #define PG8_SCHED __builtin_amdgcn_sched_barrier(0)
; template <class Epi, class Sched, bool ALIGN_EPI = false, bool SP2 = false>
; __device__ __forceinline__ void gemm_phase(PG8_LAS unsigned char* lds, const Gemm g, const Sched& S, const Epi& E) {
;     ...
;             PG8_LDA(At, 0, 1); PG8_STAGE(PG8_SB(0, 0), b2, voffB); PG8_STAGE(PG8_SB(0, 1), b2 + hstep, voffB); PG8_STAGE(PG8_SA(0, 0), a2, voffA);
;             PG8_WAIT_V(8); PG8_WAIT_L(0); PG8_BAR; PG8_MMA(1, 0, At, B0); PG8_MMA(1, 1, At, B1); PG8_BAR; PG8_SCHED;
;             PG8_LDB(B0, 1, 0); PG8_LDB(B1, 1, 1); PG8_SCHED; PG8_LDA(At, 1, 0); PG8_STAGE(PG8_SA(0, 1), a2 + hstep, voffA);
;             PG8_WAIT_V(8); PG8_WAIT_L(0); PG8_BAR; PG8_MMA(0, 0, At, B0); PG8_MMA(0, 1, At, B1); PG8_BAR; PG8_SCHED;
	s_add_i32 s51, s41, s28
	v_lshl_add_u64 v[146:147], s[22:23], 0, v[132:133]
	s_mov_b32 m0, s51
	ds_read_b128 v[186:189], v151 offset:16384
	ds_read_b128 v[190:193], v151 offset:17408
	ds_read_b128 v[194:197], v151 offset:18432
	ds_read_b128 v[198:201], v151 offset:19456
	ds_read_b128 v[202:205], v151 offset:20480
	ds_read_b128 v[206:209], v151 offset:21504
	ds_read_b128 v[210:213], v151 offset:22528
	ds_read_b128 v[214:217], v151 offset:23552
	global_load_lds_dwordx4 v[146:147], off
	s_add_i32 m0, s51, 0x2000
	s_add_u32 s52, s22, 0x40000
	v_lshl_add_u64 v[218:219], s[22:23], 0, v[128:129]
	s_addc_u32 s53, s23, 0
	s_add_i32 s51, s42, s28
	global_load_lds_dwordx4 v[218:219], off
	v_lshl_add_u64 v[220:221], s[52:53], 0, v[132:133]
	s_mov_b32 m0, s51
	v_lshl_add_u64 v[222:223], s[24:25], 0, v[130:131]
	global_load_lds_dwordx4 v[220:221], off
	v_lshl_add_u64 v[220:221], s[52:53], 0, v[128:129]
	s_add_i32 m0, s51, 0x2000
	s_nop 0
	global_load_lds_dwordx4 v[220:221], off
	v_lshl_add_u64 v[220:221], s[24:25], 0, v[134:135]
	s_mov_b32 m0, s19
	s_nop 0
	global_load_lds_dwordx4 v[220:221], off
	s_mov_b32 m0, s31
	s_nop 0
	global_load_lds_dwordx4 v[222:223], off
	s_waitcnt vmcnt(8)
	s_waitcnt lgkmcnt(0)
	s_barrier
	s_setprio 1
	s_waitcnt lgkmcnt(0)
	v_mfma_f32_16x16x32_bf16 v[60:63], v[154:157], v[186:189], v[60:63]
	v_mfma_f32_16x16x32_bf16 v[56:59], v[162:165], v[186:189], v[56:59]
	v_mfma_f32_16x16x32_bf16 v[44:47], v[154:157], v[194:197], v[44:47]
	v_mfma_f32_16x16x32_bf16 v[40:43], v[162:165], v[194:197], v[40:43]
	v_mfma_f32_16x16x32_bf16 v[28:31], v[154:157], v[202:205], v[28:31]
	v_mfma_f32_16x16x32_bf16 v[24:27], v[162:165], v[202:205], v[24:27]
	v_mfma_f32_16x16x32_bf16 v[12:15], v[154:157], v[210:213], v[12:15]
	v_mfma_f32_16x16x32_bf16 v[8:11], v[162:165], v[210:213], v[8:11]
	v_mfma_f32_16x16x32_bf16 v[60:63], v[158:161], v[190:193], v[60:63]
	v_mfma_f32_16x16x32_bf16 v[56:59], v[166:169], v[190:193], v[56:59]
	v_mfma_f32_16x16x32_bf16 v[44:47], v[158:161], v[198:201], v[44:47]
	v_mfma_f32_16x16x32_bf16 v[40:43], v[166:169], v[198:201], v[40:43]
	v_mfma_f32_16x16x32_bf16 v[28:31], v[158:161], v[206:209], v[28:31]
	v_mfma_f32_16x16x32_bf16 v[24:27], v[166:169], v[206:209], v[24:27]
	v_mfma_f32_16x16x32_bf16 v[12:15], v[158:161], v[214:217], v[12:15]
	v_mfma_f32_16x16x32_bf16 v[8:11], v[166:169], v[214:217], v[8:11]
	s_setprio 0
	s_setprio 1
	v_mfma_f32_16x16x32_bf16 v[52:55], v[170:173], v[186:189], v[52:55]
	v_mfma_f32_16x16x32_bf16 v[48:51], v[178:181], v[186:189], v[48:51]
	v_mfma_f32_16x16x32_bf16 v[36:39], v[170:173], v[194:197], v[36:39]
	v_mfma_f32_16x16x32_bf16 v[32:35], v[178:181], v[194:197], v[32:35]
	v_mfma_f32_16x16x32_bf16 v[20:23], v[170:173], v[202:205], v[20:23]
	v_mfma_f32_16x16x32_bf16 v[16:19], v[178:181], v[202:205], v[16:19]
	v_mfma_f32_16x16x32_bf16 v[4:7], v[170:173], v[210:213], v[4:7]
	v_mfma_f32_16x16x32_bf16 v[0:3], v[178:181], v[210:213], v[0:3]
	v_mfma_f32_16x16x32_bf16 v[52:55], v[174:177], v[190:193], v[52:55]
	v_mfma_f32_16x16x32_bf16 v[48:51], v[182:185], v[190:193], v[48:51]
	v_mfma_f32_16x16x32_bf16 v[36:39], v[174:177], v[198:201], v[36:39]
	v_mfma_f32_16x16x32_bf16 v[32:35], v[182:185], v[198:201], v[32:35]
	v_mfma_f32_16x16x32_bf16 v[20:23], v[174:177], v[206:209], v[20:23]
	v_mfma_f32_16x16x32_bf16 v[16:19], v[182:185], v[206:209], v[16:19]
	v_mfma_f32_16x16x32_bf16 v[4:7], v[174:177], v[214:217], v[4:7]
	v_mfma_f32_16x16x32_bf16 v[0:3], v[182:185], v[214:217], v[0:3]
	s_setprio 0
	s_barrier
	ds_read_b128 v[154:157], v152
	ds_read_b128 v[158:161], v152 offset:1024
	ds_read_b128 v[162:165], v152 offset:2048
	ds_read_b128 v[166:169], v152 offset:3072
	ds_read_b128 v[170:173], v153
	ds_read_b128 v[174:177], v153 offset:1024
	ds_read_b128 v[178:181], v153 offset:2048
	ds_read_b128 v[182:185], v153 offset:3072
	s_add_u32 s24, s24, 0x40000
	s_addc_u32 s25, s25, 0
	s_mov_b32 m0, s34
	v_lshl_add_u64 v[224:225], s[24:25], 0, v[134:135]
	ds_read_b128 v[186:189], v151 offset:32768
	ds_read_b128 v[190:193], v151 offset:33792
	ds_read_b128 v[194:197], v151 offset:34816
	ds_read_b128 v[198:201], v151 offset:35840
	ds_read_b128 v[202:205], v151 offset:36864
	ds_read_b128 v[206:209], v151 offset:37888
	ds_read_b128 v[210:213], v151 offset:38912
	ds_read_b128 v[214:217], v151 offset:39936
	global_load_lds_dwordx4 v[224:225], off
	v_lshl_add_u64 v[224:225], s[24:25], 0, v[130:131]
	s_mov_b32 m0, s35
	s_nop 0
	global_load_lds_dwordx4 v[224:225], off
	s_waitcnt vmcnt(8)
	s_waitcnt lgkmcnt(0)
	s_barrier
; #define PG8_STAGE(bufoff, gbase, voff) do { _Pragma("unroll") for (int _i = 0; _i < 2; ++_i) \
;         __builtin_amdgcn_global_load_lds((const unsigned*)((const char*)(gbase) + (voff)[_i]), (PG8_LAS unsigned*)(lds + (bufoff) + ldsw + _i * 8192), 16, 0, 0); } while (0)
; #define PG8_LDA(dst, b, h) do { _Pragma("unroll") for (int m = 0; m < 4; ++m) _Pragma("unroll") for (int k = 0; k < 2; ++k) dst[m][k] = *(const PG8_LAS bf16x8*)(lds + PG8_SA(b, h) + aoff + m * 2048 + k * 1024); } while (0)
; #define PG8_MMA(ai, bj, At, Bt) do { __builtin_amdgcn_s_setprio(1); _Pragma("unroll") for (int m = 0; m < 4; ++m) _Pragma("unroll") for (int n = 0; n < 2; ++n) _Pragma("unroll") for (int k = 0; k < 2; ++k) \
;         acc[ai][bj][m][n] = __builtin_amdgcn_mfma_f32_16x16x32_bf16(Bt[n][k], At[m][k], acc[ai][bj][m][n], 0, 0, 0); __builtin_amdgcn_s_setprio(0); } while (0)
; #define PG8_WAIT_V(n) asm volatile("s_waitcnt vmcnt(" #n ")" ::: "memory")
; #define PG8_WAIT_L(n) asm volatile("s_waitcnt lgkmcnt(" #n ")" ::: "memory")
; #define PG8_BAR __builtin_amdgcn_s_barrier()
; #define PG8_SCHED __builtin_amdgcn_sched_barrier(0)
; template <class Epi, class Sched, bool ALIGN_EPI = false, bool SP2 = false>
; __device__ __forceinline__ void gemm_phase(PG8_LAS unsigned char* lds, const Gemm g, const Sched& S, const Epi& E) {
;     ...
;             PG8_WAIT_V(8); PG8_WAIT_L(0); PG8_BAR; PG8_MMA(0, 0, At, B0); PG8_MMA(0, 1, At, B1); PG8_BAR; PG8_SCHED;
;             PG8_LDA(At, 1, 1); PG8_STAGE(PG8_SB(1, 0), b3, voffB); PG8_STAGE(PG8_SB(1, 1), b3 + hstep, voffB); PG8_STAGE(PG8_SA(1, 0), a3, voffA);
;             PG8_WAIT_V(8); PG8_WAIT_L(0); PG8_BAR; PG8_MMA(1, 0, At, B0); PG8_MMA(1, 1, At, B1); PG8_BAR; PG8_SCHED;
	s_setprio 1
	s_waitcnt lgkmcnt(0)
	v_mfma_f32_16x16x32_bf16 v[124:127], v[154:157], v[186:189], v[124:127]
	v_mfma_f32_16x16x32_bf16 v[120:123], v[162:165], v[186:189], v[120:123]
	v_mfma_f32_16x16x32_bf16 v[108:111], v[154:157], v[194:197], v[108:111]
	v_mfma_f32_16x16x32_bf16 v[104:107], v[162:165], v[194:197], v[104:107]
	v_mfma_f32_16x16x32_bf16 v[92:95], v[154:157], v[202:205], v[92:95]
	v_mfma_f32_16x16x32_bf16 v[88:91], v[162:165], v[202:205], v[88:91]
	v_mfma_f32_16x16x32_bf16 v[76:79], v[154:157], v[210:213], v[76:79]
	v_mfma_f32_16x16x32_bf16 v[72:75], v[162:165], v[210:213], v[72:75]
	v_mfma_f32_16x16x32_bf16 v[124:127], v[158:161], v[190:193], v[124:127]
	v_mfma_f32_16x16x32_bf16 v[120:123], v[166:169], v[190:193], v[120:123]
	v_mfma_f32_16x16x32_bf16 v[108:111], v[158:161], v[198:201], v[108:111]
	v_mfma_f32_16x16x32_bf16 v[104:107], v[166:169], v[198:201], v[104:107]
	v_mfma_f32_16x16x32_bf16 v[92:95], v[158:161], v[206:209], v[92:95]
	v_mfma_f32_16x16x32_bf16 v[88:91], v[166:169], v[206:209], v[88:91]
	v_mfma_f32_16x16x32_bf16 v[76:79], v[158:161], v[214:217], v[76:79]
	v_mfma_f32_16x16x32_bf16 v[72:75], v[166:169], v[214:217], v[72:75]
	s_setprio 0
	s_setprio 1
	v_mfma_f32_16x16x32_bf16 v[116:119], v[170:173], v[186:189], v[116:119]
	v_mfma_f32_16x16x32_bf16 v[112:115], v[178:181], v[186:189], v[112:115]
	v_mfma_f32_16x16x32_bf16 v[100:103], v[170:173], v[194:197], v[100:103]
	v_mfma_f32_16x16x32_bf16 v[96:99], v[178:181], v[194:197], v[96:99]
	v_mfma_f32_16x16x32_bf16 v[84:87], v[170:173], v[202:205], v[84:87]
	v_mfma_f32_16x16x32_bf16 v[80:83], v[178:181], v[202:205], v[80:83]
	v_mfma_f32_16x16x32_bf16 v[68:71], v[170:173], v[210:213], v[68:71]
	v_mfma_f32_16x16x32_bf16 v[64:67], v[178:181], v[210:213], v[64:67]
	v_mfma_f32_16x16x32_bf16 v[116:119], v[174:177], v[190:193], v[116:119]
	v_mfma_f32_16x16x32_bf16 v[112:115], v[182:185], v[190:193], v[112:115]
	v_mfma_f32_16x16x32_bf16 v[100:103], v[174:177], v[198:201], v[100:103]
	v_mfma_f32_16x16x32_bf16 v[96:99], v[182:185], v[198:201], v[96:99]
	v_mfma_f32_16x16x32_bf16 v[84:87], v[174:177], v[206:209], v[84:87]
	v_mfma_f32_16x16x32_bf16 v[80:83], v[182:185], v[206:209], v[80:83]
	v_mfma_f32_16x16x32_bf16 v[68:71], v[174:177], v[214:217], v[68:71]
	v_mfma_f32_16x16x32_bf16 v[64:67], v[182:185], v[214:217], v[64:67]
	s_setprio 0
	s_barrier
	s_add_i32 s24, s44, s28
	v_lshl_add_u64 v[146:147], v[146:147], 0, s[2:3]
	s_mov_b32 m0, s24
	ds_read_b128 v[186:189], v151 offset:49152
	ds_read_b128 v[190:193], v151 offset:50176
	ds_read_b128 v[194:197], v151 offset:51200
	ds_read_b128 v[198:201], v151 offset:52224
	ds_read_b128 v[202:205], v151 offset:53248
	ds_read_b128 v[206:209], v151 offset:54272
	ds_read_b128 v[210:213], v151 offset:55296
	ds_read_b128 v[214:217], v151 offset:56320
	global_load_lds_dwordx4 v[146:147], off
	s_add_i32 m0, s24, 0x2000
	s_add_u32 s22, s22, 0x40080
	v_lshl_add_u64 v[146:147], v[218:219], 0, s[2:3]
	s_addc_u32 s23, s23, 0
	s_add_i32 s24, s45, s28
	global_load_lds_dwordx4 v[146:147], off
	v_lshl_add_u64 v[146:147], s[22:23], 0, v[132:133]
	s_mov_b32 m0, s24
	s_nop 0
	global_load_lds_dwordx4 v[146:147], off
	v_lshl_add_u64 v[146:147], s[22:23], 0, v[128:129]
	s_add_i32 m0, s24, 0x2000
	s_nop 0
	global_load_lds_dwordx4 v[146:147], off
	v_lshl_add_u64 v[146:147], v[220:221], 0, s[2:3]
	s_mov_b32 m0, s37
	s_nop 0
	global_load_lds_dwordx4 v[146:147], off
	v_lshl_add_u64 v[146:147], v[222:223], 0, s[2:3]
	s_mov_b32 m0, s38
	s_nop 0
	global_load_lds_dwordx4 v[146:147], off
	s_waitcnt vmcnt(8)
	s_waitcnt lgkmcnt(0)
	s_barrier
	s_setprio 1
	s_waitcnt lgkmcnt(0)
	v_mfma_f32_16x16x32_bf16 v[60:63], v[154:157], v[186:189], v[60:63]
	v_mfma_f32_16x16x32_bf16 v[56:59], v[162:165], v[186:189], v[56:59]
	v_mfma_f32_16x16x32_bf16 v[44:47], v[154:157], v[194:197], v[44:47]
	v_mfma_f32_16x16x32_bf16 v[40:43], v[162:165], v[194:197], v[40:43]
	v_mfma_f32_16x16x32_bf16 v[28:31], v[154:157], v[202:205], v[28:31]
	v_mfma_f32_16x16x32_bf16 v[24:27], v[162:165], v[202:205], v[24:27]
	v_mfma_f32_16x16x32_bf16 v[12:15], v[154:157], v[210:213], v[12:15]
	v_mfma_f32_16x16x32_bf16 v[8:11], v[162:165], v[210:213], v[8:11]
	v_mfma_f32_16x16x32_bf16 v[60:63], v[158:161], v[190:193], v[60:63]
	v_mfma_f32_16x16x32_bf16 v[56:59], v[166:169], v[190:193], v[56:59]
	v_mfma_f32_16x16x32_bf16 v[44:47], v[158:161], v[198:201], v[44:47]
	v_mfma_f32_16x16x32_bf16 v[40:43], v[166:169], v[198:201], v[40:43]
	v_mfma_f32_16x16x32_bf16 v[28:31], v[158:161], v[206:209], v[28:31]
	v_mfma_f32_16x16x32_bf16 v[24:27], v[166:169], v[206:209], v[24:27]
	v_mfma_f32_16x16x32_bf16 v[12:15], v[158:161], v[214:217], v[12:15]
	v_mfma_f32_16x16x32_bf16 v[8:11], v[166:169], v[214:217], v[8:11]
	s_setprio 0
	s_setprio 1
	v_mfma_f32_16x16x32_bf16 v[52:55], v[170:173], v[186:189], v[52:55]
	v_mfma_f32_16x16x32_bf16 v[48:51], v[178:181], v[186:189], v[48:51]
	v_mfma_f32_16x16x32_bf16 v[36:39], v[170:173], v[194:197], v[36:39]
	v_mfma_f32_16x16x32_bf16 v[32:35], v[178:181], v[194:197], v[32:35]
	v_mfma_f32_16x16x32_bf16 v[20:23], v[170:173], v[202:205], v[20:23]
	v_mfma_f32_16x16x32_bf16 v[16:19], v[178:181], v[202:205], v[16:19]
	v_mfma_f32_16x16x32_bf16 v[4:7], v[170:173], v[210:213], v[4:7]
	v_mfma_f32_16x16x32_bf16 v[0:3], v[178:181], v[210:213], v[0:3]
	v_mfma_f32_16x16x32_bf16 v[52:55], v[174:177], v[190:193], v[52:55]
	v_mfma_f32_16x16x32_bf16 v[48:51], v[182:185], v[190:193], v[48:51]
	v_mfma_f32_16x16x32_bf16 v[36:39], v[174:177], v[198:201], v[36:39]
	v_mfma_f32_16x16x32_bf16 v[32:35], v[182:185], v[198:201], v[32:35]
	v_mfma_f32_16x16x32_bf16 v[20:23], v[174:177], v[206:209], v[20:23]
	v_mfma_f32_16x16x32_bf16 v[16:19], v[182:185], v[206:209], v[16:19]
	v_mfma_f32_16x16x32_bf16 v[4:7], v[174:177], v[214:217], v[4:7]
	v_mfma_f32_16x16x32_bf16 v[0:3], v[182:185], v[214:217], v[0:3]
	s_setprio 0
	s_barrier
	s_add_i32 s50, s50, 2
	s_add_u32 s20, s20, 0x100
	s_addc_u32 s21, s21, 0
	s_add_u32 s48, s48, 0x100
	s_addc_u32 s49, s49, 0
	s_cmp_gt_u32 s50, 13
	s_cbranch_scc0 .LBB0_2190
	s_and_b64 vcc, exec, s[8:9]
	s_cbranch_vccz .LBB0_2193
	s_barrier

; #define PG8_STAGE(bufoff, gbase, voff) do { _Pragma("unroll") for (int _i = 0; _i < 2; ++_i) \
;         __builtin_amdgcn_global_load_lds((const unsigned*)((const char*)(gbase) + (voff)[_i]), (PG8_LAS unsigned*)(lds + (bufoff) + ldsw + _i * 8192), 16, 0, 0); } while (0)
; #define PG8_LDA(dst, b, h) do { _Pragma("unroll") for (int m = 0; m < 4; ++m) _Pragma("unroll") for (int k = 0; k < 2; ++k) dst[m][k] = *(const PG8_LAS bf16x8*)(lds + PG8_SA(b, h) + aoff + m * 2048 + k * 1024); } while (0)
; #define PG8_LDB(dst, b, h) do { _Pragma("unroll") for (int n = 0; n < 2; ++n) _Pragma("unroll") for (int k = 0; k < 2; ++k) dst[n][k] = *(const PG8_LAS bf16x8*)(lds + PG8_SB(b, h) + boff + n * 2048 + k * 1024); } while (0)
; #define PG8_MMA(ai, bj, At, Bt) do { __builtin_amdgcn_s_setprio(1); _Pragma("unroll") for (int m = 0; m < 4; ++m) _Pragma("unroll") for (int n = 0; n < 2; ++n) _Pragma("unroll") for (int k = 0; k < 2; ++k) \
;         acc[ai][bj][m][n] = __builtin_amdgcn_mfma_f32_16x16x32_bf16(Bt[n][k], At[m][k], acc[ai][bj][m][n], 0, 0, 0); __builtin_amdgcn_s_setprio(0); } while (0)
; #define PG8_WAIT_V(n) asm volatile("s_waitcnt vmcnt(" #n ")" ::: "memory")
; template <class Epi, class Sched, bool ALIGN_EPI = false, bool SP2 = false>
; __device__ __forceinline__ void gemm_phase(PG8_LAS unsigned char* lds, const Gemm g, const Sched& S, const Epi& E) {
;     ...
;         for (int t = 0; t < nt; t += 2) {
;             const bool last = (t == nt - 2);
;             const char* a1 = cA + (size_t)(t + 1) * kstep;
;             const char* a2 = last ? nA : cA + (size_t)(t + 2) * kstep; const char* b2 = last ? nB : cB + (size_t)(t + 2) * kstep;
;             const char* a3 = a2 + kstep; const char* b3 = b2 + kstep;
;             if (last && has_next) S.a_ready(nxt);
;             if constexpr (SP2) {
;             PG8_LDB(B0, 0, 0); PG8_LDB(B1, 0, 1); PG8_SCHED; PG8_LDA(At, 0, 0); PG8_STAGE(PG8_SA(1, 1), a1 + hstep, voffA);
;             PG8_WAIT_V(8); PG8_WAIT_L(0); PG8_BAR; PG8_MMA(0, 0, At, B0); PG8_MMA(0, 1, At, B1); PG8_BAR; PG8_SCHED;
;     ...
; #pragma unroll
;         for (int a = 0; a < 2; ++a)
; #pragma unroll
;             for (int b = 0; b < 2; ++b)
; #pragma unroll
;                 for (int m = 0; m < 4; ++m)
; #pragma unroll
;                     for (int n = 0; n < 2; ++n) acc[a][b][m][n] = (f32x4){0.f, 0.f, 0.f, 0.f};
;         cur = nxt; cA = nA; cB = nB; ++ui;
.LBB0_2270:
	s_add_u32 s24, s24, 0xb0080
	s_addc_u32 s25, s25, 0
	s_add_u32 s53, s26, 0x100
	v_mov_b32_e32 v0, 0
	s_addc_u32 s54, s27, 0
	s_mov_b32 s55, -2
	v_mov_b32_e32 v1, 0
	v_mov_b64_e32 v[2:3], 0
	v_mov_b64_e32 v[4:5], 0
	v_mov_b64_e32 v[6:7], 0
	v_mov_b64_e32 v[8:9], 0
	v_mov_b64_e32 v[10:11], 0
	v_mov_b64_e32 v[12:13], 0
	v_mov_b64_e32 v[14:15], 0
	v_mov_b64_e32 v[16:17], 0
	v_mov_b64_e32 v[18:19], 0
	v_mov_b64_e32 v[20:21], 0
	v_mov_b64_e32 v[22:23], 0
	v_mov_b64_e32 v[24:25], 0
	v_mov_b64_e32 v[26:27], 0
	v_mov_b64_e32 v[28:29], 0
	v_mov_b64_e32 v[30:31], 0
	v_mov_b64_e32 v[32:33], 0
	v_mov_b64_e32 v[34:35], 0
	v_mov_b64_e32 v[36:37], 0
	v_mov_b64_e32 v[38:39], 0
	v_mov_b64_e32 v[40:41], 0
	v_mov_b64_e32 v[42:43], 0
	v_mov_b64_e32 v[44:45], 0
	v_mov_b64_e32 v[46:47], 0
	v_mov_b64_e32 v[48:49], 0
	v_mov_b64_e32 v[50:51], 0
	v_mov_b64_e32 v[52:53], 0
	v_mov_b64_e32 v[54:55], 0
	v_mov_b64_e32 v[56:57], 0
	v_mov_b64_e32 v[58:59], 0
	v_mov_b64_e32 v[60:61], 0
	v_mov_b64_e32 v[62:63], 0
	v_mov_b64_e32 v[64:65], 0
	v_mov_b64_e32 v[66:67], 0
	v_mov_b64_e32 v[68:69], 0
	v_mov_b64_e32 v[70:71], 0
	v_mov_b64_e32 v[72:73], 0
	v_mov_b64_e32 v[74:75], 0
	v_mov_b64_e32 v[76:77], 0
	v_mov_b64_e32 v[78:79], 0
	v_mov_b64_e32 v[80:81], 0
	v_mov_b64_e32 v[82:83], 0
	v_mov_b64_e32 v[84:85], 0
	v_mov_b64_e32 v[86:87], 0
	v_mov_b64_e32 v[88:89], 0
	v_mov_b64_e32 v[90:91], 0
	v_mov_b64_e32 v[92:93], 0
	v_mov_b64_e32 v[94:95], 0
	v_mov_b64_e32 v[96:97], 0
	v_mov_b64_e32 v[98:99], 0
	v_mov_b64_e32 v[100:101], 0
	v_mov_b64_e32 v[102:103], 0
	v_mov_b64_e32 v[104:105], 0
	v_mov_b64_e32 v[106:107], 0
	v_mov_b64_e32 v[108:109], 0
	v_mov_b64_e32 v[110:111], 0
	v_mov_b64_e32 v[112:113], 0
	v_mov_b64_e32 v[114:115], 0
	v_mov_b64_e32 v[116:117], 0
	v_mov_b64_e32 v[118:119], 0
	v_mov_b64_e32 v[120:121], 0
	v_mov_b64_e32 v[122:123], 0
	v_mov_b64_e32 v[124:125], 0
	v_mov_b64_e32 v[126:127], 0
	s_branch .Lz64_7
	s_nop 0
	s_nop 0
	s_nop 0
	s_nop 0
	s_nop 0
	s_nop 0
	s_nop 0
	s_nop 0
	s_nop 0
	s_nop 0
	s_nop 0
	s_nop 0
	s_nop 0
	s_nop 0
	s_nop 0
	s_nop 0
	s_nop 0
	s_nop 0
	s_nop 0
	s_nop 0
	s_nop 0
	s_nop 0
	s_nop 0
	s_nop 0
	s_nop 0
	s_nop 0
	s_nop 0
	s_nop 0
	s_nop 0
	s_nop 0
	s_nop 0
	s_nop 0
	s_nop 0
	s_nop 0
	s_nop 0
	s_nop 0
	s_nop 0
	s_nop 0
	s_nop 0
	s_nop 0
	s_nop 0
	s_nop 0
	s_nop 0
	s_nop 0
	s_nop 0
	s_nop 0
	s_nop 0
	s_nop 0
	s_nop 0
	s_nop 0
	s_nop 0
	s_nop 0
	s_nop 0
	s_nop 0
	s_nop 0
	s_nop 0
	s_nop 0
	s_nop 0
	s_nop 0
	s_nop 0
	s_nop 0
	s_nop 0
.Lz64_7:
.LBB0_2271:
	ds_read_b128 v[144:147], v160
	ds_read_b128 v[148:151], v160 offset:1024
	ds_read_b128 v[152:155], v160 offset:2048
	ds_read_b128 v[166:169], v160 offset:3072
	ds_read_b128 v[170:173], v161
	ds_read_b128 v[174:177], v161 offset:1024
	ds_read_b128 v[178:181], v161 offset:2048
	ds_read_b128 v[182:185], v161 offset:3072
	s_add_u32 s26, s24, 0xfff50080
	s_addc_u32 s27, s25, -1
	s_cmp_eq_u32 s55, 40
	s_cselect_b32 s29, s3, s27
	s_cselect_b32 s28, s2, s26
	s_cselect_b32 s27, s23, s54
	s_cselect_b32 s26, s22, s53
	v_lshl_add_u64 v[156:157], s[24:25], 0, v[136:137]
	s_add_i32 m0, s36, 0xc000
	ds_read_b128 v[186:189], v162
	ds_read_b128 v[190:193], v162 offset:1024
	ds_read_b128 v[194:197], v162 offset:2048
	ds_read_b128 v[198:201], v162 offset:3072
	ds_read_b128 v[202:205], v162 offset:4096
	ds_read_b128 v[206:209], v162 offset:5120
	ds_read_b128 v[210:213], v162 offset:6144
	ds_read_b128 v[214:217], v162 offset:7168
	global_load_lds_dwordx4 v[156:157], off
	v_lshl_add_u64 v[156:157], s[24:25], 0, v[138:139]
	s_add_i32 m0, s36, 0xe000
	s_nop 0
	global_load_lds_dwordx4 v[156:157], off
	s_waitcnt vmcnt(8)
	s_waitcnt lgkmcnt(0)
	s_barrier
	s_setprio 1
	s_waitcnt lgkmcnt(0)
	v_mfma_f32_16x16x32_bf16 v[124:127], v[144:147], v[186:189], v[124:127]
	v_mfma_f32_16x16x32_bf16 v[120:123], v[152:155], v[186:189], v[120:123]
	v_mfma_f32_16x16x32_bf16 v[108:111], v[144:147], v[194:197], v[108:111]
	v_mfma_f32_16x16x32_bf16 v[104:107], v[152:155], v[194:197], v[104:107]
	v_mfma_f32_16x16x32_bf16 v[92:95], v[144:147], v[202:205], v[92:95]
	v_mfma_f32_16x16x32_bf16 v[88:91], v[152:155], v[202:205], v[88:91]
	v_mfma_f32_16x16x32_bf16 v[76:79], v[144:147], v[210:213], v[76:79]
	v_mfma_f32_16x16x32_bf16 v[72:75], v[152:155], v[210:213], v[72:75]
	v_mfma_f32_16x16x32_bf16 v[124:127], v[148:151], v[190:193], v[124:127]
	v_mfma_f32_16x16x32_bf16 v[120:123], v[166:169], v[190:193], v[120:123]
	v_mfma_f32_16x16x32_bf16 v[108:111], v[148:151], v[198:201], v[108:111]
	v_mfma_f32_16x16x32_bf16 v[104:107], v[166:169], v[198:201], v[104:107]
	v_mfma_f32_16x16x32_bf16 v[92:95], v[148:151], v[206:209], v[92:95]
	v_mfma_f32_16x16x32_bf16 v[88:91], v[166:169], v[206:209], v[88:91]
	v_mfma_f32_16x16x32_bf16 v[76:79], v[148:151], v[214:217], v[76:79]
	v_mfma_f32_16x16x32_bf16 v[72:75], v[166:169], v[214:217], v[72:75]
	s_setprio 0
	s_setprio 1
	v_mfma_f32_16x16x32_bf16 v[116:119], v[170:173], v[186:189], v[116:119]
	v_mfma_f32_16x16x32_bf16 v[112:115], v[178:181], v[186:189], v[112:115]
	v_mfma_f32_16x16x32_bf16 v[100:103], v[170:173], v[194:197], v[100:103]
	v_mfma_f32_16x16x32_bf16 v[96:99], v[178:181], v[194:197], v[96:99]
	v_mfma_f32_16x16x32_bf16 v[84:87], v[170:173], v[202:205], v[84:87]
	v_mfma_f32_16x16x32_bf16 v[80:83], v[178:181], v[202:205], v[80:83]
	v_mfma_f32_16x16x32_bf16 v[68:71], v[170:173], v[210:213], v[68:71]
	v_mfma_f32_16x16x32_bf16 v[64:67], v[178:181], v[210:213], v[64:67]
	v_mfma_f32_16x16x32_bf16 v[116:119], v[174:177], v[190:193], v[116:119]
	v_mfma_f32_16x16x32_bf16 v[112:115], v[182:185], v[190:193], v[112:115]
	v_mfma_f32_16x16x32_bf16 v[100:103], v[174:177], v[198:201], v[100:103]
	v_mfma_f32_16x16x32_bf16 v[96:99], v[182:185], v[198:201], v[96:99]
	v_mfma_f32_16x16x32_bf16 v[84:87], v[174:177], v[206:209], v[84:87]
	v_mfma_f32_16x16x32_bf16 v[80:83], v[182:185], v[206:209], v[80:83]
	v_mfma_f32_16x16x32_bf16 v[68:71], v[174:177], v[214:217], v[68:71]
	v_mfma_f32_16x16x32_bf16 v[64:67], v[182:185], v[214:217], v[64:67]
	s_setprio 0
	s_barrier
; #define PG8_STAGE(bufoff, gbase, voff) do { _Pragma("unroll") for (int _i = 0; _i < 2; ++_i) \
;         __builtin_amdgcn_global_load_lds((const unsigned*)((const char*)(gbase) + (voff)[_i]), (PG8_LAS unsigned*)(lds + (bufoff) + ldsw + _i * 8192), 16, 0, 0); } while (0)
; #define PG8_LDA(dst, b, h) do { _Pragma("unroll") for (int m = 0; m < 4; ++m) _Pragma("unroll") for (int k = 0; k < 2; ++k) dst[m][k] = *(const PG8_LAS bf16x8*)(lds + PG8_SA(b, h) + aoff + m * 2048 + k * 1024); } while (0)
; #define PG8_LDB(dst, b, h) do { _Pragma("unroll") for (int n = 0; n < 2; ++n) _Pragma("unroll") for (int k = 0; k < 2; ++k) dst[n][k] = *(const PG8_LAS bf16x8*)(lds + PG8_SB(b, h) + boff + n * 2048 + k * 1024); } while (0)
; #define PG8_MMA(ai, bj, At, Bt) do { __builtin_amdgcn_s_setprio(1); _Pragma("unroll") for (int m = 0; m < 4; ++m) _Pragma("unroll") for (int n = 0; n < 2; ++n) _Pragma("unroll") for (int k = 0; k < 2; ++k) \
;         acc[ai][bj][m][n] = __builtin_amdgcn_mfma_f32_16x16x32_bf16(Bt[n][k], At[m][k], acc[ai][bj][m][n], 0, 0, 0); __builtin_amdgcn_s_setprio(0); } while (0)
; #define PG8_WAIT_V(n) asm volatile("s_waitcnt vmcnt(" #n ")" ::: "memory")
; #define PG8_WAIT_L(n) asm volatile("s_waitcnt lgkmcnt(" #n ")" ::: "memory")
; #define PG8_BAR __builtin_amdgcn_s_barrier()
; #define PG8_SCHED __builtin_amdgcn_sched_barrier(0)
; template <class Epi, class Sched, bool ALIGN_EPI = false, bool SP2 = false>
; __device__ __forceinline__ void gemm_phase(PG8_LAS unsigned char* lds, const Gemm g, const Sched& S, const Epi& E) {
;     ...
;             PG8_LDA(At, 0, 1); PG8_STAGE(PG8_SB(0, 0), b2, voffB); PG8_STAGE(PG8_SB(0, 1), b2 + hstep, voffB); PG8_STAGE(PG8_SA(0, 0), a2, voffA);
;             PG8_WAIT_V(8); PG8_WAIT_L(0); PG8_BAR; PG8_MMA(1, 0, At, B0); PG8_MMA(1, 1, At, B1); PG8_BAR; PG8_SCHED;
;             PG8_LDB(B0, 1, 0); PG8_LDB(B1, 1, 1); PG8_SCHED; PG8_LDA(At, 1, 0); PG8_STAGE(PG8_SA(0, 1), a2 + hstep, voffA);
;             PG8_WAIT_V(8); PG8_WAIT_L(0); PG8_BAR; PG8_MMA(0, 0, At, B0); PG8_MMA(0, 1, At, B1); PG8_BAR; PG8_SCHED;
	s_add_i32 s56, s46, s35
	v_lshl_add_u64 v[156:157], s[26:27], 0, v[130:131]
	s_mov_b32 m0, s56
	ds_read_b128 v[186:189], v162 offset:16384
	ds_read_b128 v[190:193], v162 offset:17408
	ds_read_b128 v[194:197], v162 offset:18432
	ds_read_b128 v[198:201], v162 offset:19456
	ds_read_b128 v[202:205], v162 offset:20480
	ds_read_b128 v[206:209], v162 offset:21504
	ds_read_b128 v[210:213], v162 offset:22528
	ds_read_b128 v[214:217], v162 offset:23552
	global_load_lds_dwordx4 v[156:157], off
	s_add_i32 m0, s56, 0x2000
	s_add_u32 s56, s26, 0xb0000
	v_lshl_add_u64 v[218:219], s[26:27], 0, v[134:135]
	s_addc_u32 s57, s27, 0
	s_add_i32 s58, s47, s35
	global_load_lds_dwordx4 v[218:219], off
	v_lshl_add_u64 v[220:221], s[56:57], 0, v[130:131]
	s_mov_b32 m0, s58
	v_lshl_add_u64 v[222:223], s[28:29], 0, v[132:133]
	global_load_lds_dwordx4 v[220:221], off
	v_lshl_add_u64 v[220:221], s[56:57], 0, v[134:135]
	s_add_i32 m0, s58, 0x2000
	s_nop 0
	global_load_lds_dwordx4 v[220:221], off
	v_lshl_add_u64 v[220:221], s[28:29], 0, v[128:129]
	s_mov_b32 m0, s36
	s_nop 0
	global_load_lds_dwordx4 v[220:221], off
	s_mov_b32 m0, s37
	s_nop 0
	global_load_lds_dwordx4 v[222:223], off
	s_waitcnt vmcnt(8)
	s_waitcnt lgkmcnt(0)
	s_barrier
	s_setprio 1
	s_waitcnt lgkmcnt(0)
	v_mfma_f32_16x16x32_bf16 v[60:63], v[144:147], v[186:189], v[60:63]
	v_mfma_f32_16x16x32_bf16 v[56:59], v[152:155], v[186:189], v[56:59]
	v_mfma_f32_16x16x32_bf16 v[44:47], v[144:147], v[194:197], v[44:47]
	v_mfma_f32_16x16x32_bf16 v[40:43], v[152:155], v[194:197], v[40:43]
	v_mfma_f32_16x16x32_bf16 v[28:31], v[144:147], v[202:205], v[28:31]
	v_mfma_f32_16x16x32_bf16 v[24:27], v[152:155], v[202:205], v[24:27]
	v_mfma_f32_16x16x32_bf16 v[12:15], v[144:147], v[210:213], v[12:15]
	v_mfma_f32_16x16x32_bf16 v[8:11], v[152:155], v[210:213], v[8:11]
	v_mfma_f32_16x16x32_bf16 v[60:63], v[148:151], v[190:193], v[60:63]
	v_mfma_f32_16x16x32_bf16 v[56:59], v[166:169], v[190:193], v[56:59]
	v_mfma_f32_16x16x32_bf16 v[44:47], v[148:151], v[198:201], v[44:47]
	v_mfma_f32_16x16x32_bf16 v[40:43], v[166:169], v[198:201], v[40:43]
	v_mfma_f32_16x16x32_bf16 v[28:31], v[148:151], v[206:209], v[28:31]
	v_mfma_f32_16x16x32_bf16 v[24:27], v[166:169], v[206:209], v[24:27]
	v_mfma_f32_16x16x32_bf16 v[12:15], v[148:151], v[214:217], v[12:15]
	v_mfma_f32_16x16x32_bf16 v[8:11], v[166:169], v[214:217], v[8:11]
	s_setprio 0
	s_setprio 1
	v_mfma_f32_16x16x32_bf16 v[52:55], v[170:173], v[186:189], v[52:55]
	v_mfma_f32_16x16x32_bf16 v[48:51], v[178:181], v[186:189], v[48:51]
	v_mfma_f32_16x16x32_bf16 v[36:39], v[170:173], v[194:197], v[36:39]
	v_mfma_f32_16x16x32_bf16 v[32:35], v[178:181], v[194:197], v[32:35]
	v_mfma_f32_16x16x32_bf16 v[20:23], v[170:173], v[202:205], v[20:23]
	v_mfma_f32_16x16x32_bf16 v[16:19], v[178:181], v[202:205], v[16:19]
	v_mfma_f32_16x16x32_bf16 v[4:7], v[170:173], v[210:213], v[4:7]
	v_mfma_f32_16x16x32_bf16 v[0:3], v[178:181], v[210:213], v[0:3]
	v_mfma_f32_16x16x32_bf16 v[52:55], v[174:177], v[190:193], v[52:55]
	v_mfma_f32_16x16x32_bf16 v[48:51], v[182:185], v[190:193], v[48:51]
	v_mfma_f32_16x16x32_bf16 v[36:39], v[174:177], v[198:201], v[36:39]
	v_mfma_f32_16x16x32_bf16 v[32:35], v[182:185], v[198:201], v[32:35]
	v_mfma_f32_16x16x32_bf16 v[20:23], v[174:177], v[206:209], v[20:23]
	v_mfma_f32_16x16x32_bf16 v[16:19], v[182:185], v[206:209], v[16:19]
	v_mfma_f32_16x16x32_bf16 v[4:7], v[174:177], v[214:217], v[4:7]
	v_mfma_f32_16x16x32_bf16 v[0:3], v[182:185], v[214:217], v[0:3]
	s_setprio 0
	s_barrier
	ds_read_b128 v[144:147], v163
	ds_read_b128 v[148:151], v163 offset:1024
	ds_read_b128 v[152:155], v163 offset:2048
	ds_read_b128 v[166:169], v163 offset:3072
	ds_read_b128 v[170:173], v164
	ds_read_b128 v[174:177], v164 offset:1024
	ds_read_b128 v[178:181], v164 offset:2048
	ds_read_b128 v[182:185], v164 offset:3072
	s_add_u32 s28, s28, 0xb0000
	s_addc_u32 s29, s29, 0
	s_mov_b32 m0, s38
	v_lshl_add_u64 v[224:225], s[28:29], 0, v[128:129]
	ds_read_b128 v[186:189], v162 offset:32768
	ds_read_b128 v[190:193], v162 offset:33792
	ds_read_b128 v[194:197], v162 offset:34816
	ds_read_b128 v[198:201], v162 offset:35840
	ds_read_b128 v[202:205], v162 offset:36864
	ds_read_b128 v[206:209], v162 offset:37888
	ds_read_b128 v[210:213], v162 offset:38912
	ds_read_b128 v[214:217], v162 offset:39936
	global_load_lds_dwordx4 v[224:225], off
	v_lshl_add_u64 v[224:225], s[28:29], 0, v[132:133]
	s_mov_b32 m0, s39
	s_nop 0
	global_load_lds_dwordx4 v[224:225], off
	s_waitcnt vmcnt(8)
	s_waitcnt lgkmcnt(0)
	s_barrier
; #define PG8_STAGE(bufoff, gbase, voff) do { _Pragma("unroll") for (int _i = 0; _i < 2; ++_i) \
;         __builtin_amdgcn_global_load_lds((const unsigned*)((const char*)(gbase) + (voff)[_i]), (PG8_LAS unsigned*)(lds + (bufoff) + ldsw + _i * 8192), 16, 0, 0); } while (0)
; #define PG8_LDA(dst, b, h) do { _Pragma("unroll") for (int m = 0; m < 4; ++m) _Pragma("unroll") for (int k = 0; k < 2; ++k) dst[m][k] = *(const PG8_LAS bf16x8*)(lds + PG8_SA(b, h) + aoff + m * 2048 + k * 1024); } while (0)
; #define PG8_MMA(ai, bj, At, Bt) do { __builtin_amdgcn_s_setprio(1); _Pragma("unroll") for (int m = 0; m < 4; ++m) _Pragma("unroll") for (int n = 0; n < 2; ++n) _Pragma("unroll") for (int k = 0; k < 2; ++k) \
;         acc[ai][bj][m][n] = __builtin_amdgcn_mfma_f32_16x16x32_bf16(Bt[n][k], At[m][k], acc[ai][bj][m][n], 0, 0, 0); __builtin_amdgcn_s_setprio(0); } while (0)
; #define PG8_WAIT_V(n) asm volatile("s_waitcnt vmcnt(" #n ")" ::: "memory")
; #define PG8_WAIT_L(n) asm volatile("s_waitcnt lgkmcnt(" #n ")" ::: "memory")
; #define PG8_BAR __builtin_amdgcn_s_barrier()
; #define PG8_SCHED __builtin_amdgcn_sched_barrier(0)
; template <class Epi, class Sched, bool ALIGN_EPI = false, bool SP2 = false>
; __device__ __forceinline__ void gemm_phase(PG8_LAS unsigned char* lds, const Gemm g, const Sched& S, const Epi& E) {
;     ...
;             PG8_WAIT_V(8); PG8_WAIT_L(0); PG8_BAR; PG8_MMA(0, 0, At, B0); PG8_MMA(0, 1, At, B1); PG8_BAR; PG8_SCHED;
;             PG8_LDA(At, 1, 1); PG8_STAGE(PG8_SB(1, 0), b3, voffB); PG8_STAGE(PG8_SB(1, 1), b3 + hstep, voffB); PG8_STAGE(PG8_SA(1, 0), a3, voffA);
;             PG8_WAIT_V(8); PG8_WAIT_L(0); PG8_BAR; PG8_MMA(1, 0, At, B0); PG8_MMA(1, 1, At, B1); PG8_BAR; PG8_SCHED;
	s_setprio 1
	s_waitcnt lgkmcnt(0)
	v_mfma_f32_16x16x32_bf16 v[124:127], v[144:147], v[186:189], v[124:127]
	v_mfma_f32_16x16x32_bf16 v[120:123], v[152:155], v[186:189], v[120:123]
	v_mfma_f32_16x16x32_bf16 v[108:111], v[144:147], v[194:197], v[108:111]
	v_mfma_f32_16x16x32_bf16 v[104:107], v[152:155], v[194:197], v[104:107]
	v_mfma_f32_16x16x32_bf16 v[92:95], v[144:147], v[202:205], v[92:95]
	v_mfma_f32_16x16x32_bf16 v[88:91], v[152:155], v[202:205], v[88:91]
	v_mfma_f32_16x16x32_bf16 v[76:79], v[144:147], v[210:213], v[76:79]
	v_mfma_f32_16x16x32_bf16 v[72:75], v[152:155], v[210:213], v[72:75]
	v_mfma_f32_16x16x32_bf16 v[124:127], v[148:151], v[190:193], v[124:127]
	v_mfma_f32_16x16x32_bf16 v[120:123], v[166:169], v[190:193], v[120:123]
	v_mfma_f32_16x16x32_bf16 v[108:111], v[148:151], v[198:201], v[108:111]
	v_mfma_f32_16x16x32_bf16 v[104:107], v[166:169], v[198:201], v[104:107]
	v_mfma_f32_16x16x32_bf16 v[92:95], v[148:151], v[206:209], v[92:95]
	v_mfma_f32_16x16x32_bf16 v[88:91], v[166:169], v[206:209], v[88:91]
	v_mfma_f32_16x16x32_bf16 v[76:79], v[148:151], v[214:217], v[76:79]
	v_mfma_f32_16x16x32_bf16 v[72:75], v[166:169], v[214:217], v[72:75]
	s_setprio 0
	s_setprio 1
	v_mfma_f32_16x16x32_bf16 v[116:119], v[170:173], v[186:189], v[116:119]
	v_mfma_f32_16x16x32_bf16 v[112:115], v[178:181], v[186:189], v[112:115]
	v_mfma_f32_16x16x32_bf16 v[100:103], v[170:173], v[194:197], v[100:103]
	v_mfma_f32_16x16x32_bf16 v[96:99], v[178:181], v[194:197], v[96:99]
	v_mfma_f32_16x16x32_bf16 v[84:87], v[170:173], v[202:205], v[84:87]
	v_mfma_f32_16x16x32_bf16 v[80:83], v[178:181], v[202:205], v[80:83]
	v_mfma_f32_16x16x32_bf16 v[68:71], v[170:173], v[210:213], v[68:71]
	v_mfma_f32_16x16x32_bf16 v[64:67], v[178:181], v[210:213], v[64:67]
	v_mfma_f32_16x16x32_bf16 v[116:119], v[174:177], v[190:193], v[116:119]
	v_mfma_f32_16x16x32_bf16 v[112:115], v[182:185], v[190:193], v[112:115]
	v_mfma_f32_16x16x32_bf16 v[100:103], v[174:177], v[198:201], v[100:103]
	v_mfma_f32_16x16x32_bf16 v[96:99], v[182:185], v[198:201], v[96:99]
	v_mfma_f32_16x16x32_bf16 v[84:87], v[174:177], v[206:209], v[84:87]
	v_mfma_f32_16x16x32_bf16 v[80:83], v[182:185], v[206:209], v[80:83]
	v_mfma_f32_16x16x32_bf16 v[68:71], v[174:177], v[214:217], v[68:71]
	v_mfma_f32_16x16x32_bf16 v[64:67], v[182:185], v[214:217], v[64:67]
	s_setprio 0
	s_barrier
	s_add_i32 s28, s48, s35
	v_lshl_add_u64 v[156:157], v[156:157], 0, s[10:11]
	s_mov_b32 m0, s28
	ds_read_b128 v[186:189], v162 offset:49152
	ds_read_b128 v[190:193], v162 offset:50176
	ds_read_b128 v[194:197], v162 offset:51200
	ds_read_b128 v[198:201], v162 offset:52224
	ds_read_b128 v[202:205], v162 offset:53248
	ds_read_b128 v[206:209], v162 offset:54272
	ds_read_b128 v[210:213], v162 offset:55296
	ds_read_b128 v[214:217], v162 offset:56320
	global_load_lds_dwordx4 v[156:157], off
	s_add_i32 m0, s28, 0x2000
	s_add_u32 s26, s26, 0xb0080
	v_lshl_add_u64 v[156:157], v[218:219], 0, s[10:11]
	s_addc_u32 s27, s27, 0
	s_add_i32 s28, s49, s35
	global_load_lds_dwordx4 v[156:157], off
	v_lshl_add_u64 v[156:157], s[26:27], 0, v[130:131]
	s_mov_b32 m0, s28
	s_nop 0
	global_load_lds_dwordx4 v[156:157], off
	v_lshl_add_u64 v[156:157], s[26:27], 0, v[134:135]
	s_add_i32 m0, s28, 0x2000
	s_nop 0
	global_load_lds_dwordx4 v[156:157], off
	v_lshl_add_u64 v[156:157], v[220:221], 0, s[10:11]
	s_mov_b32 m0, s42
	s_nop 0
	global_load_lds_dwordx4 v[156:157], off
	v_lshl_add_u64 v[156:157], v[222:223], 0, s[10:11]
	s_mov_b32 m0, s43
	s_nop 0
	global_load_lds_dwordx4 v[156:157], off
	s_waitcnt vmcnt(8)
	s_waitcnt lgkmcnt(0)
	s_barrier
	s_setprio 1
	s_waitcnt lgkmcnt(0)
	v_mfma_f32_16x16x32_bf16 v[60:63], v[144:147], v[186:189], v[60:63]
	v_mfma_f32_16x16x32_bf16 v[56:59], v[152:155], v[186:189], v[56:59]
	v_mfma_f32_16x16x32_bf16 v[44:47], v[144:147], v[194:197], v[44:47]
	v_mfma_f32_16x16x32_bf16 v[40:43], v[152:155], v[194:197], v[40:43]
	v_mfma_f32_16x16x32_bf16 v[28:31], v[144:147], v[202:205], v[28:31]
	v_mfma_f32_16x16x32_bf16 v[24:27], v[152:155], v[202:205], v[24:27]
	v_mfma_f32_16x16x32_bf16 v[12:15], v[144:147], v[210:213], v[12:15]
	v_mfma_f32_16x16x32_bf16 v[8:11], v[152:155], v[210:213], v[8:11]
	v_mfma_f32_16x16x32_bf16 v[60:63], v[148:151], v[190:193], v[60:63]
	v_mfma_f32_16x16x32_bf16 v[56:59], v[166:169], v[190:193], v[56:59]
	v_mfma_f32_16x16x32_bf16 v[44:47], v[148:151], v[198:201], v[44:47]
	v_mfma_f32_16x16x32_bf16 v[40:43], v[166:169], v[198:201], v[40:43]
	v_mfma_f32_16x16x32_bf16 v[28:31], v[148:151], v[206:209], v[28:31]
	v_mfma_f32_16x16x32_bf16 v[24:27], v[166:169], v[206:209], v[24:27]
	v_mfma_f32_16x16x32_bf16 v[12:15], v[148:151], v[214:217], v[12:15]
	v_mfma_f32_16x16x32_bf16 v[8:11], v[166:169], v[214:217], v[8:11]
	s_setprio 0
	s_setprio 1
	v_mfma_f32_16x16x32_bf16 v[52:55], v[170:173], v[186:189], v[52:55]
	v_mfma_f32_16x16x32_bf16 v[48:51], v[178:181], v[186:189], v[48:51]
	v_mfma_f32_16x16x32_bf16 v[36:39], v[170:173], v[194:197], v[36:39]
	v_mfma_f32_16x16x32_bf16 v[32:35], v[178:181], v[194:197], v[32:35]
	v_mfma_f32_16x16x32_bf16 v[20:23], v[170:173], v[202:205], v[20:23]
	v_mfma_f32_16x16x32_bf16 v[16:19], v[178:181], v[202:205], v[16:19]
	v_mfma_f32_16x16x32_bf16 v[4:7], v[170:173], v[210:213], v[4:7]
	v_mfma_f32_16x16x32_bf16 v[0:3], v[178:181], v[210:213], v[0:3]
	v_mfma_f32_16x16x32_bf16 v[52:55], v[174:177], v[190:193], v[52:55]
	v_mfma_f32_16x16x32_bf16 v[48:51], v[182:185], v[190:193], v[48:51]
	v_mfma_f32_16x16x32_bf16 v[36:39], v[174:177], v[198:201], v[36:39]
	v_mfma_f32_16x16x32_bf16 v[32:35], v[182:185], v[198:201], v[32:35]
	v_mfma_f32_16x16x32_bf16 v[20:23], v[174:177], v[206:209], v[20:23]
	v_mfma_f32_16x16x32_bf16 v[16:19], v[182:185], v[206:209], v[16:19]
	v_mfma_f32_16x16x32_bf16 v[4:7], v[174:177], v[214:217], v[4:7]
	v_mfma_f32_16x16x32_bf16 v[0:3], v[182:185], v[214:217], v[0:3]
	s_setprio 0
	s_barrier
	s_add_i32 s55, s55, 2
	s_add_u32 s24, s24, 0x100
	s_addc_u32 s25, s25, 0
	s_add_u32 s53, s53, 0x100
	s_addc_u32 s54, s54, 0
	s_cmp_gt_u32 s55, 41
	s_cbranch_scc0 .LBB0_2271
	s_and_b64 vcc, exec, s[12:13]
	s_cbranch_vccz .LBB0_2274
	s_barrier
